# d4 + first 8 MFMAs of each segment issued before the segment-opening barrier (fills partner-segment slack)
# speedup vs baseline: 1.0065x; 1.0065x over previous
; #define PG8_STAGE(bufoff, gbase, voff) do { _Pragma("unroll") for (int _i = 0; _i < 2; ++_i) \
;         __builtin_amdgcn_global_load_lds((const unsigned*)((const char*)(gbase) + (voff)[_i]), (LAS unsigned*)(lds + (bufoff) + ldsw + _i * 8192), 16, 0, 0); } while (0)
; #define PG8_LDA(dst, b, h) do { _Pragma("unroll") for (int m = 0; m < 4; ++m) _Pragma("unroll") for (int k = 0; k < 2; ++k) dst[m][k] = *(const LAS bf16x8*)(lds + PG8_SA(b, h) + aoff + m * 2048 + k * 1024); } while (0)
; #define PG8_LDB(dst, b, h) do { _Pragma("unroll") for (int n = 0; n < 2; ++n) _Pragma("unroll") for (int k = 0; k < 2; ++k) dst[n][k] = *(const LAS bf16x8*)(lds + PG8_SB(b, h) + boff + n * 2048 + k * 1024); } while (0)
; #define PG8_MMA(ai, bj, At, Bt) do { __builtin_amdgcn_s_setprio(1); _Pragma("unroll") for (int m = 0; m < 4; ++m) _Pragma("unroll") for (int n = 0; n < 2; ++n) _Pragma("unroll") for (int k = 0; k < 2; ++k) \
;         acc[ai][bj][m][n] = __builtin_amdgcn_mfma_f32_16x16x32_bf16(Bt[n][k], At[m][k], acc[ai][bj][m][n], 0, 0, 0); __builtin_amdgcn_s_setprio(0); } while (0)
; #define PG8_WAIT_V(n) asm volatile("s_waitcnt vmcnt(" #n ")" ::: "memory")
; #define PG8_WAIT_L(n) asm volatile("s_waitcnt lgkmcnt(" #n ")" ::: "memory")
; #define PG8_BAR __builtin_amdgcn_s_barrier()
; template <class Epi>
; __device__ __forceinline__ void gemm_phase(LAS unsigned char* lds, const Gemm g, const StaticOrder& S, const Epi& E) {
;     ...
;         for (int t = 0; t < nt; t += 2) {
;             const bool last = (t == nt - 2);
;             const char* a1 = cA + (size_t)(t + 1) * kstep;
;             const char* a2 = last ? nA : cA + (size_t)(t + 2) * kstep; const char* b2 = last ? nB : cB + (size_t)(t + 2) * kstep;
;             const char* a3 = a2 + kstep; const char* b3 = b2 + kstep;
;             if constexpr (Epi::MIDK > 0) { if (t == Epi::MIDK) E.mid(acc, cur, wr, wc, fr, fq); }
;             PG8_LDB(B0, 0, 0); PG8_LDB(B1, 0, 1); PG8_SCHED; PG8_LDA(At, 0, 0); PG8_STAGE(PG8_SA(1, 1), a1 + hstep, voffA);
;             PG8_WAIT_V(8); PG8_WAIT_L(0); PG8_BAR; PG8_MMA(0, 0, At, B0); PG8_MMA(0, 1, At, B1); PG8_BAR; PG8_SCHED;
;             PG8_LDA(At, 0, 1); PG8_STAGE(PG8_SB(0, 0), b2, voffB); PG8_STAGE(PG8_SB(0, 1), b2 + hstep, voffB); PG8_STAGE(PG8_SA(0, 0), a2, voffA);
;             PG8_WAIT_V(8); PG8_WAIT_L(0); PG8_BAR; PG8_MMA(1, 0, At, B0); PG8_MMA(1, 1, At, B1); PG8_BAR; PG8_SCHED;
.LBB0_134:
	ds_read_b128 v[158:161], v150
	ds_read_b128 v[162:165], v150 offset:1024
	ds_read_b128 v[166:169], v150 offset:2048
	ds_read_b128 v[174:177], v150 offset:3072
	ds_read_b128 v[178:181], v151
	ds_read_b128 v[182:185], v151 offset:1024
	ds_read_b128 v[186:189], v151 offset:2048
	ds_read_b128 v[190:193], v151 offset:3072
	s_add_u32 s66, s64, 0xfffc0080
	s_addc_u32 s67, s65, -1
	s_cmp_eq_u32 s92, 12
	s_cselect_b32 s69, s87, s67
	s_cselect_b32 s68, s88, s66
	s_cselect_b32 s67, s47, s91
	s_cselect_b32 s66, s89, s90
	s_add_i32 m0, s61, 0xc000
	ds_read_b128 v[194:197], v152
	ds_read_b128 v[198:201], v152 offset:1024
	ds_read_b128 v[202:205], v152 offset:2048
	ds_read_b128 v[206:209], v152 offset:3072
	ds_read_b128 v[210:213], v152 offset:4096
	ds_read_b128 v[214:217], v152 offset:5120
	ds_read_b128 v[218:221], v152 offset:6144
	ds_read_b128 v[222:225], v152 offset:7168
	global_load_lds_dwordx4 v140, s[64:65]
	s_add_i32 m0, s61, 0xe000
	s_nop 0
	global_load_lds_dwordx4 v142, s[64:65]
	s_waitcnt vmcnt(8)
	s_waitcnt lgkmcnt(0)
	s_setprio 1
	v_mfma_f32_16x16x32_bf16 v[126:129], v[158:161], v[194:197], v[126:129]
	v_mfma_f32_16x16x32_bf16 v[118:121], v[166:169], v[194:197], v[118:121]
	v_mfma_f32_16x16x32_bf16 v[110:113], v[158:161], v[202:205], v[110:113]
	v_mfma_f32_16x16x32_bf16 v[102:105], v[166:169], v[202:205], v[102:105]
	v_mfma_f32_16x16x32_bf16 v[94:97], v[158:161], v[210:213], v[94:97]
	v_mfma_f32_16x16x32_bf16 v[86:89], v[166:169], v[210:213], v[86:89]
	v_mfma_f32_16x16x32_bf16 v[78:81], v[158:161], v[218:221], v[78:81]
	v_mfma_f32_16x16x32_bf16 v[70:73], v[166:169], v[218:221], v[70:73]
	s_barrier
	v_mfma_f32_16x16x32_bf16 v[126:129], v[162:165], v[198:201], v[126:129]
	v_mfma_f32_16x16x32_bf16 v[118:121], v[174:177], v[198:201], v[118:121]
	v_mfma_f32_16x16x32_bf16 v[110:113], v[162:165], v[206:209], v[110:113]
	v_mfma_f32_16x16x32_bf16 v[102:105], v[174:177], v[206:209], v[102:105]
	v_mfma_f32_16x16x32_bf16 v[94:97], v[162:165], v[214:217], v[94:97]
	v_mfma_f32_16x16x32_bf16 v[86:89], v[174:177], v[214:217], v[86:89]
	v_mfma_f32_16x16x32_bf16 v[78:81], v[162:165], v[222:225], v[78:81]
	v_mfma_f32_16x16x32_bf16 v[70:73], v[174:177], v[222:225], v[70:73]
	v_mfma_f32_16x16x32_bf16 v[122:125], v[178:181], v[194:197], v[122:125]
	v_mfma_f32_16x16x32_bf16 v[114:117], v[186:189], v[194:197], v[114:117]
	v_mfma_f32_16x16x32_bf16 v[106:109], v[178:181], v[202:205], v[106:109]
	v_mfma_f32_16x16x32_bf16 v[98:101], v[186:189], v[202:205], v[98:101]
	v_mfma_f32_16x16x32_bf16 v[90:93], v[178:181], v[210:213], v[90:93]
	v_mfma_f32_16x16x32_bf16 v[82:85], v[186:189], v[210:213], v[82:85]
	v_mfma_f32_16x16x32_bf16 v[74:77], v[178:181], v[218:221], v[74:77]
	v_mfma_f32_16x16x32_bf16 v[66:69], v[186:189], v[218:221], v[66:69]
	v_mfma_f32_16x16x32_bf16 v[122:125], v[182:185], v[198:201], v[122:125]
	v_mfma_f32_16x16x32_bf16 v[114:117], v[190:193], v[198:201], v[114:117]
	v_mfma_f32_16x16x32_bf16 v[106:109], v[182:185], v[206:209], v[106:109]
	v_mfma_f32_16x16x32_bf16 v[98:101], v[190:193], v[206:209], v[98:101]
	v_mfma_f32_16x16x32_bf16 v[90:93], v[182:185], v[214:217], v[90:93]
	v_mfma_f32_16x16x32_bf16 v[82:85], v[190:193], v[214:217], v[82:85]
	v_mfma_f32_16x16x32_bf16 v[74:77], v[182:185], v[222:225], v[74:77]
	v_mfma_f32_16x16x32_bf16 v[66:69], v[190:193], v[222:225], v[66:69]
	s_barrier
	s_setprio 0
	s_add_u32 s98, s66, s8
	s_addc_u32 s99, s67, s9
	s_add_u32 s100, s68, s8
	s_addc_u32 s101, s69, s9
	s_add_i32 s93, s83, s6
	s_mov_b32 m0, s93
	ds_read_b128 v[194:197], v152 offset:16384
	ds_read_b128 v[198:201], v152 offset:17408
	ds_read_b128 v[202:205], v152 offset:18432
	ds_read_b128 v[206:209], v152 offset:19456
	ds_read_b128 v[210:213], v152 offset:20480
	ds_read_b128 v[214:217], v152 offset:21504
	ds_read_b128 v[218:221], v152 offset:22528
	ds_read_b128 v[222:225], v152 offset:23552
	global_load_lds_dwordx4 v132, s[66:67]
	s_add_i32 m0, s93, 0x2000
	s_add_u32 s94, s66, 0x40000
	s_addc_u32 s95, s67, 0
	s_add_i32 s93, s84, s6
	global_load_lds_dwordx4 v136, s[66:67]
	s_mov_b32 m0, s93
	s_nop 0
	global_load_lds_dwordx4 v132, s[94:95]
	s_add_i32 m0, s93, 0x2000
	s_nop 0
	global_load_lds_dwordx4 v136, s[94:95]
	s_mov_b32 m0, s61
	s_nop 0
	global_load_lds_dwordx4 v130, s[68:69]
	s_mov_b32 m0, s63
	s_nop 0
	global_load_lds_dwordx4 v134, s[68:69]
	s_waitcnt vmcnt(8)
	s_waitcnt lgkmcnt(0)
	s_setprio 1
	v_mfma_f32_16x16x32_bf16 v[62:65], v[158:161], v[194:197], v[62:65]
	v_mfma_f32_16x16x32_bf16 v[54:57], v[166:169], v[194:197], v[54:57]
	v_mfma_f32_16x16x32_bf16 v[46:49], v[158:161], v[202:205], v[46:49]
	v_mfma_f32_16x16x32_bf16 v[38:41], v[166:169], v[202:205], v[38:41]
	v_mfma_f32_16x16x32_bf16 v[30:33], v[158:161], v[210:213], v[30:33]
	v_mfma_f32_16x16x32_bf16 v[22:25], v[166:169], v[210:213], v[22:25]
	v_mfma_f32_16x16x32_bf16 v[14:17], v[158:161], v[218:221], v[14:17]
	v_mfma_f32_16x16x32_bf16 v[6:9], v[166:169], v[218:221], v[6:9]
	s_barrier
; #define PG8_STAGE(bufoff, gbase, voff) do { _Pragma("unroll") for (int _i = 0; _i < 2; ++_i) \
;         __builtin_amdgcn_global_load_lds((const unsigned*)((const char*)(gbase) + (voff)[_i]), (LAS unsigned*)(lds + (bufoff) + ldsw + _i * 8192), 16, 0, 0); } while (0)
; #define PG8_LDA(dst, b, h) do { _Pragma("unroll") for (int m = 0; m < 4; ++m) _Pragma("unroll") for (int k = 0; k < 2; ++k) dst[m][k] = *(const LAS bf16x8*)(lds + PG8_SA(b, h) + aoff + m * 2048 + k * 1024); } while (0)
; #define PG8_LDB(dst, b, h) do { _Pragma("unroll") for (int n = 0; n < 2; ++n) _Pragma("unroll") for (int k = 0; k < 2; ++k) dst[n][k] = *(const LAS bf16x8*)(lds + PG8_SB(b, h) + boff + n * 2048 + k * 1024); } while (0)
; #define PG8_MMA(ai, bj, At, Bt) do { __builtin_amdgcn_s_setprio(1); _Pragma("unroll") for (int m = 0; m < 4; ++m) _Pragma("unroll") for (int n = 0; n < 2; ++n) _Pragma("unroll") for (int k = 0; k < 2; ++k) \
;         acc[ai][bj][m][n] = __builtin_amdgcn_mfma_f32_16x16x32_bf16(Bt[n][k], At[m][k], acc[ai][bj][m][n], 0, 0, 0); __builtin_amdgcn_s_setprio(0); } while (0)
; #define PG8_WAIT_V(n) asm volatile("s_waitcnt vmcnt(" #n ")" ::: "memory")
; #define PG8_WAIT_L(n) asm volatile("s_waitcnt lgkmcnt(" #n ")" ::: "memory")
; #define PG8_BAR __builtin_amdgcn_s_barrier()
; #define PG8_SCHED __builtin_amdgcn_sched_barrier(0)
; template <class Epi>
; __device__ __forceinline__ void gemm_phase(LAS unsigned char* lds, const Gemm g, const StaticOrder& S, const Epi& E) {
;     ...
;             PG8_WAIT_V(8); PG8_WAIT_L(0); PG8_BAR; PG8_MMA(1, 0, At, B0); PG8_MMA(1, 1, At, B1); PG8_BAR; PG8_SCHED;
;             PG8_LDB(B0, 1, 0); PG8_LDB(B1, 1, 1); PG8_SCHED; PG8_LDA(At, 1, 0); PG8_STAGE(PG8_SA(0, 1), a2 + hstep, voffA);
;             PG8_WAIT_V(8); PG8_WAIT_L(0); PG8_BAR; PG8_MMA(0, 0, At, B0); PG8_MMA(0, 1, At, B1); PG8_BAR; PG8_SCHED;
	v_mfma_f32_16x16x32_bf16 v[62:65], v[162:165], v[198:201], v[62:65]
	v_mfma_f32_16x16x32_bf16 v[54:57], v[174:177], v[198:201], v[54:57]
	v_mfma_f32_16x16x32_bf16 v[46:49], v[162:165], v[206:209], v[46:49]
	v_mfma_f32_16x16x32_bf16 v[38:41], v[174:177], v[206:209], v[38:41]
	v_mfma_f32_16x16x32_bf16 v[30:33], v[162:165], v[214:217], v[30:33]
	v_mfma_f32_16x16x32_bf16 v[22:25], v[174:177], v[214:217], v[22:25]
	v_mfma_f32_16x16x32_bf16 v[14:17], v[162:165], v[222:225], v[14:17]
	v_mfma_f32_16x16x32_bf16 v[6:9], v[174:177], v[222:225], v[6:9]
	v_mfma_f32_16x16x32_bf16 v[58:61], v[178:181], v[194:197], v[58:61]
	v_mfma_f32_16x16x32_bf16 v[50:53], v[186:189], v[194:197], v[50:53]
	v_mfma_f32_16x16x32_bf16 v[42:45], v[178:181], v[202:205], v[42:45]
	v_mfma_f32_16x16x32_bf16 v[34:37], v[186:189], v[202:205], v[34:37]
	v_mfma_f32_16x16x32_bf16 v[26:29], v[178:181], v[210:213], v[26:29]
	v_mfma_f32_16x16x32_bf16 v[18:21], v[186:189], v[210:213], v[18:21]
	v_mfma_f32_16x16x32_bf16 v[10:13], v[178:181], v[218:221], v[10:13]
	v_mfma_f32_16x16x32_bf16 v[2:5], v[186:189], v[218:221], v[2:5]
	v_mfma_f32_16x16x32_bf16 v[58:61], v[182:185], v[198:201], v[58:61]
	v_mfma_f32_16x16x32_bf16 v[50:53], v[190:193], v[198:201], v[50:53]
	v_mfma_f32_16x16x32_bf16 v[42:45], v[182:185], v[206:209], v[42:45]
	v_mfma_f32_16x16x32_bf16 v[34:37], v[190:193], v[206:209], v[34:37]
	v_mfma_f32_16x16x32_bf16 v[26:29], v[182:185], v[214:217], v[26:29]
	v_mfma_f32_16x16x32_bf16 v[18:21], v[190:193], v[214:217], v[18:21]
	v_mfma_f32_16x16x32_bf16 v[10:13], v[182:185], v[222:225], v[10:13]
	v_mfma_f32_16x16x32_bf16 v[2:5], v[190:193], v[222:225], v[2:5]
	s_barrier
	s_setprio 0
	s_add_i32 s93, 0, 0x18000
	s_add_i32 s94, 0, 0x1c000
	v_add_u32_e32 v174, s93, v148
	v_add_u32_e32 v190, s94, v148
	ds_read_b128 v[158:161], v174
	ds_read_b128 v[162:165], v174 offset:1024
	ds_read_b128 v[166:169], v174 offset:2048
	ds_read_b128 v[174:177], v174 offset:3072
	ds_read_b128 v[178:181], v190
	ds_read_b128 v[182:185], v190 offset:1024
	ds_read_b128 v[186:189], v190 offset:2048
	ds_read_b128 v[190:193], v190 offset:3072
	s_add_u32 s68, s68, 0x40000
	s_addc_u32 s69, s69, 0
	s_mov_b32 m0, s77
	ds_read_b128 v[194:197], v152 offset:32768
	ds_read_b128 v[198:201], v152 offset:33792
	ds_read_b128 v[202:205], v152 offset:34816
	ds_read_b128 v[206:209], v152 offset:35840
	ds_read_b128 v[210:213], v152 offset:36864
	ds_read_b128 v[214:217], v152 offset:37888
	ds_read_b128 v[218:221], v152 offset:38912
	ds_read_b128 v[222:225], v152 offset:39936
	global_load_lds_dwordx4 v130, s[68:69]
	s_mov_b32 m0, s78
	s_nop 0
	global_load_lds_dwordx4 v134, s[68:69]
	s_waitcnt vmcnt(8)
	s_waitcnt lgkmcnt(0)
	s_setprio 1
	v_mfma_f32_16x16x32_bf16 v[126:129], v[158:161], v[194:197], v[126:129]
	v_mfma_f32_16x16x32_bf16 v[118:121], v[166:169], v[194:197], v[118:121]
	v_mfma_f32_16x16x32_bf16 v[110:113], v[158:161], v[202:205], v[110:113]
	v_mfma_f32_16x16x32_bf16 v[102:105], v[166:169], v[202:205], v[102:105]
	v_mfma_f32_16x16x32_bf16 v[94:97], v[158:161], v[210:213], v[94:97]
	v_mfma_f32_16x16x32_bf16 v[86:89], v[166:169], v[210:213], v[86:89]
	v_mfma_f32_16x16x32_bf16 v[78:81], v[158:161], v[218:221], v[78:81]
	v_mfma_f32_16x16x32_bf16 v[70:73], v[166:169], v[218:221], v[70:73]
	s_barrier
	v_mfma_f32_16x16x32_bf16 v[126:129], v[162:165], v[198:201], v[126:129]
	v_mfma_f32_16x16x32_bf16 v[118:121], v[174:177], v[198:201], v[118:121]
	v_mfma_f32_16x16x32_bf16 v[110:113], v[162:165], v[206:209], v[110:113]
	v_mfma_f32_16x16x32_bf16 v[102:105], v[174:177], v[206:209], v[102:105]
	v_mfma_f32_16x16x32_bf16 v[94:97], v[162:165], v[214:217], v[94:97]
	v_mfma_f32_16x16x32_bf16 v[86:89], v[174:177], v[214:217], v[86:89]
	v_mfma_f32_16x16x32_bf16 v[78:81], v[162:165], v[222:225], v[78:81]
	v_mfma_f32_16x16x32_bf16 v[70:73], v[174:177], v[222:225], v[70:73]
	v_mfma_f32_16x16x32_bf16 v[122:125], v[178:181], v[194:197], v[122:125]
	v_mfma_f32_16x16x32_bf16 v[114:117], v[186:189], v[194:197], v[114:117]
	v_mfma_f32_16x16x32_bf16 v[106:109], v[178:181], v[202:205], v[106:109]
	v_mfma_f32_16x16x32_bf16 v[98:101], v[186:189], v[202:205], v[98:101]
	v_mfma_f32_16x16x32_bf16 v[90:93], v[178:181], v[210:213], v[90:93]
	v_mfma_f32_16x16x32_bf16 v[82:85], v[186:189], v[210:213], v[82:85]
	v_mfma_f32_16x16x32_bf16 v[74:77], v[178:181], v[218:221], v[74:77]
	v_mfma_f32_16x16x32_bf16 v[66:69], v[186:189], v[218:221], v[66:69]
	v_mfma_f32_16x16x32_bf16 v[122:125], v[182:185], v[198:201], v[122:125]
	v_mfma_f32_16x16x32_bf16 v[114:117], v[190:193], v[198:201], v[114:117]
	v_mfma_f32_16x16x32_bf16 v[106:109], v[182:185], v[206:209], v[106:109]
	v_mfma_f32_16x16x32_bf16 v[98:101], v[190:193], v[206:209], v[98:101]
	v_mfma_f32_16x16x32_bf16 v[90:93], v[182:185], v[214:217], v[90:93]
	v_mfma_f32_16x16x32_bf16 v[82:85], v[190:193], v[214:217], v[82:85]
	v_mfma_f32_16x16x32_bf16 v[74:77], v[182:185], v[222:225], v[74:77]
	v_mfma_f32_16x16x32_bf16 v[66:69], v[190:193], v[222:225], v[66:69]
	s_barrier
; #define PG8_STAGE(bufoff, gbase, voff) do { _Pragma("unroll") for (int _i = 0; _i < 2; ++_i) \
;         __builtin_amdgcn_global_load_lds((const unsigned*)((const char*)(gbase) + (voff)[_i]), (LAS unsigned*)(lds + (bufoff) + ldsw + _i * 8192), 16, 0, 0); } while (0)
; #define PG8_LDA(dst, b, h) do { _Pragma("unroll") for (int m = 0; m < 4; ++m) _Pragma("unroll") for (int k = 0; k < 2; ++k) dst[m][k] = *(const LAS bf16x8*)(lds + PG8_SA(b, h) + aoff + m * 2048 + k * 1024); } while (0)
; #define PG8_MMA(ai, bj, At, Bt) do { __builtin_amdgcn_s_setprio(1); _Pragma("unroll") for (int m = 0; m < 4; ++m) _Pragma("unroll") for (int n = 0; n < 2; ++n) _Pragma("unroll") for (int k = 0; k < 2; ++k) \
;         acc[ai][bj][m][n] = __builtin_amdgcn_mfma_f32_16x16x32_bf16(Bt[n][k], At[m][k], acc[ai][bj][m][n], 0, 0, 0); __builtin_amdgcn_s_setprio(0); } while (0)
; #define PG8_WAIT_V(n) asm volatile("s_waitcnt vmcnt(" #n ")" ::: "memory")
; #define PG8_WAIT_L(n) asm volatile("s_waitcnt lgkmcnt(" #n ")" ::: "memory")
; #define PG8_BAR __builtin_amdgcn_s_barrier()
; #define PG8_SCHED __builtin_amdgcn_sched_barrier(0)
; template <class Epi>
; __device__ __forceinline__ void gemm_phase(LAS unsigned char* lds, const Gemm g, const StaticOrder& S, const Epi& E) {
;     ...
;             PG8_LDA(At, 1, 1); PG8_STAGE(PG8_SB(1, 0), b3, voffB); PG8_STAGE(PG8_SB(1, 1), b3 + hstep, voffB); PG8_STAGE(PG8_SA(1, 0), a3, voffA);
;             PG8_WAIT_V(8); PG8_WAIT_L(0); PG8_BAR; PG8_MMA(1, 0, At, B0); PG8_MMA(1, 1, At, B1); PG8_BAR; PG8_SCHED;
;         }
;         if (wr == 0) PG8_BAR;
	s_setprio 0
	s_add_i32 s68, s93, s6
	s_mov_b32 m0, s68
	ds_read_b128 v[194:197], v152 offset:49152
	ds_read_b128 v[198:201], v152 offset:50176
	ds_read_b128 v[202:205], v152 offset:51200
	ds_read_b128 v[206:209], v152 offset:52224
	ds_read_b128 v[210:213], v152 offset:53248
	ds_read_b128 v[214:217], v152 offset:54272
	ds_read_b128 v[218:221], v152 offset:55296
	ds_read_b128 v[222:225], v152 offset:56320
	global_load_lds_dwordx4 v132, s[98:99]
	s_add_i32 m0, s68, 0x2000
	s_add_u32 s66, s66, 0x40080
	s_addc_u32 s67, s67, 0
	s_add_i32 s68, s94, s6
	global_load_lds_dwordx4 v136, s[98:99]
	s_mov_b32 m0, s68
	s_nop 0
	global_load_lds_dwordx4 v132, s[66:67]
	s_add_i32 m0, s68, 0x2000
	s_nop 0
	global_load_lds_dwordx4 v136, s[66:67]
	s_mov_b32 m0, s79
	s_nop 0
	global_load_lds_dwordx4 v130, s[100:101]
	s_mov_b32 m0, s80
	s_nop 0
	global_load_lds_dwordx4 v134, s[100:101]
	s_waitcnt vmcnt(8)
	s_waitcnt lgkmcnt(0)
	s_setprio 1
	v_mfma_f32_16x16x32_bf16 v[62:65], v[158:161], v[194:197], v[62:65]
	v_mfma_f32_16x16x32_bf16 v[54:57], v[166:169], v[194:197], v[54:57]
	v_mfma_f32_16x16x32_bf16 v[46:49], v[158:161], v[202:205], v[46:49]
	v_mfma_f32_16x16x32_bf16 v[38:41], v[166:169], v[202:205], v[38:41]
	v_mfma_f32_16x16x32_bf16 v[30:33], v[158:161], v[210:213], v[30:33]
	v_mfma_f32_16x16x32_bf16 v[22:25], v[166:169], v[210:213], v[22:25]
	v_mfma_f32_16x16x32_bf16 v[14:17], v[158:161], v[218:221], v[14:17]
	v_mfma_f32_16x16x32_bf16 v[6:9], v[166:169], v[218:221], v[6:9]
	s_barrier
	v_mfma_f32_16x16x32_bf16 v[62:65], v[162:165], v[198:201], v[62:65]
	v_mfma_f32_16x16x32_bf16 v[54:57], v[174:177], v[198:201], v[54:57]
	v_mfma_f32_16x16x32_bf16 v[46:49], v[162:165], v[206:209], v[46:49]
	v_mfma_f32_16x16x32_bf16 v[38:41], v[174:177], v[206:209], v[38:41]
	v_mfma_f32_16x16x32_bf16 v[30:33], v[162:165], v[214:217], v[30:33]
	v_mfma_f32_16x16x32_bf16 v[22:25], v[174:177], v[214:217], v[22:25]
	v_mfma_f32_16x16x32_bf16 v[14:17], v[162:165], v[222:225], v[14:17]
	v_mfma_f32_16x16x32_bf16 v[6:9], v[174:177], v[222:225], v[6:9]
	v_mfma_f32_16x16x32_bf16 v[58:61], v[178:181], v[194:197], v[58:61]
	v_mfma_f32_16x16x32_bf16 v[50:53], v[186:189], v[194:197], v[50:53]
	v_mfma_f32_16x16x32_bf16 v[42:45], v[178:181], v[202:205], v[42:45]
	v_mfma_f32_16x16x32_bf16 v[34:37], v[186:189], v[202:205], v[34:37]
	v_mfma_f32_16x16x32_bf16 v[26:29], v[178:181], v[210:213], v[26:29]
	v_mfma_f32_16x16x32_bf16 v[18:21], v[186:189], v[210:213], v[18:21]
	v_mfma_f32_16x16x32_bf16 v[10:13], v[178:181], v[218:221], v[10:13]
	v_mfma_f32_16x16x32_bf16 v[2:5], v[186:189], v[218:221], v[2:5]
	v_mfma_f32_16x16x32_bf16 v[58:61], v[182:185], v[198:201], v[58:61]
	v_mfma_f32_16x16x32_bf16 v[50:53], v[190:193], v[198:201], v[50:53]
	v_mfma_f32_16x16x32_bf16 v[42:45], v[182:185], v[206:209], v[42:45]
	v_mfma_f32_16x16x32_bf16 v[34:37], v[190:193], v[206:209], v[34:37]
	v_mfma_f32_16x16x32_bf16 v[26:29], v[182:185], v[214:217], v[26:29]
	v_mfma_f32_16x16x32_bf16 v[18:21], v[190:193], v[214:217], v[18:21]
	v_mfma_f32_16x16x32_bf16 v[10:13], v[182:185], v[222:225], v[10:13]
	v_mfma_f32_16x16x32_bf16 v[2:5], v[190:193], v[222:225], v[2:5]
	s_barrier
	s_setprio 0
	s_add_i32 s92, s92, 2
	s_add_u32 s64, s64, 0x100
	s_addc_u32 s65, s65, 0
	s_add_u32 s90, s90, 0x100
	s_addc_u32 s91, s91, 0
	s_cmp_gt_u32 s92, 13
	s_cbranch_scc0 .LBB0_134
	s_and_b64 vcc, exec, s[38:39]
	s_cbranch_vccz .LBB0_137
	s_barrier

; #define PG8_STAGE(bufoff, gbase, voff) do { _Pragma("unroll") for (int _i = 0; _i < 2; ++_i) \
;         __builtin_amdgcn_global_load_lds((const unsigned*)((const char*)(gbase) + (voff)[_i]), (LAS unsigned*)(lds + (bufoff) + ldsw + _i * 8192), 16, 0, 0); } while (0)
; #define PG8_LDA(dst, b, h) do { _Pragma("unroll") for (int m = 0; m < 4; ++m) _Pragma("unroll") for (int k = 0; k < 2; ++k) dst[m][k] = *(const LAS bf16x8*)(lds + PG8_SA(b, h) + aoff + m * 2048 + k * 1024); } while (0)
; #define PG8_LDB(dst, b, h) do { _Pragma("unroll") for (int n = 0; n < 2; ++n) _Pragma("unroll") for (int k = 0; k < 2; ++k) dst[n][k] = *(const LAS bf16x8*)(lds + PG8_SB(b, h) + boff + n * 2048 + k * 1024); } while (0)
; #define PG8_MMA(ai, bj, At, Bt) do { __builtin_amdgcn_s_setprio(1); _Pragma("unroll") for (int m = 0; m < 4; ++m) _Pragma("unroll") for (int n = 0; n < 2; ++n) _Pragma("unroll") for (int k = 0; k < 2; ++k) \
;         acc[ai][bj][m][n] = __builtin_amdgcn_mfma_f32_16x16x32_bf16(Bt[n][k], At[m][k], acc[ai][bj][m][n], 0, 0, 0); __builtin_amdgcn_s_setprio(0); } while (0)
; #define PG8_WAIT_V(n) asm volatile("s_waitcnt vmcnt(" #n ")" ::: "memory")
; #define PG8_WAIT_L(n) asm volatile("s_waitcnt lgkmcnt(" #n ")" ::: "memory")
; #define PG8_BAR __builtin_amdgcn_s_barrier()
; template <class Epi>
; __device__ __forceinline__ void gemm_phase(LAS unsigned char* lds, const Gemm g, const StaticOrder& S, const Epi& E) {
;     ...
;         for (int t = 0; t < nt; t += 2) {
;             const bool last = (t == nt - 2);
;             const char* a1 = cA + (size_t)(t + 1) * kstep;
;             const char* a2 = last ? nA : cA + (size_t)(t + 2) * kstep; const char* b2 = last ? nB : cB + (size_t)(t + 2) * kstep;
;             const char* a3 = a2 + kstep; const char* b3 = b2 + kstep;
;             if constexpr (Epi::MIDK > 0) { if (t == Epi::MIDK) E.mid(acc, cur, wr, wc, fr, fq); }
;             PG8_LDB(B0, 0, 0); PG8_LDB(B1, 0, 1); PG8_SCHED; PG8_LDA(At, 0, 0); PG8_STAGE(PG8_SA(1, 1), a1 + hstep, voffA);
;             PG8_WAIT_V(8); PG8_WAIT_L(0); PG8_BAR; PG8_MMA(0, 0, At, B0); PG8_MMA(0, 1, At, B1); PG8_BAR; PG8_SCHED;
;             PG8_LDA(At, 0, 1); PG8_STAGE(PG8_SB(0, 0), b2, voffB); PG8_STAGE(PG8_SB(0, 1), b2 + hstep, voffB); PG8_STAGE(PG8_SA(0, 0), a2, voffA);
;             PG8_WAIT_V(8); PG8_WAIT_L(0); PG8_BAR; PG8_MMA(1, 0, At, B0); PG8_MMA(1, 1, At, B1); PG8_BAR; PG8_SCHED;
.LBB0_221:
	ds_read_b128 v[130:133], v162
	ds_read_b128 v[134:137], v162 offset:1024
	ds_read_b128 v[154:157], v162 offset:2048
	ds_read_b128 v[166:169], v162 offset:3072
	ds_read_b128 v[174:177], v163
	ds_read_b128 v[178:181], v163 offset:1024
	ds_read_b128 v[182:185], v163 offset:2048
	ds_read_b128 v[186:189], v163 offset:3072
	s_add_u32 s48, s46, 0xfff50080
	s_addc_u32 s49, s47, -1
	s_cmp_eq_u32 s84, 40
	s_cselect_b32 s51, s5, s49
	s_cselect_b32 s50, s4, s48
	s_cselect_b32 s49, s45, s83
	s_cselect_b32 s48, s44, s82
	s_add_i32 m0, s59, 0xc000
	ds_read_b128 v[190:193], v164
	ds_read_b128 v[194:197], v164 offset:1024
	ds_read_b128 v[198:201], v164 offset:2048
	ds_read_b128 v[202:205], v164 offset:3072
	ds_read_b128 v[206:209], v164 offset:4096
	ds_read_b128 v[210:213], v164 offset:5120
	ds_read_b128 v[214:217], v164 offset:6144
	ds_read_b128 v[218:221], v164 offset:7168
	global_load_lds_dwordx4 v146, s[46:47]
	s_add_i32 m0, s59, 0xe000
	s_nop 0
	global_load_lds_dwordx4 v148, s[46:47]
	s_waitcnt vmcnt(8)
	s_waitcnt lgkmcnt(0)
	s_setprio 1
	v_mfma_f32_16x16x32_bf16 v[126:129], v[130:133], v[190:193], v[126:129]
	v_mfma_f32_16x16x32_bf16 v[122:125], v[154:157], v[190:193], v[122:125]
	v_mfma_f32_16x16x32_bf16 v[110:113], v[130:133], v[198:201], v[110:113]
	v_mfma_f32_16x16x32_bf16 v[106:109], v[154:157], v[198:201], v[106:109]
	v_mfma_f32_16x16x32_bf16 v[94:97], v[130:133], v[206:209], v[94:97]
	v_mfma_f32_16x16x32_bf16 v[90:93], v[154:157], v[206:209], v[90:93]
	v_mfma_f32_16x16x32_bf16 v[78:81], v[130:133], v[214:217], v[78:81]
	v_mfma_f32_16x16x32_bf16 v[74:77], v[154:157], v[214:217], v[74:77]
	s_barrier
	v_mfma_f32_16x16x32_bf16 v[126:129], v[134:137], v[194:197], v[126:129]
	v_mfma_f32_16x16x32_bf16 v[122:125], v[166:169], v[194:197], v[122:125]
	v_mfma_f32_16x16x32_bf16 v[110:113], v[134:137], v[202:205], v[110:113]
	v_mfma_f32_16x16x32_bf16 v[106:109], v[166:169], v[202:205], v[106:109]
	v_mfma_f32_16x16x32_bf16 v[94:97], v[134:137], v[210:213], v[94:97]
	v_mfma_f32_16x16x32_bf16 v[90:93], v[166:169], v[210:213], v[90:93]
	v_mfma_f32_16x16x32_bf16 v[78:81], v[134:137], v[218:221], v[78:81]
	v_mfma_f32_16x16x32_bf16 v[74:77], v[166:169], v[218:221], v[74:77]
	v_mfma_f32_16x16x32_bf16 v[118:121], v[174:177], v[190:193], v[118:121]
	v_mfma_f32_16x16x32_bf16 v[114:117], v[182:185], v[190:193], v[114:117]
	v_mfma_f32_16x16x32_bf16 v[102:105], v[174:177], v[198:201], v[102:105]
	v_mfma_f32_16x16x32_bf16 v[98:101], v[182:185], v[198:201], v[98:101]
	v_mfma_f32_16x16x32_bf16 v[86:89], v[174:177], v[206:209], v[86:89]
	v_mfma_f32_16x16x32_bf16 v[82:85], v[182:185], v[206:209], v[82:85]
	v_mfma_f32_16x16x32_bf16 v[70:73], v[174:177], v[214:217], v[70:73]
	v_mfma_f32_16x16x32_bf16 v[66:69], v[182:185], v[214:217], v[66:69]
	v_mfma_f32_16x16x32_bf16 v[118:121], v[178:181], v[194:197], v[118:121]
	v_mfma_f32_16x16x32_bf16 v[114:117], v[186:189], v[194:197], v[114:117]
	v_mfma_f32_16x16x32_bf16 v[102:105], v[178:181], v[202:205], v[102:105]
	v_mfma_f32_16x16x32_bf16 v[98:101], v[186:189], v[202:205], v[98:101]
	v_mfma_f32_16x16x32_bf16 v[86:89], v[178:181], v[210:213], v[86:89]
	v_mfma_f32_16x16x32_bf16 v[82:85], v[186:189], v[210:213], v[82:85]
	v_mfma_f32_16x16x32_bf16 v[70:73], v[178:181], v[218:221], v[70:73]
	v_mfma_f32_16x16x32_bf16 v[66:69], v[186:189], v[218:221], v[66:69]
	s_barrier
	s_setprio 0
	s_add_u32 s98, s48, s38
	s_addc_u32 s99, s49, s39
	s_add_u32 s100, s50, s38
	s_addc_u32 s101, s51, s39
	s_add_i32 s85, s76, s58
	s_mov_b32 m0, s85
	ds_read_b128 v[190:193], v164 offset:16384
	ds_read_b128 v[194:197], v164 offset:17408
	ds_read_b128 v[198:201], v164 offset:18432
	ds_read_b128 v[202:205], v164 offset:19456
	ds_read_b128 v[206:209], v164 offset:20480
	ds_read_b128 v[210:213], v164 offset:21504
	ds_read_b128 v[214:217], v164 offset:22528
	ds_read_b128 v[218:221], v164 offset:23552
	global_load_lds_dwordx4 v140, s[48:49]
	s_add_i32 m0, s85, 0x2000
	s_add_u32 s86, s48, 0xb0000
	s_addc_u32 s87, s49, 0
	s_add_i32 s85, s77, s58
	global_load_lds_dwordx4 v144, s[48:49]
	s_mov_b32 m0, s85
	s_nop 0
	global_load_lds_dwordx4 v140, s[86:87]
	s_add_i32 m0, s85, 0x2000
	s_nop 0
	global_load_lds_dwordx4 v144, s[86:87]
	s_mov_b32 m0, s59
	s_nop 0
	global_load_lds_dwordx4 v138, s[50:51]
	s_mov_b32 m0, s60
	s_nop 0
	global_load_lds_dwordx4 v142, s[50:51]
	s_waitcnt vmcnt(8)
	s_waitcnt lgkmcnt(0)
	s_setprio 1
	v_mfma_f32_16x16x32_bf16 v[62:65], v[130:133], v[190:193], v[62:65]
	v_mfma_f32_16x16x32_bf16 v[58:61], v[154:157], v[190:193], v[58:61]
	v_mfma_f32_16x16x32_bf16 v[46:49], v[130:133], v[198:201], v[46:49]
	v_mfma_f32_16x16x32_bf16 v[42:45], v[154:157], v[198:201], v[42:45]
	v_mfma_f32_16x16x32_bf16 v[30:33], v[130:133], v[206:209], v[30:33]
	v_mfma_f32_16x16x32_bf16 v[26:29], v[154:157], v[206:209], v[26:29]
	v_mfma_f32_16x16x32_bf16 v[14:17], v[130:133], v[214:217], v[14:17]
	v_mfma_f32_16x16x32_bf16 v[10:13], v[154:157], v[214:217], v[10:13]
	s_barrier
; #define PG8_STAGE(bufoff, gbase, voff) do { _Pragma("unroll") for (int _i = 0; _i < 2; ++_i) \
;         __builtin_amdgcn_global_load_lds((const unsigned*)((const char*)(gbase) + (voff)[_i]), (LAS unsigned*)(lds + (bufoff) + ldsw + _i * 8192), 16, 0, 0); } while (0)
; #define PG8_LDA(dst, b, h) do { _Pragma("unroll") for (int m = 0; m < 4; ++m) _Pragma("unroll") for (int k = 0; k < 2; ++k) dst[m][k] = *(const LAS bf16x8*)(lds + PG8_SA(b, h) + aoff + m * 2048 + k * 1024); } while (0)
; #define PG8_LDB(dst, b, h) do { _Pragma("unroll") for (int n = 0; n < 2; ++n) _Pragma("unroll") for (int k = 0; k < 2; ++k) dst[n][k] = *(const LAS bf16x8*)(lds + PG8_SB(b, h) + boff + n * 2048 + k * 1024); } while (0)
; #define PG8_MMA(ai, bj, At, Bt) do { __builtin_amdgcn_s_setprio(1); _Pragma("unroll") for (int m = 0; m < 4; ++m) _Pragma("unroll") for (int n = 0; n < 2; ++n) _Pragma("unroll") for (int k = 0; k < 2; ++k) \
;         acc[ai][bj][m][n] = __builtin_amdgcn_mfma_f32_16x16x32_bf16(Bt[n][k], At[m][k], acc[ai][bj][m][n], 0, 0, 0); __builtin_amdgcn_s_setprio(0); } while (0)
; #define PG8_WAIT_V(n) asm volatile("s_waitcnt vmcnt(" #n ")" ::: "memory")
; #define PG8_WAIT_L(n) asm volatile("s_waitcnt lgkmcnt(" #n ")" ::: "memory")
; #define PG8_BAR __builtin_amdgcn_s_barrier()
; #define PG8_SCHED __builtin_amdgcn_sched_barrier(0)
; template <class Epi>
; __device__ __forceinline__ void gemm_phase(LAS unsigned char* lds, const Gemm g, const StaticOrder& S, const Epi& E) {
;     ...
;             PG8_WAIT_V(8); PG8_WAIT_L(0); PG8_BAR; PG8_MMA(1, 0, At, B0); PG8_MMA(1, 1, At, B1); PG8_BAR; PG8_SCHED;
;             PG8_LDB(B0, 1, 0); PG8_LDB(B1, 1, 1); PG8_SCHED; PG8_LDA(At, 1, 0); PG8_STAGE(PG8_SA(0, 1), a2 + hstep, voffA);
;             PG8_WAIT_V(8); PG8_WAIT_L(0); PG8_BAR; PG8_MMA(0, 0, At, B0); PG8_MMA(0, 1, At, B1); PG8_BAR; PG8_SCHED;
	v_mfma_f32_16x16x32_bf16 v[62:65], v[134:137], v[194:197], v[62:65]
	v_mfma_f32_16x16x32_bf16 v[58:61], v[166:169], v[194:197], v[58:61]
	v_mfma_f32_16x16x32_bf16 v[46:49], v[134:137], v[202:205], v[46:49]
	v_mfma_f32_16x16x32_bf16 v[42:45], v[166:169], v[202:205], v[42:45]
	v_mfma_f32_16x16x32_bf16 v[30:33], v[134:137], v[210:213], v[30:33]
	v_mfma_f32_16x16x32_bf16 v[26:29], v[166:169], v[210:213], v[26:29]
	v_mfma_f32_16x16x32_bf16 v[14:17], v[134:137], v[218:221], v[14:17]
	v_mfma_f32_16x16x32_bf16 v[10:13], v[166:169], v[218:221], v[10:13]
	v_mfma_f32_16x16x32_bf16 v[54:57], v[174:177], v[190:193], v[54:57]
	v_mfma_f32_16x16x32_bf16 v[50:53], v[182:185], v[190:193], v[50:53]
	v_mfma_f32_16x16x32_bf16 v[38:41], v[174:177], v[198:201], v[38:41]
	v_mfma_f32_16x16x32_bf16 v[34:37], v[182:185], v[198:201], v[34:37]
	v_mfma_f32_16x16x32_bf16 v[22:25], v[174:177], v[206:209], v[22:25]
	v_mfma_f32_16x16x32_bf16 v[18:21], v[182:185], v[206:209], v[18:21]
	v_mfma_f32_16x16x32_bf16 v[6:9], v[174:177], v[214:217], v[6:9]
	v_mfma_f32_16x16x32_bf16 v[2:5], v[182:185], v[214:217], v[2:5]
	v_mfma_f32_16x16x32_bf16 v[54:57], v[178:181], v[194:197], v[54:57]
	v_mfma_f32_16x16x32_bf16 v[50:53], v[186:189], v[194:197], v[50:53]
	v_mfma_f32_16x16x32_bf16 v[38:41], v[178:181], v[202:205], v[38:41]
	v_mfma_f32_16x16x32_bf16 v[34:37], v[186:189], v[202:205], v[34:37]
	v_mfma_f32_16x16x32_bf16 v[22:25], v[178:181], v[210:213], v[22:25]
	v_mfma_f32_16x16x32_bf16 v[18:21], v[186:189], v[210:213], v[18:21]
	v_mfma_f32_16x16x32_bf16 v[6:9], v[178:181], v[218:221], v[6:9]
	v_mfma_f32_16x16x32_bf16 v[2:5], v[186:189], v[218:221], v[2:5]
	s_barrier
	s_setprio 0
	s_add_i32 s85, 0, 0x18000
	s_add_i32 s86, 0, 0x1c000
	v_add_u32_e32 v166, s85, v160
	v_add_u32_e32 v186, s86, v160
	ds_read_b128 v[130:133], v166
	ds_read_b128 v[134:137], v166 offset:1024
	ds_read_b128 v[154:157], v166 offset:2048
	ds_read_b128 v[166:169], v166 offset:3072
	ds_read_b128 v[174:177], v186
	ds_read_b128 v[178:181], v186 offset:1024
	ds_read_b128 v[182:185], v186 offset:2048
	ds_read_b128 v[186:189], v186 offset:3072
	s_add_u32 s50, s50, 0xb0000
	s_addc_u32 s51, s51, 0
	s_mov_b32 m0, s61
	ds_read_b128 v[190:193], v164 offset:32768
	ds_read_b128 v[194:197], v164 offset:33792
	ds_read_b128 v[198:201], v164 offset:34816
	ds_read_b128 v[202:205], v164 offset:35840
	ds_read_b128 v[206:209], v164 offset:36864
	ds_read_b128 v[210:213], v164 offset:37888
	ds_read_b128 v[214:217], v164 offset:38912
	ds_read_b128 v[218:221], v164 offset:39936
	global_load_lds_dwordx4 v138, s[50:51]
	s_mov_b32 m0, s62
	s_nop 0
	global_load_lds_dwordx4 v142, s[50:51]
	s_waitcnt vmcnt(8)
	s_waitcnt lgkmcnt(0)
	s_setprio 1
	v_mfma_f32_16x16x32_bf16 v[126:129], v[130:133], v[190:193], v[126:129]
	v_mfma_f32_16x16x32_bf16 v[122:125], v[154:157], v[190:193], v[122:125]
	v_mfma_f32_16x16x32_bf16 v[110:113], v[130:133], v[198:201], v[110:113]
	v_mfma_f32_16x16x32_bf16 v[106:109], v[154:157], v[198:201], v[106:109]
	v_mfma_f32_16x16x32_bf16 v[94:97], v[130:133], v[206:209], v[94:97]
	v_mfma_f32_16x16x32_bf16 v[90:93], v[154:157], v[206:209], v[90:93]
	v_mfma_f32_16x16x32_bf16 v[78:81], v[130:133], v[214:217], v[78:81]
	v_mfma_f32_16x16x32_bf16 v[74:77], v[154:157], v[214:217], v[74:77]
	s_barrier
	v_mfma_f32_16x16x32_bf16 v[126:129], v[134:137], v[194:197], v[126:129]
	v_mfma_f32_16x16x32_bf16 v[122:125], v[166:169], v[194:197], v[122:125]
	v_mfma_f32_16x16x32_bf16 v[110:113], v[134:137], v[202:205], v[110:113]
	v_mfma_f32_16x16x32_bf16 v[106:109], v[166:169], v[202:205], v[106:109]
	v_mfma_f32_16x16x32_bf16 v[94:97], v[134:137], v[210:213], v[94:97]
	v_mfma_f32_16x16x32_bf16 v[90:93], v[166:169], v[210:213], v[90:93]
	v_mfma_f32_16x16x32_bf16 v[78:81], v[134:137], v[218:221], v[78:81]
	v_mfma_f32_16x16x32_bf16 v[74:77], v[166:169], v[218:221], v[74:77]
	v_mfma_f32_16x16x32_bf16 v[118:121], v[174:177], v[190:193], v[118:121]
	v_mfma_f32_16x16x32_bf16 v[114:117], v[182:185], v[190:193], v[114:117]
	v_mfma_f32_16x16x32_bf16 v[102:105], v[174:177], v[198:201], v[102:105]
	v_mfma_f32_16x16x32_bf16 v[98:101], v[182:185], v[198:201], v[98:101]
	v_mfma_f32_16x16x32_bf16 v[86:89], v[174:177], v[206:209], v[86:89]
	v_mfma_f32_16x16x32_bf16 v[82:85], v[182:185], v[206:209], v[82:85]
	v_mfma_f32_16x16x32_bf16 v[70:73], v[174:177], v[214:217], v[70:73]
	v_mfma_f32_16x16x32_bf16 v[66:69], v[182:185], v[214:217], v[66:69]
	v_mfma_f32_16x16x32_bf16 v[118:121], v[178:181], v[194:197], v[118:121]
	v_mfma_f32_16x16x32_bf16 v[114:117], v[186:189], v[194:197], v[114:117]
	v_mfma_f32_16x16x32_bf16 v[102:105], v[178:181], v[202:205], v[102:105]
	v_mfma_f32_16x16x32_bf16 v[98:101], v[186:189], v[202:205], v[98:101]
	v_mfma_f32_16x16x32_bf16 v[86:89], v[178:181], v[210:213], v[86:89]
	v_mfma_f32_16x16x32_bf16 v[82:85], v[186:189], v[210:213], v[82:85]
	v_mfma_f32_16x16x32_bf16 v[70:73], v[178:181], v[218:221], v[70:73]
	v_mfma_f32_16x16x32_bf16 v[66:69], v[186:189], v[218:221], v[66:69]
	s_barrier
; #define PG8_STAGE(bufoff, gbase, voff) do { _Pragma("unroll") for (int _i = 0; _i < 2; ++_i) \
;         __builtin_amdgcn_global_load_lds((const unsigned*)((const char*)(gbase) + (voff)[_i]), (LAS unsigned*)(lds + (bufoff) + ldsw + _i * 8192), 16, 0, 0); } while (0)
; #define PG8_LDA(dst, b, h) do { _Pragma("unroll") for (int m = 0; m < 4; ++m) _Pragma("unroll") for (int k = 0; k < 2; ++k) dst[m][k] = *(const LAS bf16x8*)(lds + PG8_SA(b, h) + aoff + m * 2048 + k * 1024); } while (0)
; #define PG8_MMA(ai, bj, At, Bt) do { __builtin_amdgcn_s_setprio(1); _Pragma("unroll") for (int m = 0; m < 4; ++m) _Pragma("unroll") for (int n = 0; n < 2; ++n) _Pragma("unroll") for (int k = 0; k < 2; ++k) \
;         acc[ai][bj][m][n] = __builtin_amdgcn_mfma_f32_16x16x32_bf16(Bt[n][k], At[m][k], acc[ai][bj][m][n], 0, 0, 0); __builtin_amdgcn_s_setprio(0); } while (0)
; #define PG8_WAIT_V(n) asm volatile("s_waitcnt vmcnt(" #n ")" ::: "memory")
; #define PG8_WAIT_L(n) asm volatile("s_waitcnt lgkmcnt(" #n ")" ::: "memory")
; #define PG8_BAR __builtin_amdgcn_s_barrier()
; #define PG8_SCHED __builtin_amdgcn_sched_barrier(0)
; template <class Epi>
; __device__ __forceinline__ void gemm_phase(LAS unsigned char* lds, const Gemm g, const StaticOrder& S, const Epi& E) {
;     ...
;             PG8_LDA(At, 1, 1); PG8_STAGE(PG8_SB(1, 0), b3, voffB); PG8_STAGE(PG8_SB(1, 1), b3 + hstep, voffB); PG8_STAGE(PG8_SA(1, 0), a3, voffA);
;             PG8_WAIT_V(8); PG8_WAIT_L(0); PG8_BAR; PG8_MMA(1, 0, At, B0); PG8_MMA(1, 1, At, B1); PG8_BAR; PG8_SCHED;
;         }
;         if (wr == 0) PG8_BAR;
	s_setprio 0
	s_add_i32 s50, s85, s58
	s_mov_b32 m0, s50
	ds_read_b128 v[190:193], v164 offset:49152
	ds_read_b128 v[194:197], v164 offset:50176
	ds_read_b128 v[198:201], v164 offset:51200
	ds_read_b128 v[202:205], v164 offset:52224
	ds_read_b128 v[206:209], v164 offset:53248
	ds_read_b128 v[210:213], v164 offset:54272
	ds_read_b128 v[214:217], v164 offset:55296
	ds_read_b128 v[218:221], v164 offset:56320
	global_load_lds_dwordx4 v140, s[98:99]
	s_add_i32 m0, s50, 0x2000
	s_add_u32 s48, s48, 0xb0080
	s_addc_u32 s49, s49, 0
	s_add_i32 s50, s86, s58
	global_load_lds_dwordx4 v144, s[98:99]
	s_mov_b32 m0, s50
	s_nop 0
	global_load_lds_dwordx4 v140, s[48:49]
	s_add_i32 m0, s50, 0x2000
	s_nop 0
	global_load_lds_dwordx4 v144, s[48:49]
	s_mov_b32 m0, s64
	s_nop 0
	global_load_lds_dwordx4 v138, s[100:101]
	s_mov_b32 m0, s65
	s_nop 0
	global_load_lds_dwordx4 v142, s[100:101]
	s_waitcnt vmcnt(8)
	s_waitcnt lgkmcnt(0)
	s_setprio 1
	v_mfma_f32_16x16x32_bf16 v[62:65], v[130:133], v[190:193], v[62:65]
	v_mfma_f32_16x16x32_bf16 v[58:61], v[154:157], v[190:193], v[58:61]
	v_mfma_f32_16x16x32_bf16 v[46:49], v[130:133], v[198:201], v[46:49]
	v_mfma_f32_16x16x32_bf16 v[42:45], v[154:157], v[198:201], v[42:45]
	v_mfma_f32_16x16x32_bf16 v[30:33], v[130:133], v[206:209], v[30:33]
	v_mfma_f32_16x16x32_bf16 v[26:29], v[154:157], v[206:209], v[26:29]
	v_mfma_f32_16x16x32_bf16 v[14:17], v[130:133], v[214:217], v[14:17]
	v_mfma_f32_16x16x32_bf16 v[10:13], v[154:157], v[214:217], v[10:13]
	s_barrier
	v_mfma_f32_16x16x32_bf16 v[62:65], v[134:137], v[194:197], v[62:65]
	v_mfma_f32_16x16x32_bf16 v[58:61], v[166:169], v[194:197], v[58:61]
	v_mfma_f32_16x16x32_bf16 v[46:49], v[134:137], v[202:205], v[46:49]
	v_mfma_f32_16x16x32_bf16 v[42:45], v[166:169], v[202:205], v[42:45]
	v_mfma_f32_16x16x32_bf16 v[30:33], v[134:137], v[210:213], v[30:33]
	v_mfma_f32_16x16x32_bf16 v[26:29], v[166:169], v[210:213], v[26:29]
	v_mfma_f32_16x16x32_bf16 v[14:17], v[134:137], v[218:221], v[14:17]
	v_mfma_f32_16x16x32_bf16 v[10:13], v[166:169], v[218:221], v[10:13]
	v_mfma_f32_16x16x32_bf16 v[54:57], v[174:177], v[190:193], v[54:57]
	v_mfma_f32_16x16x32_bf16 v[50:53], v[182:185], v[190:193], v[50:53]
	v_mfma_f32_16x16x32_bf16 v[38:41], v[174:177], v[198:201], v[38:41]
	v_mfma_f32_16x16x32_bf16 v[34:37], v[182:185], v[198:201], v[34:37]
	v_mfma_f32_16x16x32_bf16 v[22:25], v[174:177], v[206:209], v[22:25]
	v_mfma_f32_16x16x32_bf16 v[18:21], v[182:185], v[206:209], v[18:21]
	v_mfma_f32_16x16x32_bf16 v[6:9], v[174:177], v[214:217], v[6:9]
	v_mfma_f32_16x16x32_bf16 v[2:5], v[182:185], v[214:217], v[2:5]
	v_mfma_f32_16x16x32_bf16 v[54:57], v[178:181], v[194:197], v[54:57]
	v_mfma_f32_16x16x32_bf16 v[50:53], v[186:189], v[194:197], v[50:53]
	v_mfma_f32_16x16x32_bf16 v[38:41], v[178:181], v[202:205], v[38:41]
	v_mfma_f32_16x16x32_bf16 v[34:37], v[186:189], v[202:205], v[34:37]
	v_mfma_f32_16x16x32_bf16 v[22:25], v[178:181], v[210:213], v[22:25]
	v_mfma_f32_16x16x32_bf16 v[18:21], v[186:189], v[210:213], v[18:21]
	v_mfma_f32_16x16x32_bf16 v[6:9], v[178:181], v[218:221], v[6:9]
	v_mfma_f32_16x16x32_bf16 v[2:5], v[186:189], v[218:221], v[2:5]
	s_barrier
	s_setprio 0
	s_add_i32 s84, s84, 2
	s_add_u32 s46, s46, 0x100
	s_addc_u32 s47, s47, 0
	s_add_u32 s82, s82, 0x100
	s_addc_u32 s83, s83, 0
	s_cmp_gt_u32 s84, 41
	s_cbranch_scc0 .LBB0_221
	s_and_b64 vcc, exec, s[42:43]
	s_cbranch_vccz .LBB0_224
	s_barrier

; #define PG8_STAGE(bufoff, gbase, voff) do { _Pragma("unroll") for (int _i = 0; _i < 2; ++_i) \
;         __builtin_amdgcn_global_load_lds((const unsigned*)((const char*)(gbase) + (voff)[_i]), (LAS unsigned*)(lds + (bufoff) + ldsw + _i * 8192), 16, 0, 0); } while (0)
; #define PG8_LDA(dst, b, h) do { _Pragma("unroll") for (int m = 0; m < 4; ++m) _Pragma("unroll") for (int k = 0; k < 2; ++k) dst[m][k] = *(const LAS bf16x8*)(lds + PG8_SA(b, h) + aoff + m * 2048 + k * 1024); } while (0)
; #define PG8_LDB(dst, b, h) do { _Pragma("unroll") for (int n = 0; n < 2; ++n) _Pragma("unroll") for (int k = 0; k < 2; ++k) dst[n][k] = *(const LAS bf16x8*)(lds + PG8_SB(b, h) + boff + n * 2048 + k * 1024); } while (0)
; #define PG8_MMA(ai, bj, At, Bt) do { __builtin_amdgcn_s_setprio(1); _Pragma("unroll") for (int m = 0; m < 4; ++m) _Pragma("unroll") for (int n = 0; n < 2; ++n) _Pragma("unroll") for (int k = 0; k < 2; ++k) \
;         acc[ai][bj][m][n] = __builtin_amdgcn_mfma_f32_16x16x32_bf16(Bt[n][k], At[m][k], acc[ai][bj][m][n], 0, 0, 0); __builtin_amdgcn_s_setprio(0); } while (0)
; #define PG8_WAIT_V(n) asm volatile("s_waitcnt vmcnt(" #n ")" ::: "memory")
; #define PG8_WAIT_L(n) asm volatile("s_waitcnt lgkmcnt(" #n ")" ::: "memory")
; #define PG8_BAR __builtin_amdgcn_s_barrier()
; template <class Epi>
; __device__ __forceinline__ void gemm_phase(LAS unsigned char* lds, const Gemm g, const StaticOrder& S, const Epi& E) {
;     ...
;         for (int t = 0; t < nt; t += 2) {
;             const bool last = (t == nt - 2);
;             const char* a1 = cA + (size_t)(t + 1) * kstep;
;             const char* a2 = last ? nA : cA + (size_t)(t + 2) * kstep; const char* b2 = last ? nB : cB + (size_t)(t + 2) * kstep;
;             const char* a3 = a2 + kstep; const char* b3 = b2 + kstep;
;             if constexpr (Epi::MIDK > 0) { if (t == Epi::MIDK) E.mid(acc, cur, wr, wc, fr, fq); }
;             PG8_LDB(B0, 0, 0); PG8_LDB(B1, 0, 1); PG8_SCHED; PG8_LDA(At, 0, 0); PG8_STAGE(PG8_SA(1, 1), a1 + hstep, voffA);
;             PG8_WAIT_V(8); PG8_WAIT_L(0); PG8_BAR; PG8_MMA(0, 0, At, B0); PG8_MMA(0, 1, At, B1); PG8_BAR; PG8_SCHED;
;             PG8_LDA(At, 0, 1); PG8_STAGE(PG8_SB(0, 0), b2, voffB); PG8_STAGE(PG8_SB(0, 1), b2 + hstep, voffB); PG8_STAGE(PG8_SA(0, 0), a2, voffA);
;             PG8_WAIT_V(8); PG8_WAIT_L(0); PG8_BAR; PG8_MMA(1, 0, At, B0); PG8_MMA(1, 1, At, B1); PG8_BAR; PG8_SCHED;
.LBB0_322:
	ds_read_b128 v[130:133], v191
	ds_read_b128 v[134:137], v191 offset:1024
	ds_read_b128 v[138:141], v191 offset:2048
	ds_read_b128 v[142:145], v191 offset:3072
	ds_read_b128 v[166:169], v193
	ds_read_b128 v[172:175], v193 offset:1024
	ds_read_b128 v[176:179], v193 offset:2048
	ds_read_b128 v[180:183], v193 offset:3072
	s_add_u32 s76, s88, 0xfffc0080
	s_addc_u32 s77, s89, -1
	s_cmp_eq_u32 vcc_hi, 12
	s_cselect_b32 s93, s1, s77
	s_cselect_b32 s92, s7, s76
	s_cselect_b32 s91, s9, vcc_lo
	s_cselect_b32 s90, s46, s81
	s_add_i32 m0, s96, 0xc000
	ds_read_b128 v[200:203], v194
	ds_read_b128 v[204:207], v194 offset:1024
	ds_read_b128 v[208:211], v194 offset:2048
	ds_read_b128 v[212:215], v194 offset:3072
	ds_read_b128 v[216:219], v194 offset:4096
	ds_read_b128 v[220:223], v194 offset:5120
	ds_read_b128 v[224:227], v194 offset:6144
	ds_read_b128 v[228:231], v194 offset:7168
	global_load_lds_dwordx4 v158, s[88:89]
	s_add_i32 m0, s96, 0xe000
	s_nop 0
	global_load_lds_dwordx4 v160, s[88:89]
	s_waitcnt vmcnt(8)
	s_waitcnt lgkmcnt(0)
	s_setprio 1
	v_mfma_f32_16x16x32_bf16 v[126:129], v[130:133], v[200:203], v[126:129]
	v_mfma_f32_16x16x32_bf16 v[122:125], v[138:141], v[200:203], v[122:125]
	v_mfma_f32_16x16x32_bf16 v[110:113], v[130:133], v[208:211], v[110:113]
	v_mfma_f32_16x16x32_bf16 v[106:109], v[138:141], v[208:211], v[106:109]
	v_mfma_f32_16x16x32_bf16 v[94:97], v[130:133], v[216:219], v[94:97]
	v_mfma_f32_16x16x32_bf16 v[90:93], v[138:141], v[216:219], v[90:93]
	v_mfma_f32_16x16x32_bf16 v[78:81], v[130:133], v[224:227], v[78:81]
	v_mfma_f32_16x16x32_bf16 v[74:77], v[138:141], v[224:227], v[74:77]
	s_barrier
	v_mfma_f32_16x16x32_bf16 v[126:129], v[134:137], v[204:207], v[126:129]
	v_mfma_f32_16x16x32_bf16 v[122:125], v[142:145], v[204:207], v[122:125]
	v_mfma_f32_16x16x32_bf16 v[110:113], v[134:137], v[212:215], v[110:113]
	v_mfma_f32_16x16x32_bf16 v[106:109], v[142:145], v[212:215], v[106:109]
	v_mfma_f32_16x16x32_bf16 v[94:97], v[134:137], v[220:223], v[94:97]
	v_mfma_f32_16x16x32_bf16 v[90:93], v[142:145], v[220:223], v[90:93]
	v_mfma_f32_16x16x32_bf16 v[78:81], v[134:137], v[228:231], v[78:81]
	v_mfma_f32_16x16x32_bf16 v[74:77], v[142:145], v[228:231], v[74:77]
	v_mfma_f32_16x16x32_bf16 v[118:121], v[166:169], v[200:203], v[118:121]
	v_mfma_f32_16x16x32_bf16 v[114:117], v[176:179], v[200:203], v[114:117]
	v_mfma_f32_16x16x32_bf16 v[102:105], v[166:169], v[208:211], v[102:105]
	v_mfma_f32_16x16x32_bf16 v[98:101], v[176:179], v[208:211], v[98:101]
	v_mfma_f32_16x16x32_bf16 v[86:89], v[166:169], v[216:219], v[86:89]
	v_mfma_f32_16x16x32_bf16 v[82:85], v[176:179], v[216:219], v[82:85]
	v_mfma_f32_16x16x32_bf16 v[70:73], v[166:169], v[224:227], v[70:73]
	v_mfma_f32_16x16x32_bf16 v[66:69], v[176:179], v[224:227], v[66:69]
	v_mfma_f32_16x16x32_bf16 v[118:121], v[172:175], v[204:207], v[118:121]
	v_mfma_f32_16x16x32_bf16 v[114:117], v[180:183], v[204:207], v[114:117]
	v_mfma_f32_16x16x32_bf16 v[102:105], v[172:175], v[212:215], v[102:105]
	v_mfma_f32_16x16x32_bf16 v[98:101], v[180:183], v[212:215], v[98:101]
	v_mfma_f32_16x16x32_bf16 v[86:89], v[172:175], v[220:223], v[86:89]
	v_mfma_f32_16x16x32_bf16 v[82:85], v[180:183], v[220:223], v[82:85]
	v_mfma_f32_16x16x32_bf16 v[70:73], v[172:175], v[228:231], v[70:73]
	v_mfma_f32_16x16x32_bf16 v[66:69], v[180:183], v[228:231], v[66:69]
	s_barrier
	s_setprio 0
	s_add_u32 s98, s90, s50
	s_addc_u32 s99, s91, s51
	s_add_u32 s100, s92, s50
	s_addc_u32 s101, s93, s51
	s_add_i32 s76, s42, s44
	s_mov_b32 m0, s76
	ds_read_b128 v[200:203], v194 offset:16384
	ds_read_b128 v[204:207], v194 offset:17408
	ds_read_b128 v[208:211], v194 offset:18432
	ds_read_b128 v[212:215], v194 offset:19456
	ds_read_b128 v[216:219], v194 offset:20480
	ds_read_b128 v[220:223], v194 offset:21504
	ds_read_b128 v[224:227], v194 offset:22528
	ds_read_b128 v[228:231], v194 offset:23552
	global_load_lds_dwordx4 v148, s[90:91]
	s_add_i32 m0, s76, 0x2000
	s_add_u32 s76, s90, 0x40000
	s_addc_u32 s77, s91, 0
	s_add_i32 s60, s43, s44
	global_load_lds_dwordx4 v152, s[90:91]
	s_mov_b32 m0, s60
	s_nop 0
	global_load_lds_dwordx4 v148, s[76:77]
	s_add_i32 m0, s60, 0x2000
	s_nop 0
	global_load_lds_dwordx4 v152, s[76:77]
	s_mov_b32 m0, s96
	s_nop 0
	global_load_lds_dwordx4 v146, s[92:93]
	s_mov_b32 m0, s97
	s_nop 0
	global_load_lds_dwordx4 v150, s[92:93]
	s_waitcnt vmcnt(8)
	s_waitcnt lgkmcnt(0)
	s_setprio 1
	v_mfma_f32_16x16x32_bf16 v[62:65], v[130:133], v[200:203], v[62:65]
	v_mfma_f32_16x16x32_bf16 v[58:61], v[138:141], v[200:203], v[58:61]
	v_mfma_f32_16x16x32_bf16 v[46:49], v[130:133], v[208:211], v[46:49]
	v_mfma_f32_16x16x32_bf16 v[42:45], v[138:141], v[208:211], v[42:45]
	v_mfma_f32_16x16x32_bf16 v[30:33], v[130:133], v[216:219], v[30:33]
	v_mfma_f32_16x16x32_bf16 v[26:29], v[138:141], v[216:219], v[26:29]
	v_mfma_f32_16x16x32_bf16 v[14:17], v[130:133], v[224:227], v[14:17]
	v_mfma_f32_16x16x32_bf16 v[10:13], v[138:141], v[224:227], v[10:13]
	s_barrier
; #define PG8_STAGE(bufoff, gbase, voff) do { _Pragma("unroll") for (int _i = 0; _i < 2; ++_i) \
;         __builtin_amdgcn_global_load_lds((const unsigned*)((const char*)(gbase) + (voff)[_i]), (LAS unsigned*)(lds + (bufoff) + ldsw + _i * 8192), 16, 0, 0); } while (0)
; #define PG8_LDA(dst, b, h) do { _Pragma("unroll") for (int m = 0; m < 4; ++m) _Pragma("unroll") for (int k = 0; k < 2; ++k) dst[m][k] = *(const LAS bf16x8*)(lds + PG8_SA(b, h) + aoff + m * 2048 + k * 1024); } while (0)
; #define PG8_LDB(dst, b, h) do { _Pragma("unroll") for (int n = 0; n < 2; ++n) _Pragma("unroll") for (int k = 0; k < 2; ++k) dst[n][k] = *(const LAS bf16x8*)(lds + PG8_SB(b, h) + boff + n * 2048 + k * 1024); } while (0)
; #define PG8_MMA(ai, bj, At, Bt) do { __builtin_amdgcn_s_setprio(1); _Pragma("unroll") for (int m = 0; m < 4; ++m) _Pragma("unroll") for (int n = 0; n < 2; ++n) _Pragma("unroll") for (int k = 0; k < 2; ++k) \
;         acc[ai][bj][m][n] = __builtin_amdgcn_mfma_f32_16x16x32_bf16(Bt[n][k], At[m][k], acc[ai][bj][m][n], 0, 0, 0); __builtin_amdgcn_s_setprio(0); } while (0)
; #define PG8_WAIT_V(n) asm volatile("s_waitcnt vmcnt(" #n ")" ::: "memory")
; #define PG8_WAIT_L(n) asm volatile("s_waitcnt lgkmcnt(" #n ")" ::: "memory")
; #define PG8_BAR __builtin_amdgcn_s_barrier()
; #define PG8_SCHED __builtin_amdgcn_sched_barrier(0)
; template <class Epi>
; __device__ __forceinline__ void gemm_phase(LAS unsigned char* lds, const Gemm g, const StaticOrder& S, const Epi& E) {
;     ...
;             PG8_WAIT_V(8); PG8_WAIT_L(0); PG8_BAR; PG8_MMA(1, 0, At, B0); PG8_MMA(1, 1, At, B1); PG8_BAR; PG8_SCHED;
;             PG8_LDB(B0, 1, 0); PG8_LDB(B1, 1, 1); PG8_SCHED; PG8_LDA(At, 1, 0); PG8_STAGE(PG8_SA(0, 1), a2 + hstep, voffA);
;             PG8_WAIT_V(8); PG8_WAIT_L(0); PG8_BAR; PG8_MMA(0, 0, At, B0); PG8_MMA(0, 1, At, B1); PG8_BAR; PG8_SCHED;
	v_mfma_f32_16x16x32_bf16 v[62:65], v[134:137], v[204:207], v[62:65]
	v_mfma_f32_16x16x32_bf16 v[58:61], v[142:145], v[204:207], v[58:61]
	v_mfma_f32_16x16x32_bf16 v[46:49], v[134:137], v[212:215], v[46:49]
	v_mfma_f32_16x16x32_bf16 v[42:45], v[142:145], v[212:215], v[42:45]
	v_mfma_f32_16x16x32_bf16 v[30:33], v[134:137], v[220:223], v[30:33]
	v_mfma_f32_16x16x32_bf16 v[26:29], v[142:145], v[220:223], v[26:29]
	v_mfma_f32_16x16x32_bf16 v[14:17], v[134:137], v[228:231], v[14:17]
	v_mfma_f32_16x16x32_bf16 v[10:13], v[142:145], v[228:231], v[10:13]
	v_mfma_f32_16x16x32_bf16 v[54:57], v[166:169], v[200:203], v[54:57]
	v_mfma_f32_16x16x32_bf16 v[50:53], v[176:179], v[200:203], v[50:53]
	v_mfma_f32_16x16x32_bf16 v[38:41], v[166:169], v[208:211], v[38:41]
	v_mfma_f32_16x16x32_bf16 v[34:37], v[176:179], v[208:211], v[34:37]
	v_mfma_f32_16x16x32_bf16 v[22:25], v[166:169], v[216:219], v[22:25]
	v_mfma_f32_16x16x32_bf16 v[18:21], v[176:179], v[216:219], v[18:21]
	v_mfma_f32_16x16x32_bf16 v[6:9], v[166:169], v[224:227], v[6:9]
	v_mfma_f32_16x16x32_bf16 v[2:5], v[176:179], v[224:227], v[2:5]
	v_mfma_f32_16x16x32_bf16 v[54:57], v[172:175], v[204:207], v[54:57]
	v_mfma_f32_16x16x32_bf16 v[50:53], v[180:183], v[204:207], v[50:53]
	v_mfma_f32_16x16x32_bf16 v[38:41], v[172:175], v[212:215], v[38:41]
	v_mfma_f32_16x16x32_bf16 v[34:37], v[180:183], v[212:215], v[34:37]
	v_mfma_f32_16x16x32_bf16 v[22:25], v[172:175], v[220:223], v[22:25]
	v_mfma_f32_16x16x32_bf16 v[18:21], v[180:183], v[220:223], v[18:21]
	v_mfma_f32_16x16x32_bf16 v[6:9], v[172:175], v[228:231], v[6:9]
	v_mfma_f32_16x16x32_bf16 v[2:5], v[180:183], v[228:231], v[2:5]
	s_barrier
	s_setprio 0
	s_add_i32 s60, 0, 0x18000
	s_add_i32 s61, 0, 0x1c000
	v_add_u32_e32 v142, s60, v187
	v_add_u32_e32 v180, s61, v187
	ds_read_b128 v[130:133], v142
	ds_read_b128 v[134:137], v142 offset:1024
	ds_read_b128 v[138:141], v142 offset:2048
	ds_read_b128 v[142:145], v142 offset:3072
	ds_read_b128 v[166:169], v180
	ds_read_b128 v[172:175], v180 offset:1024
	ds_read_b128 v[176:179], v180 offset:2048
	ds_read_b128 v[180:183], v180 offset:3072
	s_add_u32 s76, s92, 0x40000
	s_addc_u32 s77, s93, 0
	s_mov_b32 m0, s11
	ds_read_b128 v[200:203], v194 offset:32768
	ds_read_b128 v[204:207], v194 offset:33792
	ds_read_b128 v[208:211], v194 offset:34816
	ds_read_b128 v[212:215], v194 offset:35840
	ds_read_b128 v[216:219], v194 offset:36864
	ds_read_b128 v[220:223], v194 offset:37888
	ds_read_b128 v[224:227], v194 offset:38912
	ds_read_b128 v[228:231], v194 offset:39936
	global_load_lds_dwordx4 v146, s[76:77]
	s_mov_b32 m0, s94
	s_nop 0
	global_load_lds_dwordx4 v150, s[76:77]
	s_waitcnt vmcnt(8)
	s_waitcnt lgkmcnt(0)
	s_setprio 1
	v_mfma_f32_16x16x32_bf16 v[126:129], v[130:133], v[200:203], v[126:129]
	v_mfma_f32_16x16x32_bf16 v[122:125], v[138:141], v[200:203], v[122:125]
	v_mfma_f32_16x16x32_bf16 v[110:113], v[130:133], v[208:211], v[110:113]
	v_mfma_f32_16x16x32_bf16 v[106:109], v[138:141], v[208:211], v[106:109]
	v_mfma_f32_16x16x32_bf16 v[94:97], v[130:133], v[216:219], v[94:97]
	v_mfma_f32_16x16x32_bf16 v[90:93], v[138:141], v[216:219], v[90:93]
	v_mfma_f32_16x16x32_bf16 v[78:81], v[130:133], v[224:227], v[78:81]
	v_mfma_f32_16x16x32_bf16 v[74:77], v[138:141], v[224:227], v[74:77]
	s_barrier
	v_mfma_f32_16x16x32_bf16 v[126:129], v[134:137], v[204:207], v[126:129]
	v_mfma_f32_16x16x32_bf16 v[122:125], v[142:145], v[204:207], v[122:125]
	v_mfma_f32_16x16x32_bf16 v[110:113], v[134:137], v[212:215], v[110:113]
	v_mfma_f32_16x16x32_bf16 v[106:109], v[142:145], v[212:215], v[106:109]
	v_mfma_f32_16x16x32_bf16 v[94:97], v[134:137], v[220:223], v[94:97]
	v_mfma_f32_16x16x32_bf16 v[90:93], v[142:145], v[220:223], v[90:93]
	v_mfma_f32_16x16x32_bf16 v[78:81], v[134:137], v[228:231], v[78:81]
	v_mfma_f32_16x16x32_bf16 v[74:77], v[142:145], v[228:231], v[74:77]
	v_mfma_f32_16x16x32_bf16 v[118:121], v[166:169], v[200:203], v[118:121]
	v_mfma_f32_16x16x32_bf16 v[114:117], v[176:179], v[200:203], v[114:117]
	v_mfma_f32_16x16x32_bf16 v[102:105], v[166:169], v[208:211], v[102:105]
	v_mfma_f32_16x16x32_bf16 v[98:101], v[176:179], v[208:211], v[98:101]
	v_mfma_f32_16x16x32_bf16 v[86:89], v[166:169], v[216:219], v[86:89]
	v_mfma_f32_16x16x32_bf16 v[82:85], v[176:179], v[216:219], v[82:85]
	v_mfma_f32_16x16x32_bf16 v[70:73], v[166:169], v[224:227], v[70:73]
	v_mfma_f32_16x16x32_bf16 v[66:69], v[176:179], v[224:227], v[66:69]
	v_mfma_f32_16x16x32_bf16 v[118:121], v[172:175], v[204:207], v[118:121]
	v_mfma_f32_16x16x32_bf16 v[114:117], v[180:183], v[204:207], v[114:117]
	v_mfma_f32_16x16x32_bf16 v[102:105], v[172:175], v[212:215], v[102:105]
	v_mfma_f32_16x16x32_bf16 v[98:101], v[180:183], v[212:215], v[98:101]
	v_mfma_f32_16x16x32_bf16 v[86:89], v[172:175], v[220:223], v[86:89]
	v_mfma_f32_16x16x32_bf16 v[82:85], v[180:183], v[220:223], v[82:85]
	v_mfma_f32_16x16x32_bf16 v[70:73], v[172:175], v[228:231], v[70:73]
	v_mfma_f32_16x16x32_bf16 v[66:69], v[180:183], v[228:231], v[66:69]
	s_barrier
; #define PG8_STAGE(bufoff, gbase, voff) do { _Pragma("unroll") for (int _i = 0; _i < 2; ++_i) \
;         __builtin_amdgcn_global_load_lds((const unsigned*)((const char*)(gbase) + (voff)[_i]), (LAS unsigned*)(lds + (bufoff) + ldsw + _i * 8192), 16, 0, 0); } while (0)
; #define PG8_LDA(dst, b, h) do { _Pragma("unroll") for (int m = 0; m < 4; ++m) _Pragma("unroll") for (int k = 0; k < 2; ++k) dst[m][k] = *(const LAS bf16x8*)(lds + PG8_SA(b, h) + aoff + m * 2048 + k * 1024); } while (0)
; #define PG8_MMA(ai, bj, At, Bt) do { __builtin_amdgcn_s_setprio(1); _Pragma("unroll") for (int m = 0; m < 4; ++m) _Pragma("unroll") for (int n = 0; n < 2; ++n) _Pragma("unroll") for (int k = 0; k < 2; ++k) \
;         acc[ai][bj][m][n] = __builtin_amdgcn_mfma_f32_16x16x32_bf16(Bt[n][k], At[m][k], acc[ai][bj][m][n], 0, 0, 0); __builtin_amdgcn_s_setprio(0); } while (0)
; #define PG8_WAIT_V(n) asm volatile("s_waitcnt vmcnt(" #n ")" ::: "memory")
; #define PG8_WAIT_L(n) asm volatile("s_waitcnt lgkmcnt(" #n ")" ::: "memory")
; #define PG8_BAR __builtin_amdgcn_s_barrier()
; #define PG8_SCHED __builtin_amdgcn_sched_barrier(0)
; template <class Epi>
; __device__ __forceinline__ void gemm_phase(LAS unsigned char* lds, const Gemm g, const StaticOrder& S, const Epi& E) {
;     ...
;             PG8_LDA(At, 1, 1); PG8_STAGE(PG8_SB(1, 0), b3, voffB); PG8_STAGE(PG8_SB(1, 1), b3 + hstep, voffB); PG8_STAGE(PG8_SA(1, 0), a3, voffA);
;             PG8_WAIT_V(8); PG8_WAIT_L(0); PG8_BAR; PG8_MMA(1, 0, At, B0); PG8_MMA(1, 1, At, B1); PG8_BAR; PG8_SCHED;
;         }
;         if (wr == 0) PG8_BAR;
	s_setprio 0
	s_add_i32 s60, s60, s44
	s_mov_b32 m0, s60
	ds_read_b128 v[200:203], v194 offset:49152
	ds_read_b128 v[204:207], v194 offset:50176
	ds_read_b128 v[208:211], v194 offset:51200
	ds_read_b128 v[212:215], v194 offset:52224
	ds_read_b128 v[216:219], v194 offset:53248
	ds_read_b128 v[220:223], v194 offset:54272
	ds_read_b128 v[224:227], v194 offset:55296
	ds_read_b128 v[228:231], v194 offset:56320
	global_load_lds_dwordx4 v148, s[98:99]
	s_add_i32 m0, s60, 0x2000
	s_add_u32 s76, s90, 0x40080
	s_addc_u32 s77, s91, 0
	s_add_i32 s60, s61, s44
	global_load_lds_dwordx4 v152, s[98:99]
	s_mov_b32 m0, s60
	s_nop 0
	global_load_lds_dwordx4 v148, s[76:77]
	s_add_i32 m0, s60, 0x2000
	s_nop 0
	global_load_lds_dwordx4 v152, s[76:77]
	s_mov_b32 m0, s79
	s_nop 0
	global_load_lds_dwordx4 v146, s[100:101]
	s_mov_b32 m0, s33
	s_nop 0
	global_load_lds_dwordx4 v150, s[100:101]
	s_waitcnt vmcnt(8)
	s_waitcnt lgkmcnt(0)
	s_setprio 1
	v_mfma_f32_16x16x32_bf16 v[62:65], v[130:133], v[200:203], v[62:65]
	v_mfma_f32_16x16x32_bf16 v[58:61], v[138:141], v[200:203], v[58:61]
	v_mfma_f32_16x16x32_bf16 v[46:49], v[130:133], v[208:211], v[46:49]
	v_mfma_f32_16x16x32_bf16 v[42:45], v[138:141], v[208:211], v[42:45]
	v_mfma_f32_16x16x32_bf16 v[30:33], v[130:133], v[216:219], v[30:33]
	v_mfma_f32_16x16x32_bf16 v[26:29], v[138:141], v[216:219], v[26:29]
	v_mfma_f32_16x16x32_bf16 v[14:17], v[130:133], v[224:227], v[14:17]
	v_mfma_f32_16x16x32_bf16 v[10:13], v[138:141], v[224:227], v[10:13]
	s_barrier
	v_mfma_f32_16x16x32_bf16 v[62:65], v[134:137], v[204:207], v[62:65]
	v_mfma_f32_16x16x32_bf16 v[58:61], v[142:145], v[204:207], v[58:61]
	v_mfma_f32_16x16x32_bf16 v[46:49], v[134:137], v[212:215], v[46:49]
	v_mfma_f32_16x16x32_bf16 v[42:45], v[142:145], v[212:215], v[42:45]
	v_mfma_f32_16x16x32_bf16 v[30:33], v[134:137], v[220:223], v[30:33]
	v_mfma_f32_16x16x32_bf16 v[26:29], v[142:145], v[220:223], v[26:29]
	v_mfma_f32_16x16x32_bf16 v[14:17], v[134:137], v[228:231], v[14:17]
	v_mfma_f32_16x16x32_bf16 v[10:13], v[142:145], v[228:231], v[10:13]
	v_mfma_f32_16x16x32_bf16 v[54:57], v[166:169], v[200:203], v[54:57]
	v_mfma_f32_16x16x32_bf16 v[50:53], v[176:179], v[200:203], v[50:53]
	v_mfma_f32_16x16x32_bf16 v[38:41], v[166:169], v[208:211], v[38:41]
	v_mfma_f32_16x16x32_bf16 v[34:37], v[176:179], v[208:211], v[34:37]
	v_mfma_f32_16x16x32_bf16 v[22:25], v[166:169], v[216:219], v[22:25]
	v_mfma_f32_16x16x32_bf16 v[18:21], v[176:179], v[216:219], v[18:21]
	v_mfma_f32_16x16x32_bf16 v[6:9], v[166:169], v[224:227], v[6:9]
	v_mfma_f32_16x16x32_bf16 v[2:5], v[176:179], v[224:227], v[2:5]
	v_mfma_f32_16x16x32_bf16 v[54:57], v[172:175], v[204:207], v[54:57]
	v_mfma_f32_16x16x32_bf16 v[50:53], v[180:183], v[204:207], v[50:53]
	v_mfma_f32_16x16x32_bf16 v[38:41], v[172:175], v[212:215], v[38:41]
	v_mfma_f32_16x16x32_bf16 v[34:37], v[180:183], v[212:215], v[34:37]
	v_mfma_f32_16x16x32_bf16 v[22:25], v[172:175], v[220:223], v[22:25]
	v_mfma_f32_16x16x32_bf16 v[18:21], v[180:183], v[220:223], v[18:21]
	v_mfma_f32_16x16x32_bf16 v[6:9], v[172:175], v[228:231], v[6:9]
	v_mfma_f32_16x16x32_bf16 v[2:5], v[180:183], v[228:231], v[2:5]
	s_barrier
	s_setprio 0
	s_add_i32 vcc_hi, vcc_hi, 2
	s_add_u32 s88, s88, 0x100
	s_addc_u32 s89, s89, 0
	s_add_u32 s81, s81, 0x100
	s_addc_u32 vcc_lo, vcc_lo, 0
	s_cmp_gt_u32 vcc_hi, 13
	s_cbranch_scc0 .LBB0_322
	s_and_b64 vcc, exec, s[58:59]
	s_cbranch_vccz .LBB0_325
	s_barrier

; #define PG8_STAGE(bufoff, gbase, voff) do { _Pragma("unroll") for (int _i = 0; _i < 2; ++_i) \
;         __builtin_amdgcn_global_load_lds((const unsigned*)((const char*)(gbase) + (voff)[_i]), (LAS unsigned*)(lds + (bufoff) + ldsw + _i * 8192), 16, 0, 0); } while (0)
; #define PG8_LDA(dst, b, h) do { _Pragma("unroll") for (int m = 0; m < 4; ++m) _Pragma("unroll") for (int k = 0; k < 2; ++k) dst[m][k] = *(const LAS bf16x8*)(lds + PG8_SA(b, h) + aoff + m * 2048 + k * 1024); } while (0)
; #define PG8_LDB(dst, b, h) do { _Pragma("unroll") for (int n = 0; n < 2; ++n) _Pragma("unroll") for (int k = 0; k < 2; ++k) dst[n][k] = *(const LAS bf16x8*)(lds + PG8_SB(b, h) + boff + n * 2048 + k * 1024); } while (0)
; #define PG8_MMA(ai, bj, At, Bt) do { __builtin_amdgcn_s_setprio(1); _Pragma("unroll") for (int m = 0; m < 4; ++m) _Pragma("unroll") for (int n = 0; n < 2; ++n) _Pragma("unroll") for (int k = 0; k < 2; ++k) \
;         acc[ai][bj][m][n] = __builtin_amdgcn_mfma_f32_16x16x32_bf16(Bt[n][k], At[m][k], acc[ai][bj][m][n], 0, 0, 0); __builtin_amdgcn_s_setprio(0); } while (0)
; #define PG8_WAIT_V(n) asm volatile("s_waitcnt vmcnt(" #n ")" ::: "memory")
; #define PG8_WAIT_L(n) asm volatile("s_waitcnt lgkmcnt(" #n ")" ::: "memory")
; #define PG8_BAR __builtin_amdgcn_s_barrier()
; template <class Epi>
; __device__ __forceinline__ void gemm_phase(LAS unsigned char* lds, const Gemm g, const StaticOrder& S, const Epi& E) {
;     ...
;         for (int t = 0; t < nt; t += 2) {
;             const bool last = (t == nt - 2);
;             const char* a1 = cA + (size_t)(t + 1) * kstep;
;             const char* a2 = last ? nA : cA + (size_t)(t + 2) * kstep; const char* b2 = last ? nB : cB + (size_t)(t + 2) * kstep;
;             const char* a3 = a2 + kstep; const char* b3 = b2 + kstep;
;             if constexpr (Epi::MIDK > 0) { if (t == Epi::MIDK) E.mid(acc, cur, wr, wc, fr, fq); }
;             PG8_LDB(B0, 0, 0); PG8_LDB(B1, 0, 1); PG8_SCHED; PG8_LDA(At, 0, 0); PG8_STAGE(PG8_SA(1, 1), a1 + hstep, voffA);
;             PG8_WAIT_V(8); PG8_WAIT_L(0); PG8_BAR; PG8_MMA(0, 0, At, B0); PG8_MMA(0, 1, At, B1); PG8_BAR; PG8_SCHED;
;             PG8_LDA(At, 0, 1); PG8_STAGE(PG8_SB(0, 0), b2, voffB); PG8_STAGE(PG8_SB(0, 1), b2 + hstep, voffB); PG8_STAGE(PG8_SA(0, 0), a2, voffA);
;             PG8_WAIT_V(8); PG8_WAIT_L(0); PG8_BAR; PG8_MMA(1, 0, At, B0); PG8_MMA(1, 1, At, B1); PG8_BAR; PG8_SCHED;
.LBB0_619:
	ds_read_b128 v[154:157], v174
	ds_read_b128 v[158:161], v174 offset:1024
	ds_read_b128 v[162:165], v174 offset:2048
	ds_read_b128 v[166:169], v174 offset:3072
	ds_read_b128 v[182:185], v175
	ds_read_b128 v[186:189], v175 offset:1024
	ds_read_b128 v[190:193], v175 offset:2048
	ds_read_b128 v[194:197], v175 offset:3072
	s_add_u32 s46, s44, 0xfffc0080
	s_addc_u32 s47, s45, -1
	s_cmp_eq_u32 s69, 12
	s_cselect_b32 s49, s64, s47
	s_cselect_b32 s48, s65, s46
	s_cselect_b32 s47, s25, s68
	s_cselect_b32 s46, s66, s67
	s_add_i32 m0, s43, 0xc000
	ds_read_b128 v[198:201], v176
	ds_read_b128 v[202:205], v176 offset:1024
	ds_read_b128 v[206:209], v176 offset:2048
	ds_read_b128 v[210:213], v176 offset:3072
	ds_read_b128 v[214:217], v176 offset:4096
	ds_read_b128 v[218:221], v176 offset:5120
	ds_read_b128 v[222:225], v176 offset:6144
	ds_read_b128 v[226:229], v176 offset:7168
	global_load_lds_dwordx4 v144, s[44:45]
	s_add_i32 m0, s43, 0xe000
	s_nop 0
	global_load_lds_dwordx4 v146, s[44:45]
	s_waitcnt vmcnt(8)
	s_waitcnt lgkmcnt(0)
	s_setprio 1
	v_mfma_f32_16x16x32_bf16 v[126:129], v[154:157], v[198:201], v[126:129]
	v_mfma_f32_16x16x32_bf16 v[122:125], v[162:165], v[198:201], v[122:125]
	v_mfma_f32_16x16x32_bf16 v[110:113], v[154:157], v[206:209], v[110:113]
	v_mfma_f32_16x16x32_bf16 v[106:109], v[162:165], v[206:209], v[106:109]
	v_mfma_f32_16x16x32_bf16 v[94:97], v[154:157], v[214:217], v[94:97]
	v_mfma_f32_16x16x32_bf16 v[90:93], v[162:165], v[214:217], v[90:93]
	v_mfma_f32_16x16x32_bf16 v[78:81], v[154:157], v[222:225], v[78:81]
	v_mfma_f32_16x16x32_bf16 v[74:77], v[162:165], v[222:225], v[74:77]
	s_barrier
	v_mfma_f32_16x16x32_bf16 v[126:129], v[158:161], v[202:205], v[126:129]
	v_mfma_f32_16x16x32_bf16 v[122:125], v[166:169], v[202:205], v[122:125]
	v_mfma_f32_16x16x32_bf16 v[110:113], v[158:161], v[210:213], v[110:113]
	v_mfma_f32_16x16x32_bf16 v[106:109], v[166:169], v[210:213], v[106:109]
	v_mfma_f32_16x16x32_bf16 v[94:97], v[158:161], v[218:221], v[94:97]
	v_mfma_f32_16x16x32_bf16 v[90:93], v[166:169], v[218:221], v[90:93]
	v_mfma_f32_16x16x32_bf16 v[78:81], v[158:161], v[226:229], v[78:81]
	v_mfma_f32_16x16x32_bf16 v[74:77], v[166:169], v[226:229], v[74:77]
	v_mfma_f32_16x16x32_bf16 v[118:121], v[182:185], v[198:201], v[118:121]
	v_mfma_f32_16x16x32_bf16 v[114:117], v[190:193], v[198:201], v[114:117]
	v_mfma_f32_16x16x32_bf16 v[102:105], v[182:185], v[206:209], v[102:105]
	v_mfma_f32_16x16x32_bf16 v[98:101], v[190:193], v[206:209], v[98:101]
	v_mfma_f32_16x16x32_bf16 v[86:89], v[182:185], v[214:217], v[86:89]
	v_mfma_f32_16x16x32_bf16 v[82:85], v[190:193], v[214:217], v[82:85]
	v_mfma_f32_16x16x32_bf16 v[70:73], v[182:185], v[222:225], v[70:73]
	v_mfma_f32_16x16x32_bf16 v[66:69], v[190:193], v[222:225], v[66:69]
	v_mfma_f32_16x16x32_bf16 v[118:121], v[186:189], v[202:205], v[118:121]
	v_mfma_f32_16x16x32_bf16 v[114:117], v[194:197], v[202:205], v[114:117]
	v_mfma_f32_16x16x32_bf16 v[102:105], v[186:189], v[210:213], v[102:105]
	v_mfma_f32_16x16x32_bf16 v[98:101], v[194:197], v[210:213], v[98:101]
	v_mfma_f32_16x16x32_bf16 v[86:89], v[186:189], v[218:221], v[86:89]
	v_mfma_f32_16x16x32_bf16 v[82:85], v[194:197], v[218:221], v[82:85]
	v_mfma_f32_16x16x32_bf16 v[70:73], v[186:189], v[226:229], v[70:73]
	v_mfma_f32_16x16x32_bf16 v[66:69], v[194:197], v[226:229], v[66:69]
	s_barrier
	s_setprio 0
	s_add_u32 s98, s46, s8
	s_addc_u32 s99, s47, s9
	s_add_u32 s100, s48, s8
	s_addc_u32 s101, s49, s9
	s_add_i32 s76, s60, s6
	s_mov_b32 m0, s76
	ds_read_b128 v[198:201], v176 offset:16384
	ds_read_b128 v[202:205], v176 offset:17408
	ds_read_b128 v[206:209], v176 offset:18432
	ds_read_b128 v[210:213], v176 offset:19456
	ds_read_b128 v[214:217], v176 offset:20480
	ds_read_b128 v[218:221], v176 offset:21504
	ds_read_b128 v[222:225], v176 offset:22528
	ds_read_b128 v[226:229], v176 offset:23552
	global_load_lds_dwordx4 v132, s[46:47]
	s_add_i32 m0, s76, 0x2000
	s_add_u32 s76, s46, 0x40000
	s_addc_u32 s77, s47, 0
	s_add_i32 s78, s61, s6
	global_load_lds_dwordx4 v136, s[46:47]
	s_mov_b32 m0, s78
	s_nop 0
	global_load_lds_dwordx4 v132, s[76:77]
	s_add_i32 m0, s78, 0x2000
	s_nop 0
	global_load_lds_dwordx4 v136, s[76:77]
	s_mov_b32 m0, s43
	s_nop 0
	global_load_lds_dwordx4 v130, s[48:49]
	s_mov_b32 m0, s51
	s_nop 0
	global_load_lds_dwordx4 v134, s[48:49]
	s_waitcnt vmcnt(8)
	s_waitcnt lgkmcnt(0)
	s_setprio 1
	v_mfma_f32_16x16x32_bf16 v[62:65], v[154:157], v[198:201], v[62:65]
	v_mfma_f32_16x16x32_bf16 v[58:61], v[162:165], v[198:201], v[58:61]
	v_mfma_f32_16x16x32_bf16 v[46:49], v[154:157], v[206:209], v[46:49]
	v_mfma_f32_16x16x32_bf16 v[42:45], v[162:165], v[206:209], v[42:45]
	v_mfma_f32_16x16x32_bf16 v[30:33], v[154:157], v[214:217], v[30:33]
	v_mfma_f32_16x16x32_bf16 v[26:29], v[162:165], v[214:217], v[26:29]
	v_mfma_f32_16x16x32_bf16 v[14:17], v[154:157], v[222:225], v[14:17]
	v_mfma_f32_16x16x32_bf16 v[10:13], v[162:165], v[222:225], v[10:13]
	s_barrier
; #define PG8_STAGE(bufoff, gbase, voff) do { _Pragma("unroll") for (int _i = 0; _i < 2; ++_i) \
;         __builtin_amdgcn_global_load_lds((const unsigned*)((const char*)(gbase) + (voff)[_i]), (LAS unsigned*)(lds + (bufoff) + ldsw + _i * 8192), 16, 0, 0); } while (0)
; #define PG8_LDA(dst, b, h) do { _Pragma("unroll") for (int m = 0; m < 4; ++m) _Pragma("unroll") for (int k = 0; k < 2; ++k) dst[m][k] = *(const LAS bf16x8*)(lds + PG8_SA(b, h) + aoff + m * 2048 + k * 1024); } while (0)
; #define PG8_LDB(dst, b, h) do { _Pragma("unroll") for (int n = 0; n < 2; ++n) _Pragma("unroll") for (int k = 0; k < 2; ++k) dst[n][k] = *(const LAS bf16x8*)(lds + PG8_SB(b, h) + boff + n * 2048 + k * 1024); } while (0)
; #define PG8_MMA(ai, bj, At, Bt) do { __builtin_amdgcn_s_setprio(1); _Pragma("unroll") for (int m = 0; m < 4; ++m) _Pragma("unroll") for (int n = 0; n < 2; ++n) _Pragma("unroll") for (int k = 0; k < 2; ++k) \
;         acc[ai][bj][m][n] = __builtin_amdgcn_mfma_f32_16x16x32_bf16(Bt[n][k], At[m][k], acc[ai][bj][m][n], 0, 0, 0); __builtin_amdgcn_s_setprio(0); } while (0)
; #define PG8_WAIT_V(n) asm volatile("s_waitcnt vmcnt(" #n ")" ::: "memory")
; #define PG8_BAR __builtin_amdgcn_s_barrier()
; template <class Epi>
; __device__ __forceinline__ void gemm_phase(LAS unsigned char* lds, const Gemm g, const StaticOrder& S, const Epi& E) {
;     ...
;             PG8_LDB(B0, 0, 0); PG8_LDB(B1, 0, 1); PG8_SCHED; PG8_LDA(At, 0, 0); PG8_STAGE(PG8_SA(1, 1), a1 + hstep, voffA);
;             PG8_WAIT_V(8); PG8_WAIT_L(0); PG8_BAR; PG8_MMA(0, 0, At, B0); PG8_MMA(0, 1, At, B1); PG8_BAR; PG8_SCHED;
;             PG8_LDA(At, 0, 1); PG8_STAGE(PG8_SB(0, 0), b2, voffB); PG8_STAGE(PG8_SB(0, 1), b2 + hstep, voffB); PG8_STAGE(PG8_SA(0, 0), a2, voffA);
;             PG8_WAIT_V(8); PG8_WAIT_L(0); PG8_BAR; PG8_MMA(1, 0, At, B0); PG8_MMA(1, 1, At, B1); PG8_BAR; PG8_SCHED;
;             PG8_LDB(B0, 1, 0); PG8_LDB(B1, 1, 1); PG8_SCHED; PG8_LDA(At, 1, 0); PG8_STAGE(PG8_SA(0, 1), a2 + hstep, voffA);
;             PG8_WAIT_V(8); PG8_WAIT_L(0); PG8_BAR; PG8_MMA(0, 0, At, B0); PG8_MMA(0, 1, At, B1); PG8_BAR; PG8_SCHED;
;             PG8_LDA(At, 1, 1); PG8_STAGE(PG8_SB(1, 0), b3, voffB); PG8_STAGE(PG8_SB(1, 1), b3 + hstep, voffB); PG8_STAGE(PG8_SA(1, 0), a3, voffA);
;             PG8_WAIT_V(8); PG8_WAIT_L(0); PG8_BAR; PG8_MMA(1, 0, At, B0); PG8_MMA(1, 1, At, B1); PG8_BAR; PG8_SCHED;
	v_mfma_f32_16x16x32_bf16 v[62:65], v[158:161], v[202:205], v[62:65]
	v_mfma_f32_16x16x32_bf16 v[58:61], v[166:169], v[202:205], v[58:61]
	v_mfma_f32_16x16x32_bf16 v[46:49], v[158:161], v[210:213], v[46:49]
	v_mfma_f32_16x16x32_bf16 v[42:45], v[166:169], v[210:213], v[42:45]
	v_mfma_f32_16x16x32_bf16 v[30:33], v[158:161], v[218:221], v[30:33]
	v_mfma_f32_16x16x32_bf16 v[26:29], v[166:169], v[218:221], v[26:29]
	v_mfma_f32_16x16x32_bf16 v[14:17], v[158:161], v[226:229], v[14:17]
	v_mfma_f32_16x16x32_bf16 v[10:13], v[166:169], v[226:229], v[10:13]
	v_mfma_f32_16x16x32_bf16 v[54:57], v[182:185], v[198:201], v[54:57]
	v_mfma_f32_16x16x32_bf16 v[50:53], v[190:193], v[198:201], v[50:53]
	v_mfma_f32_16x16x32_bf16 v[38:41], v[182:185], v[206:209], v[38:41]
	v_mfma_f32_16x16x32_bf16 v[34:37], v[190:193], v[206:209], v[34:37]
	v_mfma_f32_16x16x32_bf16 v[22:25], v[182:185], v[214:217], v[22:25]
	v_mfma_f32_16x16x32_bf16 v[18:21], v[190:193], v[214:217], v[18:21]
	v_mfma_f32_16x16x32_bf16 v[6:9], v[182:185], v[222:225], v[6:9]
	v_mfma_f32_16x16x32_bf16 v[2:5], v[190:193], v[222:225], v[2:5]
	v_mfma_f32_16x16x32_bf16 v[54:57], v[186:189], v[202:205], v[54:57]
	v_mfma_f32_16x16x32_bf16 v[50:53], v[194:197], v[202:205], v[50:53]
	v_mfma_f32_16x16x32_bf16 v[38:41], v[186:189], v[210:213], v[38:41]
	v_mfma_f32_16x16x32_bf16 v[34:37], v[194:197], v[210:213], v[34:37]
	v_mfma_f32_16x16x32_bf16 v[22:25], v[186:189], v[218:221], v[22:25]
	v_mfma_f32_16x16x32_bf16 v[18:21], v[194:197], v[218:221], v[18:21]
	v_mfma_f32_16x16x32_bf16 v[6:9], v[186:189], v[226:229], v[6:9]
	v_mfma_f32_16x16x32_bf16 v[2:5], v[194:197], v[226:229], v[2:5]
	s_barrier
	s_setprio 0
	s_add_i32 s76, 0, 0x18000
	v_add_u32_e32 v138, s76, v172
	s_add_i32 s77, 0, 0x1c000
	ds_read_b128 v[154:157], v138
	ds_read_b128 v[158:161], v138 offset:1024
	ds_read_b128 v[162:165], v138 offset:2048
	ds_read_b128 v[166:169], v138 offset:3072
	v_add_u32_e32 v138, s77, v172
	ds_read_b128 v[182:185], v138
	ds_read_b128 v[186:189], v138 offset:1024
	ds_read_b128 v[190:193], v138 offset:2048
	ds_read_b128 v[194:197], v138 offset:3072
	s_add_u32 s48, s48, 0x40000
	s_addc_u32 s49, s49, 0
	s_mov_b32 m0, s52
	ds_read_b128 v[198:201], v176 offset:32768
	ds_read_b128 v[202:205], v176 offset:33792
	ds_read_b128 v[206:209], v176 offset:34816
	ds_read_b128 v[210:213], v176 offset:35840
	ds_read_b128 v[214:217], v176 offset:36864
	ds_read_b128 v[218:221], v176 offset:37888
	ds_read_b128 v[222:225], v176 offset:38912
	ds_read_b128 v[226:229], v176 offset:39936
	global_load_lds_dwordx4 v130, s[48:49]
	s_mov_b32 m0, s53
	s_nop 0
	global_load_lds_dwordx4 v134, s[48:49]
	s_waitcnt vmcnt(8)
	s_waitcnt lgkmcnt(0)
	s_setprio 1
	v_mfma_f32_16x16x32_bf16 v[126:129], v[154:157], v[198:201], v[126:129]
	v_mfma_f32_16x16x32_bf16 v[122:125], v[162:165], v[198:201], v[122:125]
	v_mfma_f32_16x16x32_bf16 v[110:113], v[154:157], v[206:209], v[110:113]
	v_mfma_f32_16x16x32_bf16 v[106:109], v[162:165], v[206:209], v[106:109]
	v_mfma_f32_16x16x32_bf16 v[94:97], v[154:157], v[214:217], v[94:97]
	v_mfma_f32_16x16x32_bf16 v[90:93], v[162:165], v[214:217], v[90:93]
	v_mfma_f32_16x16x32_bf16 v[78:81], v[154:157], v[222:225], v[78:81]
	v_mfma_f32_16x16x32_bf16 v[74:77], v[162:165], v[222:225], v[74:77]
	s_barrier
	v_mfma_f32_16x16x32_bf16 v[126:129], v[158:161], v[202:205], v[126:129]
	v_mfma_f32_16x16x32_bf16 v[122:125], v[166:169], v[202:205], v[122:125]
	v_mfma_f32_16x16x32_bf16 v[110:113], v[158:161], v[210:213], v[110:113]
	v_mfma_f32_16x16x32_bf16 v[106:109], v[166:169], v[210:213], v[106:109]
	v_mfma_f32_16x16x32_bf16 v[94:97], v[158:161], v[218:221], v[94:97]
	v_mfma_f32_16x16x32_bf16 v[90:93], v[166:169], v[218:221], v[90:93]
	v_mfma_f32_16x16x32_bf16 v[78:81], v[158:161], v[226:229], v[78:81]
	v_mfma_f32_16x16x32_bf16 v[74:77], v[166:169], v[226:229], v[74:77]
	v_mfma_f32_16x16x32_bf16 v[118:121], v[182:185], v[198:201], v[118:121]
	v_mfma_f32_16x16x32_bf16 v[114:117], v[190:193], v[198:201], v[114:117]
	v_mfma_f32_16x16x32_bf16 v[102:105], v[182:185], v[206:209], v[102:105]
	v_mfma_f32_16x16x32_bf16 v[98:101], v[190:193], v[206:209], v[98:101]
	v_mfma_f32_16x16x32_bf16 v[86:89], v[182:185], v[214:217], v[86:89]
	v_mfma_f32_16x16x32_bf16 v[82:85], v[190:193], v[214:217], v[82:85]
	v_mfma_f32_16x16x32_bf16 v[70:73], v[182:185], v[222:225], v[70:73]
	v_mfma_f32_16x16x32_bf16 v[66:69], v[190:193], v[222:225], v[66:69]
	v_mfma_f32_16x16x32_bf16 v[118:121], v[186:189], v[202:205], v[118:121]
	v_mfma_f32_16x16x32_bf16 v[114:117], v[194:197], v[202:205], v[114:117]
	v_mfma_f32_16x16x32_bf16 v[102:105], v[186:189], v[210:213], v[102:105]
	v_mfma_f32_16x16x32_bf16 v[98:101], v[194:197], v[210:213], v[98:101]
	v_mfma_f32_16x16x32_bf16 v[86:89], v[186:189], v[218:221], v[86:89]
	v_mfma_f32_16x16x32_bf16 v[82:85], v[194:197], v[218:221], v[82:85]
	v_mfma_f32_16x16x32_bf16 v[70:73], v[186:189], v[226:229], v[70:73]
	v_mfma_f32_16x16x32_bf16 v[66:69], v[194:197], v[226:229], v[66:69]
	s_barrier
; #define PG8_STAGE(bufoff, gbase, voff) do { _Pragma("unroll") for (int _i = 0; _i < 2; ++_i) \
;         __builtin_amdgcn_global_load_lds((const unsigned*)((const char*)(gbase) + (voff)[_i]), (LAS unsigned*)(lds + (bufoff) + ldsw + _i * 8192), 16, 0, 0); } while (0)
; #define PG8_LDA(dst, b, h) do { _Pragma("unroll") for (int m = 0; m < 4; ++m) _Pragma("unroll") for (int k = 0; k < 2; ++k) dst[m][k] = *(const LAS bf16x8*)(lds + PG8_SA(b, h) + aoff + m * 2048 + k * 1024); } while (0)
; #define PG8_LDB(dst, b, h) do { _Pragma("unroll") for (int n = 0; n < 2; ++n) _Pragma("unroll") for (int k = 0; k < 2; ++k) dst[n][k] = *(const LAS bf16x8*)(lds + PG8_SB(b, h) + boff + n * 2048 + k * 1024); } while (0)
; #define PG8_MMA(ai, bj, At, Bt) do { __builtin_amdgcn_s_setprio(1); _Pragma("unroll") for (int m = 0; m < 4; ++m) _Pragma("unroll") for (int n = 0; n < 2; ++n) _Pragma("unroll") for (int k = 0; k < 2; ++k) \
;         acc[ai][bj][m][n] = __builtin_amdgcn_mfma_f32_16x16x32_bf16(Bt[n][k], At[m][k], acc[ai][bj][m][n], 0, 0, 0); __builtin_amdgcn_s_setprio(0); } while (0)
; #define PG8_WAIT_V(n) asm volatile("s_waitcnt vmcnt(" #n ")" ::: "memory")
; #define PG8_WAIT_L(n) asm volatile("s_waitcnt lgkmcnt(" #n ")" ::: "memory")
; #define PG8_BAR __builtin_amdgcn_s_barrier()
; #define PG8_SCHED __builtin_amdgcn_sched_barrier(0)
; template <class Epi>
; __device__ __forceinline__ void gemm_phase(LAS unsigned char* lds, const Gemm g, const StaticOrder& S, const Epi& E) {
;     ...
;             PG8_WAIT_V(8); PG8_WAIT_L(0); PG8_BAR; PG8_MMA(1, 0, At, B0); PG8_MMA(1, 1, At, B1); PG8_BAR; PG8_SCHED;
;             PG8_LDB(B0, 1, 0); PG8_LDB(B1, 1, 1); PG8_SCHED; PG8_LDA(At, 1, 0); PG8_STAGE(PG8_SA(0, 1), a2 + hstep, voffA);
;             PG8_WAIT_V(8); PG8_WAIT_L(0); PG8_BAR; PG8_MMA(0, 0, At, B0); PG8_MMA(0, 1, At, B1); PG8_BAR; PG8_SCHED;
;             PG8_LDA(At, 1, 1); PG8_STAGE(PG8_SB(1, 0), b3, voffB); PG8_STAGE(PG8_SB(1, 1), b3 + hstep, voffB); PG8_STAGE(PG8_SA(1, 0), a3, voffA);
;             PG8_WAIT_V(8); PG8_WAIT_L(0); PG8_BAR; PG8_MMA(1, 0, At, B0); PG8_MMA(1, 1, At, B1); PG8_BAR; PG8_SCHED;
;         }
;         if (wr == 0) PG8_BAR;
	s_setprio 0
	s_add_i32 s48, s76, s6
	s_mov_b32 m0, s48
	ds_read_b128 v[198:201], v176 offset:49152
	ds_read_b128 v[202:205], v176 offset:50176
	ds_read_b128 v[206:209], v176 offset:51200
	ds_read_b128 v[210:213], v176 offset:52224
	ds_read_b128 v[214:217], v176 offset:53248
	ds_read_b128 v[218:221], v176 offset:54272
	ds_read_b128 v[222:225], v176 offset:55296
	ds_read_b128 v[226:229], v176 offset:56320
	global_load_lds_dwordx4 v132, s[98:99]
	s_add_i32 m0, s48, 0x2000
	s_add_u32 s46, s46, 0x40080
	s_addc_u32 s47, s47, 0
	s_add_i32 s48, s77, s6
	global_load_lds_dwordx4 v136, s[98:99]
	s_mov_b32 m0, s48
	s_nop 0
	global_load_lds_dwordx4 v132, s[46:47]
	s_add_i32 m0, s48, 0x2000
	s_nop 0
	global_load_lds_dwordx4 v136, s[46:47]
	s_mov_b32 m0, s56
	s_nop 0
	global_load_lds_dwordx4 v130, s[100:101]
	s_mov_b32 m0, s57
	s_nop 0
	global_load_lds_dwordx4 v134, s[100:101]
	s_waitcnt vmcnt(8)
	s_waitcnt lgkmcnt(0)
	s_setprio 1
	v_mfma_f32_16x16x32_bf16 v[62:65], v[154:157], v[198:201], v[62:65]
	v_mfma_f32_16x16x32_bf16 v[58:61], v[162:165], v[198:201], v[58:61]
	v_mfma_f32_16x16x32_bf16 v[46:49], v[154:157], v[206:209], v[46:49]
	v_mfma_f32_16x16x32_bf16 v[42:45], v[162:165], v[206:209], v[42:45]
	v_mfma_f32_16x16x32_bf16 v[30:33], v[154:157], v[214:217], v[30:33]
	v_mfma_f32_16x16x32_bf16 v[26:29], v[162:165], v[214:217], v[26:29]
	v_mfma_f32_16x16x32_bf16 v[14:17], v[154:157], v[222:225], v[14:17]
	v_mfma_f32_16x16x32_bf16 v[10:13], v[162:165], v[222:225], v[10:13]
	s_barrier
	v_mfma_f32_16x16x32_bf16 v[62:65], v[158:161], v[202:205], v[62:65]
	v_mfma_f32_16x16x32_bf16 v[58:61], v[166:169], v[202:205], v[58:61]
	v_mfma_f32_16x16x32_bf16 v[46:49], v[158:161], v[210:213], v[46:49]
	v_mfma_f32_16x16x32_bf16 v[42:45], v[166:169], v[210:213], v[42:45]
	v_mfma_f32_16x16x32_bf16 v[30:33], v[158:161], v[218:221], v[30:33]
	v_mfma_f32_16x16x32_bf16 v[26:29], v[166:169], v[218:221], v[26:29]
	v_mfma_f32_16x16x32_bf16 v[14:17], v[158:161], v[226:229], v[14:17]
	v_mfma_f32_16x16x32_bf16 v[10:13], v[166:169], v[226:229], v[10:13]
	v_mfma_f32_16x16x32_bf16 v[54:57], v[182:185], v[198:201], v[54:57]
	v_mfma_f32_16x16x32_bf16 v[50:53], v[190:193], v[198:201], v[50:53]
	v_mfma_f32_16x16x32_bf16 v[38:41], v[182:185], v[206:209], v[38:41]
	v_mfma_f32_16x16x32_bf16 v[34:37], v[190:193], v[206:209], v[34:37]
	v_mfma_f32_16x16x32_bf16 v[22:25], v[182:185], v[214:217], v[22:25]
	v_mfma_f32_16x16x32_bf16 v[18:21], v[190:193], v[214:217], v[18:21]
	v_mfma_f32_16x16x32_bf16 v[6:9], v[182:185], v[222:225], v[6:9]
	v_mfma_f32_16x16x32_bf16 v[2:5], v[190:193], v[222:225], v[2:5]
	v_mfma_f32_16x16x32_bf16 v[54:57], v[186:189], v[202:205], v[54:57]
	v_mfma_f32_16x16x32_bf16 v[50:53], v[194:197], v[202:205], v[50:53]
	v_mfma_f32_16x16x32_bf16 v[38:41], v[186:189], v[210:213], v[38:41]
	v_mfma_f32_16x16x32_bf16 v[34:37], v[194:197], v[210:213], v[34:37]
	v_mfma_f32_16x16x32_bf16 v[22:25], v[186:189], v[218:221], v[22:25]
	v_mfma_f32_16x16x32_bf16 v[18:21], v[194:197], v[218:221], v[18:21]
	v_mfma_f32_16x16x32_bf16 v[6:9], v[186:189], v[226:229], v[6:9]
	v_mfma_f32_16x16x32_bf16 v[2:5], v[194:197], v[226:229], v[2:5]
	s_barrier
	s_setprio 0
	s_add_i32 s69, s69, 2
	s_add_u32 s44, s44, 0x100
	s_addc_u32 s45, s45, 0
	s_add_u32 s67, s67, 0x100
	s_addc_u32 s68, s68, 0
	s_cmp_gt_u32 s69, 13
	s_cbranch_scc0 .LBB0_619
	s_and_b64 vcc, exec, s[18:19]
	s_cbranch_vccz .LBB0_622
	s_barrier

; #define PG8_STAGE(bufoff, gbase, voff) do { _Pragma("unroll") for (int _i = 0; _i < 2; ++_i) \
;         __builtin_amdgcn_global_load_lds((const unsigned*)((const char*)(gbase) + (voff)[_i]), (LAS unsigned*)(lds + (bufoff) + ldsw + _i * 8192), 16, 0, 0); } while (0)
; #define PG8_LDA(dst, b, h) do { _Pragma("unroll") for (int m = 0; m < 4; ++m) _Pragma("unroll") for (int k = 0; k < 2; ++k) dst[m][k] = *(const LAS bf16x8*)(lds + PG8_SA(b, h) + aoff + m * 2048 + k * 1024); } while (0)
; #define PG8_LDB(dst, b, h) do { _Pragma("unroll") for (int n = 0; n < 2; ++n) _Pragma("unroll") for (int k = 0; k < 2; ++k) dst[n][k] = *(const LAS bf16x8*)(lds + PG8_SB(b, h) + boff + n * 2048 + k * 1024); } while (0)
; #define PG8_MMA(ai, bj, At, Bt) do { __builtin_amdgcn_s_setprio(1); _Pragma("unroll") for (int m = 0; m < 4; ++m) _Pragma("unroll") for (int n = 0; n < 2; ++n) _Pragma("unroll") for (int k = 0; k < 2; ++k) \
;         acc[ai][bj][m][n] = __builtin_amdgcn_mfma_f32_16x16x32_bf16(Bt[n][k], At[m][k], acc[ai][bj][m][n], 0, 0, 0); __builtin_amdgcn_s_setprio(0); } while (0)
; #define PG8_WAIT_V(n) asm volatile("s_waitcnt vmcnt(" #n ")" ::: "memory")
; #define PG8_WAIT_L(n) asm volatile("s_waitcnt lgkmcnt(" #n ")" ::: "memory")
; #define PG8_BAR __builtin_amdgcn_s_barrier()
; template <class Epi>
; __device__ __forceinline__ void gemm_phase(LAS unsigned char* lds, const Gemm g, const StaticOrder& S, const Epi& E) {
;     ...
;         for (int t = 0; t < nt; t += 2) {
;             const bool last = (t == nt - 2);
;             const char* a1 = cA + (size_t)(t + 1) * kstep;
;             const char* a2 = last ? nA : cA + (size_t)(t + 2) * kstep; const char* b2 = last ? nB : cB + (size_t)(t + 2) * kstep;
;             const char* a3 = a2 + kstep; const char* b3 = b2 + kstep;
;             if constexpr (Epi::MIDK > 0) { if (t == Epi::MIDK) E.mid(acc, cur, wr, wc, fr, fq); }
;             PG8_LDB(B0, 0, 0); PG8_LDB(B1, 0, 1); PG8_SCHED; PG8_LDA(At, 0, 0); PG8_STAGE(PG8_SA(1, 1), a1 + hstep, voffA);
;             PG8_WAIT_V(8); PG8_WAIT_L(0); PG8_BAR; PG8_MMA(0, 0, At, B0); PG8_MMA(0, 1, At, B1); PG8_BAR; PG8_SCHED;
;             PG8_LDA(At, 0, 1); PG8_STAGE(PG8_SB(0, 0), b2, voffB); PG8_STAGE(PG8_SB(0, 1), b2 + hstep, voffB); PG8_STAGE(PG8_SA(0, 0), a2, voffA);
;             PG8_WAIT_V(8); PG8_WAIT_L(0); PG8_BAR; PG8_MMA(1, 0, At, B0); PG8_MMA(1, 1, At, B1); PG8_BAR; PG8_SCHED;
.LBB0_785:
	ds_read_b128 v[130:133], v162
	ds_read_b128 v[134:137], v162 offset:1024
	ds_read_b128 v[154:157], v162 offset:2048
	ds_read_b128 v[166:169], v162 offset:3072
	ds_read_b128 v[172:175], v163
	ds_read_b128 v[176:179], v163 offset:1024
	ds_read_b128 v[180:183], v163 offset:2048
	ds_read_b128 v[184:187], v163 offset:3072
	s_add_u32 s40, s38, 0xfffc0080
	s_addc_u32 s41, s39, -1
	s_cmp_eq_u32 s63, 12
	s_cselect_b32 s43, s21, s41
	s_cselect_b32 s42, s27, s40
	s_cselect_b32 s41, s19, s62
	s_cselect_b32 s40, s60, s61
	s_add_i32 m0, s45, 0xc000
	ds_read_b128 v[188:191], v164
	ds_read_b128 v[192:195], v164 offset:1024
	ds_read_b128 v[196:199], v164 offset:2048
	ds_read_b128 v[200:203], v164 offset:3072
	ds_read_b128 v[204:207], v164 offset:4096
	ds_read_b128 v[208:211], v164 offset:5120
	ds_read_b128 v[212:215], v164 offset:6144
	ds_read_b128 v[216:219], v164 offset:7168
	global_load_lds_dwordx4 v146, s[38:39]
	s_add_i32 m0, s45, 0xe000
	s_nop 0
	global_load_lds_dwordx4 v148, s[38:39]
	s_waitcnt vmcnt(8)
	s_waitcnt lgkmcnt(0)
	s_setprio 1
	v_mfma_f32_16x16x32_bf16 v[126:129], v[130:133], v[188:191], v[126:129]
	v_mfma_f32_16x16x32_bf16 v[122:125], v[154:157], v[188:191], v[122:125]
	v_mfma_f32_16x16x32_bf16 v[110:113], v[130:133], v[196:199], v[110:113]
	v_mfma_f32_16x16x32_bf16 v[106:109], v[154:157], v[196:199], v[106:109]
	v_mfma_f32_16x16x32_bf16 v[94:97], v[130:133], v[204:207], v[94:97]
	v_mfma_f32_16x16x32_bf16 v[90:93], v[154:157], v[204:207], v[90:93]
	v_mfma_f32_16x16x32_bf16 v[78:81], v[130:133], v[212:215], v[78:81]
	v_mfma_f32_16x16x32_bf16 v[74:77], v[154:157], v[212:215], v[74:77]
	s_barrier
	v_mfma_f32_16x16x32_bf16 v[126:129], v[134:137], v[192:195], v[126:129]
	v_mfma_f32_16x16x32_bf16 v[122:125], v[166:169], v[192:195], v[122:125]
	v_mfma_f32_16x16x32_bf16 v[110:113], v[134:137], v[200:203], v[110:113]
	v_mfma_f32_16x16x32_bf16 v[106:109], v[166:169], v[200:203], v[106:109]
	v_mfma_f32_16x16x32_bf16 v[94:97], v[134:137], v[208:211], v[94:97]
	v_mfma_f32_16x16x32_bf16 v[90:93], v[166:169], v[208:211], v[90:93]
	v_mfma_f32_16x16x32_bf16 v[78:81], v[134:137], v[216:219], v[78:81]
	v_mfma_f32_16x16x32_bf16 v[74:77], v[166:169], v[216:219], v[74:77]
	v_mfma_f32_16x16x32_bf16 v[118:121], v[172:175], v[188:191], v[118:121]
	v_mfma_f32_16x16x32_bf16 v[114:117], v[180:183], v[188:191], v[114:117]
	v_mfma_f32_16x16x32_bf16 v[102:105], v[172:175], v[196:199], v[102:105]
	v_mfma_f32_16x16x32_bf16 v[98:101], v[180:183], v[196:199], v[98:101]
	v_mfma_f32_16x16x32_bf16 v[86:89], v[172:175], v[204:207], v[86:89]
	v_mfma_f32_16x16x32_bf16 v[82:85], v[180:183], v[204:207], v[82:85]
	v_mfma_f32_16x16x32_bf16 v[70:73], v[172:175], v[212:215], v[70:73]
	v_mfma_f32_16x16x32_bf16 v[66:69], v[180:183], v[212:215], v[66:69]
	v_mfma_f32_16x16x32_bf16 v[118:121], v[176:179], v[192:195], v[118:121]
	v_mfma_f32_16x16x32_bf16 v[114:117], v[184:187], v[192:195], v[114:117]
	v_mfma_f32_16x16x32_bf16 v[102:105], v[176:179], v[200:203], v[102:105]
	v_mfma_f32_16x16x32_bf16 v[98:101], v[184:187], v[200:203], v[98:101]
	v_mfma_f32_16x16x32_bf16 v[86:89], v[176:179], v[208:211], v[86:89]
	v_mfma_f32_16x16x32_bf16 v[82:85], v[184:187], v[208:211], v[82:85]
	v_mfma_f32_16x16x32_bf16 v[70:73], v[176:179], v[216:219], v[70:73]
	v_mfma_f32_16x16x32_bf16 v[66:69], v[184:187], v[216:219], v[66:69]
	s_barrier
	s_setprio 0
	s_add_u32 s98, s40, s12
	s_addc_u32 s99, s41, s13
	s_add_u32 s100, s42, s12
	s_addc_u32 s101, s43, s13
	s_add_i32 s64, s57, s44
	s_mov_b32 m0, s64
	ds_read_b128 v[188:191], v164 offset:16384
	ds_read_b128 v[192:195], v164 offset:17408
	ds_read_b128 v[196:199], v164 offset:18432
	ds_read_b128 v[200:203], v164 offset:19456
	ds_read_b128 v[204:207], v164 offset:20480
	ds_read_b128 v[208:211], v164 offset:21504
	ds_read_b128 v[212:215], v164 offset:22528
	ds_read_b128 v[216:219], v164 offset:23552
	global_load_lds_dwordx4 v140, s[40:41]
	s_add_i32 m0, s64, 0x2000
	s_add_u32 s64, s40, 0x40000
	s_addc_u32 s65, s41, 0
	s_add_i32 s66, s58, s44
	global_load_lds_dwordx4 v144, s[40:41]
	s_mov_b32 m0, s66
	s_nop 0
	global_load_lds_dwordx4 v140, s[64:65]
	s_add_i32 m0, s66, 0x2000
	s_nop 0
	global_load_lds_dwordx4 v144, s[64:65]
	s_mov_b32 m0, s45
	s_nop 0
	global_load_lds_dwordx4 v138, s[42:43]
	s_mov_b32 m0, s46
	s_nop 0
	global_load_lds_dwordx4 v142, s[42:43]
	s_waitcnt vmcnt(8)
	s_waitcnt lgkmcnt(0)
	s_setprio 1
	v_mfma_f32_16x16x32_bf16 v[62:65], v[130:133], v[188:191], v[62:65]
	v_mfma_f32_16x16x32_bf16 v[58:61], v[154:157], v[188:191], v[58:61]
	v_mfma_f32_16x16x32_bf16 v[46:49], v[130:133], v[196:199], v[46:49]
	v_mfma_f32_16x16x32_bf16 v[42:45], v[154:157], v[196:199], v[42:45]
	v_mfma_f32_16x16x32_bf16 v[30:33], v[130:133], v[204:207], v[30:33]
	v_mfma_f32_16x16x32_bf16 v[26:29], v[154:157], v[204:207], v[26:29]
	v_mfma_f32_16x16x32_bf16 v[14:17], v[130:133], v[212:215], v[14:17]
	v_mfma_f32_16x16x32_bf16 v[10:13], v[154:157], v[212:215], v[10:13]
	s_barrier
; #define PG8_STAGE(bufoff, gbase, voff) do { _Pragma("unroll") for (int _i = 0; _i < 2; ++_i) \
;         __builtin_amdgcn_global_load_lds((const unsigned*)((const char*)(gbase) + (voff)[_i]), (LAS unsigned*)(lds + (bufoff) + ldsw + _i * 8192), 16, 0, 0); } while (0)
; #define PG8_LDA(dst, b, h) do { _Pragma("unroll") for (int m = 0; m < 4; ++m) _Pragma("unroll") for (int k = 0; k < 2; ++k) dst[m][k] = *(const LAS bf16x8*)(lds + PG8_SA(b, h) + aoff + m * 2048 + k * 1024); } while (0)
; #define PG8_LDB(dst, b, h) do { _Pragma("unroll") for (int n = 0; n < 2; ++n) _Pragma("unroll") for (int k = 0; k < 2; ++k) dst[n][k] = *(const LAS bf16x8*)(lds + PG8_SB(b, h) + boff + n * 2048 + k * 1024); } while (0)
; #define PG8_MMA(ai, bj, At, Bt) do { __builtin_amdgcn_s_setprio(1); _Pragma("unroll") for (int m = 0; m < 4; ++m) _Pragma("unroll") for (int n = 0; n < 2; ++n) _Pragma("unroll") for (int k = 0; k < 2; ++k) \
;         acc[ai][bj][m][n] = __builtin_amdgcn_mfma_f32_16x16x32_bf16(Bt[n][k], At[m][k], acc[ai][bj][m][n], 0, 0, 0); __builtin_amdgcn_s_setprio(0); } while (0)
; #define PG8_WAIT_V(n) asm volatile("s_waitcnt vmcnt(" #n ")" ::: "memory")
; #define PG8_WAIT_L(n) asm volatile("s_waitcnt lgkmcnt(" #n ")" ::: "memory")
; #define PG8_BAR __builtin_amdgcn_s_barrier()
; #define PG8_SCHED __builtin_amdgcn_sched_barrier(0)
; template <class Epi>
; __device__ __forceinline__ void gemm_phase(LAS unsigned char* lds, const Gemm g, const StaticOrder& S, const Epi& E) {
;     ...
;             PG8_WAIT_V(8); PG8_WAIT_L(0); PG8_BAR; PG8_MMA(0, 0, At, B0); PG8_MMA(0, 1, At, B1); PG8_BAR; PG8_SCHED;
;             PG8_LDA(At, 0, 1); PG8_STAGE(PG8_SB(0, 0), b2, voffB); PG8_STAGE(PG8_SB(0, 1), b2 + hstep, voffB); PG8_STAGE(PG8_SA(0, 0), a2, voffA);
;             PG8_WAIT_V(8); PG8_WAIT_L(0); PG8_BAR; PG8_MMA(1, 0, At, B0); PG8_MMA(1, 1, At, B1); PG8_BAR; PG8_SCHED;
;             PG8_LDB(B0, 1, 0); PG8_LDB(B1, 1, 1); PG8_SCHED; PG8_LDA(At, 1, 0); PG8_STAGE(PG8_SA(0, 1), a2 + hstep, voffA);
;             PG8_WAIT_V(8); PG8_WAIT_L(0); PG8_BAR; PG8_MMA(0, 0, At, B0); PG8_MMA(0, 1, At, B1); PG8_BAR; PG8_SCHED;
	v_mfma_f32_16x16x32_bf16 v[62:65], v[134:137], v[192:195], v[62:65]
	v_mfma_f32_16x16x32_bf16 v[58:61], v[166:169], v[192:195], v[58:61]
	v_mfma_f32_16x16x32_bf16 v[46:49], v[134:137], v[200:203], v[46:49]
	v_mfma_f32_16x16x32_bf16 v[42:45], v[166:169], v[200:203], v[42:45]
	v_mfma_f32_16x16x32_bf16 v[30:33], v[134:137], v[208:211], v[30:33]
	v_mfma_f32_16x16x32_bf16 v[26:29], v[166:169], v[208:211], v[26:29]
	v_mfma_f32_16x16x32_bf16 v[14:17], v[134:137], v[216:219], v[14:17]
	v_mfma_f32_16x16x32_bf16 v[10:13], v[166:169], v[216:219], v[10:13]
	v_mfma_f32_16x16x32_bf16 v[54:57], v[172:175], v[188:191], v[54:57]
	v_mfma_f32_16x16x32_bf16 v[50:53], v[180:183], v[188:191], v[50:53]
	v_mfma_f32_16x16x32_bf16 v[38:41], v[172:175], v[196:199], v[38:41]
	v_mfma_f32_16x16x32_bf16 v[34:37], v[180:183], v[196:199], v[34:37]
	v_mfma_f32_16x16x32_bf16 v[22:25], v[172:175], v[204:207], v[22:25]
	v_mfma_f32_16x16x32_bf16 v[18:21], v[180:183], v[204:207], v[18:21]
	v_mfma_f32_16x16x32_bf16 v[6:9], v[172:175], v[212:215], v[6:9]
	v_mfma_f32_16x16x32_bf16 v[2:5], v[180:183], v[212:215], v[2:5]
	v_mfma_f32_16x16x32_bf16 v[54:57], v[176:179], v[192:195], v[54:57]
	v_mfma_f32_16x16x32_bf16 v[50:53], v[184:187], v[192:195], v[50:53]
	v_mfma_f32_16x16x32_bf16 v[38:41], v[176:179], v[200:203], v[38:41]
	v_mfma_f32_16x16x32_bf16 v[34:37], v[184:187], v[200:203], v[34:37]
	v_mfma_f32_16x16x32_bf16 v[22:25], v[176:179], v[208:211], v[22:25]
	v_mfma_f32_16x16x32_bf16 v[18:21], v[184:187], v[208:211], v[18:21]
	v_mfma_f32_16x16x32_bf16 v[6:9], v[176:179], v[216:219], v[6:9]
	v_mfma_f32_16x16x32_bf16 v[2:5], v[184:187], v[216:219], v[2:5]
	s_barrier
	s_setprio 0
	s_add_i32 s64, 0, 0x18000
	s_add_i32 s65, 0, 0x1c000
	v_add_u32_e32 v166, s64, v160
	v_add_u32_e32 v184, s65, v160
	ds_read_b128 v[130:133], v166
	ds_read_b128 v[134:137], v166 offset:1024
	ds_read_b128 v[154:157], v166 offset:2048
	ds_read_b128 v[166:169], v166 offset:3072
	ds_read_b128 v[172:175], v184
	ds_read_b128 v[176:179], v184 offset:1024
	ds_read_b128 v[180:183], v184 offset:2048
	ds_read_b128 v[184:187], v184 offset:3072
	s_add_u32 s42, s42, 0x40000
	s_addc_u32 s43, s43, 0
	s_mov_b32 m0, s47
	ds_read_b128 v[188:191], v164 offset:32768
	ds_read_b128 v[192:195], v164 offset:33792
	ds_read_b128 v[196:199], v164 offset:34816
	ds_read_b128 v[200:203], v164 offset:35840
	ds_read_b128 v[204:207], v164 offset:36864
	ds_read_b128 v[208:211], v164 offset:37888
	ds_read_b128 v[212:215], v164 offset:38912
	ds_read_b128 v[216:219], v164 offset:39936
	global_load_lds_dwordx4 v138, s[42:43]
	s_mov_b32 m0, s48
	s_nop 0
	global_load_lds_dwordx4 v142, s[42:43]
	s_waitcnt vmcnt(8)
	s_waitcnt lgkmcnt(0)
	s_setprio 1
	v_mfma_f32_16x16x32_bf16 v[126:129], v[130:133], v[188:191], v[126:129]
	v_mfma_f32_16x16x32_bf16 v[122:125], v[154:157], v[188:191], v[122:125]
	v_mfma_f32_16x16x32_bf16 v[110:113], v[130:133], v[196:199], v[110:113]
	v_mfma_f32_16x16x32_bf16 v[106:109], v[154:157], v[196:199], v[106:109]
	v_mfma_f32_16x16x32_bf16 v[94:97], v[130:133], v[204:207], v[94:97]
	v_mfma_f32_16x16x32_bf16 v[90:93], v[154:157], v[204:207], v[90:93]
	v_mfma_f32_16x16x32_bf16 v[78:81], v[130:133], v[212:215], v[78:81]
	v_mfma_f32_16x16x32_bf16 v[74:77], v[154:157], v[212:215], v[74:77]
	s_barrier
	v_mfma_f32_16x16x32_bf16 v[126:129], v[134:137], v[192:195], v[126:129]
	v_mfma_f32_16x16x32_bf16 v[122:125], v[166:169], v[192:195], v[122:125]
	v_mfma_f32_16x16x32_bf16 v[110:113], v[134:137], v[200:203], v[110:113]
	v_mfma_f32_16x16x32_bf16 v[106:109], v[166:169], v[200:203], v[106:109]
	v_mfma_f32_16x16x32_bf16 v[94:97], v[134:137], v[208:211], v[94:97]
	v_mfma_f32_16x16x32_bf16 v[90:93], v[166:169], v[208:211], v[90:93]
	v_mfma_f32_16x16x32_bf16 v[78:81], v[134:137], v[216:219], v[78:81]
	v_mfma_f32_16x16x32_bf16 v[74:77], v[166:169], v[216:219], v[74:77]
	v_mfma_f32_16x16x32_bf16 v[118:121], v[172:175], v[188:191], v[118:121]
	v_mfma_f32_16x16x32_bf16 v[114:117], v[180:183], v[188:191], v[114:117]
	v_mfma_f32_16x16x32_bf16 v[102:105], v[172:175], v[196:199], v[102:105]
	v_mfma_f32_16x16x32_bf16 v[98:101], v[180:183], v[196:199], v[98:101]
	v_mfma_f32_16x16x32_bf16 v[86:89], v[172:175], v[204:207], v[86:89]
	v_mfma_f32_16x16x32_bf16 v[82:85], v[180:183], v[204:207], v[82:85]
	v_mfma_f32_16x16x32_bf16 v[70:73], v[172:175], v[212:215], v[70:73]
	v_mfma_f32_16x16x32_bf16 v[66:69], v[180:183], v[212:215], v[66:69]
	v_mfma_f32_16x16x32_bf16 v[118:121], v[176:179], v[192:195], v[118:121]
	v_mfma_f32_16x16x32_bf16 v[114:117], v[184:187], v[192:195], v[114:117]
	v_mfma_f32_16x16x32_bf16 v[102:105], v[176:179], v[200:203], v[102:105]
	v_mfma_f32_16x16x32_bf16 v[98:101], v[184:187], v[200:203], v[98:101]
	v_mfma_f32_16x16x32_bf16 v[86:89], v[176:179], v[208:211], v[86:89]
	v_mfma_f32_16x16x32_bf16 v[82:85], v[184:187], v[208:211], v[82:85]
	v_mfma_f32_16x16x32_bf16 v[70:73], v[176:179], v[216:219], v[70:73]
	v_mfma_f32_16x16x32_bf16 v[66:69], v[184:187], v[216:219], v[66:69]
	s_barrier
; #define PG8_STAGE(bufoff, gbase, voff) do { _Pragma("unroll") for (int _i = 0; _i < 2; ++_i) \
;         __builtin_amdgcn_global_load_lds((const unsigned*)((const char*)(gbase) + (voff)[_i]), (LAS unsigned*)(lds + (bufoff) + ldsw + _i * 8192), 16, 0, 0); } while (0)
; #define PG8_LDA(dst, b, h) do { _Pragma("unroll") for (int m = 0; m < 4; ++m) _Pragma("unroll") for (int k = 0; k < 2; ++k) dst[m][k] = *(const LAS bf16x8*)(lds + PG8_SA(b, h) + aoff + m * 2048 + k * 1024); } while (0)
; #define PG8_MMA(ai, bj, At, Bt) do { __builtin_amdgcn_s_setprio(1); _Pragma("unroll") for (int m = 0; m < 4; ++m) _Pragma("unroll") for (int n = 0; n < 2; ++n) _Pragma("unroll") for (int k = 0; k < 2; ++k) \
;         acc[ai][bj][m][n] = __builtin_amdgcn_mfma_f32_16x16x32_bf16(Bt[n][k], At[m][k], acc[ai][bj][m][n], 0, 0, 0); __builtin_amdgcn_s_setprio(0); } while (0)
; #define PG8_WAIT_V(n) asm volatile("s_waitcnt vmcnt(" #n ")" ::: "memory")
; #define PG8_WAIT_L(n) asm volatile("s_waitcnt lgkmcnt(" #n ")" ::: "memory")
; #define PG8_BAR __builtin_amdgcn_s_barrier()
; #define PG8_SCHED __builtin_amdgcn_sched_barrier(0)
; template <class Epi>
; __device__ __forceinline__ void gemm_phase(LAS unsigned char* lds, const Gemm g, const StaticOrder& S, const Epi& E) {
;     ...
;             PG8_WAIT_V(8); PG8_WAIT_L(0); PG8_BAR; PG8_MMA(0, 0, At, B0); PG8_MMA(0, 1, At, B1); PG8_BAR; PG8_SCHED;
;             PG8_LDA(At, 1, 1); PG8_STAGE(PG8_SB(1, 0), b3, voffB); PG8_STAGE(PG8_SB(1, 1), b3 + hstep, voffB); PG8_STAGE(PG8_SA(1, 0), a3, voffA);
;             PG8_WAIT_V(8); PG8_WAIT_L(0); PG8_BAR; PG8_MMA(1, 0, At, B0); PG8_MMA(1, 1, At, B1); PG8_BAR; PG8_SCHED;
;         }
;         if (wr == 0) PG8_BAR;
	s_setprio 0
	s_add_i32 s42, s64, s44
	s_mov_b32 m0, s42
	ds_read_b128 v[188:191], v164 offset:49152
	ds_read_b128 v[192:195], v164 offset:50176
	ds_read_b128 v[196:199], v164 offset:51200
	ds_read_b128 v[200:203], v164 offset:52224
	ds_read_b128 v[204:207], v164 offset:53248
	ds_read_b128 v[208:211], v164 offset:54272
	ds_read_b128 v[212:215], v164 offset:55296
	ds_read_b128 v[216:219], v164 offset:56320
	global_load_lds_dwordx4 v140, s[98:99]
	s_add_i32 m0, s42, 0x2000
	s_add_u32 s40, s40, 0x40080
	s_addc_u32 s41, s41, 0
	s_add_i32 s42, s65, s44
	global_load_lds_dwordx4 v144, s[98:99]
	s_mov_b32 m0, s42
	s_nop 0
	global_load_lds_dwordx4 v140, s[40:41]
	s_add_i32 m0, s42, 0x2000
	s_nop 0
	global_load_lds_dwordx4 v144, s[40:41]
	s_mov_b32 m0, s50
	s_nop 0
	global_load_lds_dwordx4 v138, s[100:101]
	s_mov_b32 m0, s51
	s_nop 0
	global_load_lds_dwordx4 v142, s[100:101]
	s_waitcnt vmcnt(8)
	s_waitcnt lgkmcnt(0)
	s_setprio 1
	v_mfma_f32_16x16x32_bf16 v[62:65], v[130:133], v[188:191], v[62:65]
	v_mfma_f32_16x16x32_bf16 v[58:61], v[154:157], v[188:191], v[58:61]
	v_mfma_f32_16x16x32_bf16 v[46:49], v[130:133], v[196:199], v[46:49]
	v_mfma_f32_16x16x32_bf16 v[42:45], v[154:157], v[196:199], v[42:45]
	v_mfma_f32_16x16x32_bf16 v[30:33], v[130:133], v[204:207], v[30:33]
	v_mfma_f32_16x16x32_bf16 v[26:29], v[154:157], v[204:207], v[26:29]
	v_mfma_f32_16x16x32_bf16 v[14:17], v[130:133], v[212:215], v[14:17]
	v_mfma_f32_16x16x32_bf16 v[10:13], v[154:157], v[212:215], v[10:13]
	s_barrier
	v_mfma_f32_16x16x32_bf16 v[62:65], v[134:137], v[192:195], v[62:65]
	v_mfma_f32_16x16x32_bf16 v[58:61], v[166:169], v[192:195], v[58:61]
	v_mfma_f32_16x16x32_bf16 v[46:49], v[134:137], v[200:203], v[46:49]
	v_mfma_f32_16x16x32_bf16 v[42:45], v[166:169], v[200:203], v[42:45]
	v_mfma_f32_16x16x32_bf16 v[30:33], v[134:137], v[208:211], v[30:33]
	v_mfma_f32_16x16x32_bf16 v[26:29], v[166:169], v[208:211], v[26:29]
	v_mfma_f32_16x16x32_bf16 v[14:17], v[134:137], v[216:219], v[14:17]
	v_mfma_f32_16x16x32_bf16 v[10:13], v[166:169], v[216:219], v[10:13]
	v_mfma_f32_16x16x32_bf16 v[54:57], v[172:175], v[188:191], v[54:57]
	v_mfma_f32_16x16x32_bf16 v[50:53], v[180:183], v[188:191], v[50:53]
	v_mfma_f32_16x16x32_bf16 v[38:41], v[172:175], v[196:199], v[38:41]
	v_mfma_f32_16x16x32_bf16 v[34:37], v[180:183], v[196:199], v[34:37]
	v_mfma_f32_16x16x32_bf16 v[22:25], v[172:175], v[204:207], v[22:25]
	v_mfma_f32_16x16x32_bf16 v[18:21], v[180:183], v[204:207], v[18:21]
	v_mfma_f32_16x16x32_bf16 v[6:9], v[172:175], v[212:215], v[6:9]
	v_mfma_f32_16x16x32_bf16 v[2:5], v[180:183], v[212:215], v[2:5]
	v_mfma_f32_16x16x32_bf16 v[54:57], v[176:179], v[192:195], v[54:57]
	v_mfma_f32_16x16x32_bf16 v[50:53], v[184:187], v[192:195], v[50:53]
	v_mfma_f32_16x16x32_bf16 v[38:41], v[176:179], v[200:203], v[38:41]
	v_mfma_f32_16x16x32_bf16 v[34:37], v[184:187], v[200:203], v[34:37]
	v_mfma_f32_16x16x32_bf16 v[22:25], v[176:179], v[208:211], v[22:25]
	v_mfma_f32_16x16x32_bf16 v[18:21], v[184:187], v[208:211], v[18:21]
	v_mfma_f32_16x16x32_bf16 v[6:9], v[176:179], v[216:219], v[6:9]
	v_mfma_f32_16x16x32_bf16 v[2:5], v[184:187], v[216:219], v[2:5]
	s_barrier
	s_setprio 0
	s_add_i32 s63, s63, 2
	s_add_u32 s38, s38, 0x100
	s_addc_u32 s39, s39, 0
	s_add_u32 s61, s61, 0x100
	s_addc_u32 s62, s62, 0
	s_cmp_gt_u32 s63, 13
	s_cbranch_scc0 .LBB0_785
	s_and_b64 vcc, exec, s[14:15]
	s_cbranch_vccz .LBB0_788
	s_barrier

; #define PG8_STAGE(bufoff, gbase, voff) do { _Pragma("unroll") for (int _i = 0; _i < 2; ++_i) \
;         __builtin_amdgcn_global_load_lds((const unsigned*)((const char*)(gbase) + (voff)[_i]), (LAS unsigned*)(lds + (bufoff) + ldsw + _i * 8192), 16, 0, 0); } while (0)
; #define PG8_LDA(dst, b, h) do { _Pragma("unroll") for (int m = 0; m < 4; ++m) _Pragma("unroll") for (int k = 0; k < 2; ++k) dst[m][k] = *(const LAS bf16x8*)(lds + PG8_SA(b, h) + aoff + m * 2048 + k * 1024); } while (0)
; #define PG8_LDB(dst, b, h) do { _Pragma("unroll") for (int n = 0; n < 2; ++n) _Pragma("unroll") for (int k = 0; k < 2; ++k) dst[n][k] = *(const LAS bf16x8*)(lds + PG8_SB(b, h) + boff + n * 2048 + k * 1024); } while (0)
; #define PG8_MMA(ai, bj, At, Bt) do { __builtin_amdgcn_s_setprio(1); _Pragma("unroll") for (int m = 0; m < 4; ++m) _Pragma("unroll") for (int n = 0; n < 2; ++n) _Pragma("unroll") for (int k = 0; k < 2; ++k) \
;         acc[ai][bj][m][n] = __builtin_amdgcn_mfma_f32_16x16x32_bf16(Bt[n][k], At[m][k], acc[ai][bj][m][n], 0, 0, 0); __builtin_amdgcn_s_setprio(0); } while (0)
; #define PG8_WAIT_V(n) asm volatile("s_waitcnt vmcnt(" #n ")" ::: "memory")
; #define PG8_WAIT_L(n) asm volatile("s_waitcnt lgkmcnt(" #n ")" ::: "memory")
; #define PG8_BAR __builtin_amdgcn_s_barrier()
; template <class Epi>
; __device__ __forceinline__ void gemm_phase(LAS unsigned char* lds, const Gemm g, const StaticOrder& S, const Epi& E) {
;     ...
;         for (int t = 0; t < nt; t += 2) {
;             const bool last = (t == nt - 2);
;             const char* a1 = cA + (size_t)(t + 1) * kstep;
;             const char* a2 = last ? nA : cA + (size_t)(t + 2) * kstep; const char* b2 = last ? nB : cB + (size_t)(t + 2) * kstep;
;             const char* a3 = a2 + kstep; const char* b3 = b2 + kstep;
;             if constexpr (Epi::MIDK > 0) { if (t == Epi::MIDK) E.mid(acc, cur, wr, wc, fr, fq); }
;             PG8_LDB(B0, 0, 0); PG8_LDB(B1, 0, 1); PG8_SCHED; PG8_LDA(At, 0, 0); PG8_STAGE(PG8_SA(1, 1), a1 + hstep, voffA);
;             PG8_WAIT_V(8); PG8_WAIT_L(0); PG8_BAR; PG8_MMA(0, 0, At, B0); PG8_MMA(0, 1, At, B1); PG8_BAR; PG8_SCHED;
;             PG8_LDA(At, 0, 1); PG8_STAGE(PG8_SB(0, 0), b2, voffB); PG8_STAGE(PG8_SB(0, 1), b2 + hstep, voffB); PG8_STAGE(PG8_SA(0, 0), a2, voffA);
;             PG8_WAIT_V(8); PG8_WAIT_L(0); PG8_BAR; PG8_MMA(1, 0, At, B0); PG8_MMA(1, 1, At, B1); PG8_BAR; PG8_SCHED;
.LBB0_884:
	ds_read_b128 v[158:161], v150
	ds_read_b128 v[162:165], v150 offset:1024
	ds_read_b128 v[166:169], v150 offset:2048
	ds_read_b128 v[174:177], v150 offset:3072
	ds_read_b128 v[178:181], v151
	ds_read_b128 v[182:185], v151 offset:1024
	ds_read_b128 v[186:189], v151 offset:2048
	ds_read_b128 v[190:193], v151 offset:3072
	s_add_u32 s46, s44, 0xfffc0080
	s_addc_u32 s47, s45, -1
	s_cmp_eq_u32 s67, 12
	s_cselect_b32 s49, s62, s47
	s_cselect_b32 s48, s63, s46
	s_cselect_b32 s47, s23, s66
	s_cselect_b32 s46, s64, s65
	s_add_i32 m0, s41, 0xc000
	ds_read_b128 v[194:197], v152
	ds_read_b128 v[198:201], v152 offset:1024
	ds_read_b128 v[202:205], v152 offset:2048
	ds_read_b128 v[206:209], v152 offset:3072
	ds_read_b128 v[210:213], v152 offset:4096
	ds_read_b128 v[214:217], v152 offset:5120
	ds_read_b128 v[218:221], v152 offset:6144
	ds_read_b128 v[222:225], v152 offset:7168
	global_load_lds_dwordx4 v140, s[44:45]
	s_add_i32 m0, s41, 0xe000
	s_nop 0
	global_load_lds_dwordx4 v142, s[44:45]
	s_waitcnt vmcnt(8)
	s_waitcnt lgkmcnt(0)
	s_setprio 1
	v_mfma_f32_16x16x32_bf16 v[126:129], v[158:161], v[194:197], v[126:129]
	v_mfma_f32_16x16x32_bf16 v[118:121], v[166:169], v[194:197], v[118:121]
	v_mfma_f32_16x16x32_bf16 v[110:113], v[158:161], v[202:205], v[110:113]
	v_mfma_f32_16x16x32_bf16 v[102:105], v[166:169], v[202:205], v[102:105]
	v_mfma_f32_16x16x32_bf16 v[94:97], v[158:161], v[210:213], v[94:97]
	v_mfma_f32_16x16x32_bf16 v[86:89], v[166:169], v[210:213], v[86:89]
	v_mfma_f32_16x16x32_bf16 v[78:81], v[158:161], v[218:221], v[78:81]
	v_mfma_f32_16x16x32_bf16 v[70:73], v[166:169], v[218:221], v[70:73]
	s_barrier
	v_mfma_f32_16x16x32_bf16 v[126:129], v[162:165], v[198:201], v[126:129]
	v_mfma_f32_16x16x32_bf16 v[118:121], v[174:177], v[198:201], v[118:121]
	v_mfma_f32_16x16x32_bf16 v[110:113], v[162:165], v[206:209], v[110:113]
	v_mfma_f32_16x16x32_bf16 v[102:105], v[174:177], v[206:209], v[102:105]
	v_mfma_f32_16x16x32_bf16 v[94:97], v[162:165], v[214:217], v[94:97]
	v_mfma_f32_16x16x32_bf16 v[86:89], v[174:177], v[214:217], v[86:89]
	v_mfma_f32_16x16x32_bf16 v[78:81], v[162:165], v[222:225], v[78:81]
	v_mfma_f32_16x16x32_bf16 v[70:73], v[174:177], v[222:225], v[70:73]
	v_mfma_f32_16x16x32_bf16 v[122:125], v[178:181], v[194:197], v[122:125]
	v_mfma_f32_16x16x32_bf16 v[114:117], v[186:189], v[194:197], v[114:117]
	v_mfma_f32_16x16x32_bf16 v[106:109], v[178:181], v[202:205], v[106:109]
	v_mfma_f32_16x16x32_bf16 v[98:101], v[186:189], v[202:205], v[98:101]
	v_mfma_f32_16x16x32_bf16 v[90:93], v[178:181], v[210:213], v[90:93]
	v_mfma_f32_16x16x32_bf16 v[82:85], v[186:189], v[210:213], v[82:85]
	v_mfma_f32_16x16x32_bf16 v[74:77], v[178:181], v[218:221], v[74:77]
	v_mfma_f32_16x16x32_bf16 v[66:69], v[186:189], v[218:221], v[66:69]
	v_mfma_f32_16x16x32_bf16 v[122:125], v[182:185], v[198:201], v[122:125]
	v_mfma_f32_16x16x32_bf16 v[114:117], v[190:193], v[198:201], v[114:117]
	v_mfma_f32_16x16x32_bf16 v[106:109], v[182:185], v[206:209], v[106:109]
	v_mfma_f32_16x16x32_bf16 v[98:101], v[190:193], v[206:209], v[98:101]
	v_mfma_f32_16x16x32_bf16 v[90:93], v[182:185], v[214:217], v[90:93]
	v_mfma_f32_16x16x32_bf16 v[82:85], v[190:193], v[214:217], v[82:85]
	v_mfma_f32_16x16x32_bf16 v[74:77], v[182:185], v[222:225], v[74:77]
	v_mfma_f32_16x16x32_bf16 v[66:69], v[190:193], v[222:225], v[66:69]
	s_barrier
	s_setprio 0
	s_add_u32 s98, s46, s8
	s_addc_u32 s99, s47, s9
	s_add_u32 s100, s48, s8
	s_addc_u32 s101, s49, s9
	s_add_i32 s68, s58, s6
	s_mov_b32 m0, s68
	ds_read_b128 v[194:197], v152 offset:16384
	ds_read_b128 v[198:201], v152 offset:17408
	ds_read_b128 v[202:205], v152 offset:18432
	ds_read_b128 v[206:209], v152 offset:19456
	ds_read_b128 v[210:213], v152 offset:20480
	ds_read_b128 v[214:217], v152 offset:21504
	ds_read_b128 v[218:221], v152 offset:22528
	ds_read_b128 v[222:225], v152 offset:23552
	global_load_lds_dwordx4 v132, s[46:47]
	s_add_i32 m0, s68, 0x2000
	s_add_u32 s68, s46, 0x40000
	s_addc_u32 s69, s47, 0
	s_add_i32 s76, s59, s6
	global_load_lds_dwordx4 v136, s[46:47]
	s_mov_b32 m0, s76
	s_nop 0
	global_load_lds_dwordx4 v132, s[68:69]
	s_add_i32 m0, s76, 0x2000
	s_nop 0
	global_load_lds_dwordx4 v136, s[68:69]
	s_mov_b32 m0, s41
	s_nop 0
	global_load_lds_dwordx4 v130, s[48:49]
	s_mov_b32 m0, s43
	s_nop 0
	global_load_lds_dwordx4 v134, s[48:49]
	s_waitcnt vmcnt(8)
	s_waitcnt lgkmcnt(0)
	s_setprio 1
	v_mfma_f32_16x16x32_bf16 v[62:65], v[158:161], v[194:197], v[62:65]
	v_mfma_f32_16x16x32_bf16 v[54:57], v[166:169], v[194:197], v[54:57]
	v_mfma_f32_16x16x32_bf16 v[46:49], v[158:161], v[202:205], v[46:49]
	v_mfma_f32_16x16x32_bf16 v[38:41], v[166:169], v[202:205], v[38:41]
	v_mfma_f32_16x16x32_bf16 v[30:33], v[158:161], v[210:213], v[30:33]
	v_mfma_f32_16x16x32_bf16 v[22:25], v[166:169], v[210:213], v[22:25]
	v_mfma_f32_16x16x32_bf16 v[14:17], v[158:161], v[218:221], v[14:17]
	v_mfma_f32_16x16x32_bf16 v[6:9], v[166:169], v[218:221], v[6:9]
	s_barrier
; #define PG8_STAGE(bufoff, gbase, voff) do { _Pragma("unroll") for (int _i = 0; _i < 2; ++_i) \
;         __builtin_amdgcn_global_load_lds((const unsigned*)((const char*)(gbase) + (voff)[_i]), (LAS unsigned*)(lds + (bufoff) + ldsw + _i * 8192), 16, 0, 0); } while (0)
; #define PG8_LDA(dst, b, h) do { _Pragma("unroll") for (int m = 0; m < 4; ++m) _Pragma("unroll") for (int k = 0; k < 2; ++k) dst[m][k] = *(const LAS bf16x8*)(lds + PG8_SA(b, h) + aoff + m * 2048 + k * 1024); } while (0)
; #define PG8_LDB(dst, b, h) do { _Pragma("unroll") for (int n = 0; n < 2; ++n) _Pragma("unroll") for (int k = 0; k < 2; ++k) dst[n][k] = *(const LAS bf16x8*)(lds + PG8_SB(b, h) + boff + n * 2048 + k * 1024); } while (0)
; #define PG8_MMA(ai, bj, At, Bt) do { __builtin_amdgcn_s_setprio(1); _Pragma("unroll") for (int m = 0; m < 4; ++m) _Pragma("unroll") for (int n = 0; n < 2; ++n) _Pragma("unroll") for (int k = 0; k < 2; ++k) \
;         acc[ai][bj][m][n] = __builtin_amdgcn_mfma_f32_16x16x32_bf16(Bt[n][k], At[m][k], acc[ai][bj][m][n], 0, 0, 0); __builtin_amdgcn_s_setprio(0); } while (0)
; #define PG8_WAIT_V(n) asm volatile("s_waitcnt vmcnt(" #n ")" ::: "memory")
; #define PG8_WAIT_L(n) asm volatile("s_waitcnt lgkmcnt(" #n ")" ::: "memory")
; #define PG8_BAR __builtin_amdgcn_s_barrier()
; #define PG8_SCHED __builtin_amdgcn_sched_barrier(0)
; template <class Epi>
; __device__ __forceinline__ void gemm_phase(LAS unsigned char* lds, const Gemm g, const StaticOrder& S, const Epi& E) {
;     ...
;             PG8_WAIT_V(8); PG8_WAIT_L(0); PG8_BAR; PG8_MMA(0, 0, At, B0); PG8_MMA(0, 1, At, B1); PG8_BAR; PG8_SCHED;
;             PG8_LDA(At, 0, 1); PG8_STAGE(PG8_SB(0, 0), b2, voffB); PG8_STAGE(PG8_SB(0, 1), b2 + hstep, voffB); PG8_STAGE(PG8_SA(0, 0), a2, voffA);
;             PG8_WAIT_V(8); PG8_WAIT_L(0); PG8_BAR; PG8_MMA(1, 0, At, B0); PG8_MMA(1, 1, At, B1); PG8_BAR; PG8_SCHED;
;             PG8_LDB(B0, 1, 0); PG8_LDB(B1, 1, 1); PG8_SCHED; PG8_LDA(At, 1, 0); PG8_STAGE(PG8_SA(0, 1), a2 + hstep, voffA);
;             PG8_WAIT_V(8); PG8_WAIT_L(0); PG8_BAR; PG8_MMA(0, 0, At, B0); PG8_MMA(0, 1, At, B1); PG8_BAR; PG8_SCHED;
	v_mfma_f32_16x16x32_bf16 v[62:65], v[162:165], v[198:201], v[62:65]
	v_mfma_f32_16x16x32_bf16 v[54:57], v[174:177], v[198:201], v[54:57]
	v_mfma_f32_16x16x32_bf16 v[46:49], v[162:165], v[206:209], v[46:49]
	v_mfma_f32_16x16x32_bf16 v[38:41], v[174:177], v[206:209], v[38:41]
	v_mfma_f32_16x16x32_bf16 v[30:33], v[162:165], v[214:217], v[30:33]
	v_mfma_f32_16x16x32_bf16 v[22:25], v[174:177], v[214:217], v[22:25]
	v_mfma_f32_16x16x32_bf16 v[14:17], v[162:165], v[222:225], v[14:17]
	v_mfma_f32_16x16x32_bf16 v[6:9], v[174:177], v[222:225], v[6:9]
	v_mfma_f32_16x16x32_bf16 v[58:61], v[178:181], v[194:197], v[58:61]
	v_mfma_f32_16x16x32_bf16 v[50:53], v[186:189], v[194:197], v[50:53]
	v_mfma_f32_16x16x32_bf16 v[42:45], v[178:181], v[202:205], v[42:45]
	v_mfma_f32_16x16x32_bf16 v[34:37], v[186:189], v[202:205], v[34:37]
	v_mfma_f32_16x16x32_bf16 v[26:29], v[178:181], v[210:213], v[26:29]
	v_mfma_f32_16x16x32_bf16 v[18:21], v[186:189], v[210:213], v[18:21]
	v_mfma_f32_16x16x32_bf16 v[10:13], v[178:181], v[218:221], v[10:13]
	v_mfma_f32_16x16x32_bf16 v[2:5], v[186:189], v[218:221], v[2:5]
	v_mfma_f32_16x16x32_bf16 v[58:61], v[182:185], v[198:201], v[58:61]
	v_mfma_f32_16x16x32_bf16 v[50:53], v[190:193], v[198:201], v[50:53]
	v_mfma_f32_16x16x32_bf16 v[42:45], v[182:185], v[206:209], v[42:45]
	v_mfma_f32_16x16x32_bf16 v[34:37], v[190:193], v[206:209], v[34:37]
	v_mfma_f32_16x16x32_bf16 v[26:29], v[182:185], v[214:217], v[26:29]
	v_mfma_f32_16x16x32_bf16 v[18:21], v[190:193], v[214:217], v[18:21]
	v_mfma_f32_16x16x32_bf16 v[10:13], v[182:185], v[222:225], v[10:13]
	v_mfma_f32_16x16x32_bf16 v[2:5], v[190:193], v[222:225], v[2:5]
	s_barrier
	s_setprio 0
	s_add_i32 s68, 0, 0x18000
	s_add_i32 s69, 0, 0x1c000
	v_add_u32_e32 v174, s68, v148
	v_add_u32_e32 v190, s69, v148
	ds_read_b128 v[158:161], v174
	ds_read_b128 v[162:165], v174 offset:1024
	ds_read_b128 v[166:169], v174 offset:2048
	ds_read_b128 v[174:177], v174 offset:3072
	ds_read_b128 v[178:181], v190
	ds_read_b128 v[182:185], v190 offset:1024
	ds_read_b128 v[186:189], v190 offset:2048
	ds_read_b128 v[190:193], v190 offset:3072
	s_add_u32 s48, s48, 0x40000
	s_addc_u32 s49, s49, 0
	s_mov_b32 m0, s51
	ds_read_b128 v[194:197], v152 offset:32768
	ds_read_b128 v[198:201], v152 offset:33792
	ds_read_b128 v[202:205], v152 offset:34816
	ds_read_b128 v[206:209], v152 offset:35840
	ds_read_b128 v[210:213], v152 offset:36864
	ds_read_b128 v[214:217], v152 offset:37888
	ds_read_b128 v[218:221], v152 offset:38912
	ds_read_b128 v[222:225], v152 offset:39936
	global_load_lds_dwordx4 v130, s[48:49]
	s_mov_b32 m0, s52
	s_nop 0
	global_load_lds_dwordx4 v134, s[48:49]
	s_waitcnt vmcnt(8)
	s_waitcnt lgkmcnt(0)
	s_setprio 1
	v_mfma_f32_16x16x32_bf16 v[126:129], v[158:161], v[194:197], v[126:129]
	v_mfma_f32_16x16x32_bf16 v[118:121], v[166:169], v[194:197], v[118:121]
	v_mfma_f32_16x16x32_bf16 v[110:113], v[158:161], v[202:205], v[110:113]
	v_mfma_f32_16x16x32_bf16 v[102:105], v[166:169], v[202:205], v[102:105]
	v_mfma_f32_16x16x32_bf16 v[94:97], v[158:161], v[210:213], v[94:97]
	v_mfma_f32_16x16x32_bf16 v[86:89], v[166:169], v[210:213], v[86:89]
	v_mfma_f32_16x16x32_bf16 v[78:81], v[158:161], v[218:221], v[78:81]
	v_mfma_f32_16x16x32_bf16 v[70:73], v[166:169], v[218:221], v[70:73]
	s_barrier
	v_mfma_f32_16x16x32_bf16 v[126:129], v[162:165], v[198:201], v[126:129]
	v_mfma_f32_16x16x32_bf16 v[118:121], v[174:177], v[198:201], v[118:121]
	v_mfma_f32_16x16x32_bf16 v[110:113], v[162:165], v[206:209], v[110:113]
	v_mfma_f32_16x16x32_bf16 v[102:105], v[174:177], v[206:209], v[102:105]
	v_mfma_f32_16x16x32_bf16 v[94:97], v[162:165], v[214:217], v[94:97]
	v_mfma_f32_16x16x32_bf16 v[86:89], v[174:177], v[214:217], v[86:89]
	v_mfma_f32_16x16x32_bf16 v[78:81], v[162:165], v[222:225], v[78:81]
	v_mfma_f32_16x16x32_bf16 v[70:73], v[174:177], v[222:225], v[70:73]
	v_mfma_f32_16x16x32_bf16 v[122:125], v[178:181], v[194:197], v[122:125]
	v_mfma_f32_16x16x32_bf16 v[114:117], v[186:189], v[194:197], v[114:117]
	v_mfma_f32_16x16x32_bf16 v[106:109], v[178:181], v[202:205], v[106:109]
	v_mfma_f32_16x16x32_bf16 v[98:101], v[186:189], v[202:205], v[98:101]
	v_mfma_f32_16x16x32_bf16 v[90:93], v[178:181], v[210:213], v[90:93]
	v_mfma_f32_16x16x32_bf16 v[82:85], v[186:189], v[210:213], v[82:85]
	v_mfma_f32_16x16x32_bf16 v[74:77], v[178:181], v[218:221], v[74:77]
	v_mfma_f32_16x16x32_bf16 v[66:69], v[186:189], v[218:221], v[66:69]
	v_mfma_f32_16x16x32_bf16 v[122:125], v[182:185], v[198:201], v[122:125]
	v_mfma_f32_16x16x32_bf16 v[114:117], v[190:193], v[198:201], v[114:117]
	v_mfma_f32_16x16x32_bf16 v[106:109], v[182:185], v[206:209], v[106:109]
	v_mfma_f32_16x16x32_bf16 v[98:101], v[190:193], v[206:209], v[98:101]
	v_mfma_f32_16x16x32_bf16 v[90:93], v[182:185], v[214:217], v[90:93]
	v_mfma_f32_16x16x32_bf16 v[82:85], v[190:193], v[214:217], v[82:85]
	v_mfma_f32_16x16x32_bf16 v[74:77], v[182:185], v[222:225], v[74:77]
	v_mfma_f32_16x16x32_bf16 v[66:69], v[190:193], v[222:225], v[66:69]
	s_barrier
; #define PG8_STAGE(bufoff, gbase, voff) do { _Pragma("unroll") for (int _i = 0; _i < 2; ++_i) \
;         __builtin_amdgcn_global_load_lds((const unsigned*)((const char*)(gbase) + (voff)[_i]), (LAS unsigned*)(lds + (bufoff) + ldsw + _i * 8192), 16, 0, 0); } while (0)
; #define PG8_LDA(dst, b, h) do { _Pragma("unroll") for (int m = 0; m < 4; ++m) _Pragma("unroll") for (int k = 0; k < 2; ++k) dst[m][k] = *(const LAS bf16x8*)(lds + PG8_SA(b, h) + aoff + m * 2048 + k * 1024); } while (0)
; #define PG8_MMA(ai, bj, At, Bt) do { __builtin_amdgcn_s_setprio(1); _Pragma("unroll") for (int m = 0; m < 4; ++m) _Pragma("unroll") for (int n = 0; n < 2; ++n) _Pragma("unroll") for (int k = 0; k < 2; ++k) \
;         acc[ai][bj][m][n] = __builtin_amdgcn_mfma_f32_16x16x32_bf16(Bt[n][k], At[m][k], acc[ai][bj][m][n], 0, 0, 0); __builtin_amdgcn_s_setprio(0); } while (0)
; #define PG8_WAIT_V(n) asm volatile("s_waitcnt vmcnt(" #n ")" ::: "memory")
; #define PG8_WAIT_L(n) asm volatile("s_waitcnt lgkmcnt(" #n ")" ::: "memory")
; #define PG8_BAR __builtin_amdgcn_s_barrier()
; #define PG8_SCHED __builtin_amdgcn_sched_barrier(0)
; template <class Epi>
; __device__ __forceinline__ void gemm_phase(LAS unsigned char* lds, const Gemm g, const StaticOrder& S, const Epi& E) {
;     ...
;             PG8_WAIT_V(8); PG8_WAIT_L(0); PG8_BAR; PG8_MMA(0, 0, At, B0); PG8_MMA(0, 1, At, B1); PG8_BAR; PG8_SCHED;
;             PG8_LDA(At, 1, 1); PG8_STAGE(PG8_SB(1, 0), b3, voffB); PG8_STAGE(PG8_SB(1, 1), b3 + hstep, voffB); PG8_STAGE(PG8_SA(1, 0), a3, voffA);
;             PG8_WAIT_V(8); PG8_WAIT_L(0); PG8_BAR; PG8_MMA(1, 0, At, B0); PG8_MMA(1, 1, At, B1); PG8_BAR; PG8_SCHED;
;         }
;         if (wr == 0) PG8_BAR;
	s_setprio 0
	s_add_i32 s48, s68, s6
	s_mov_b32 m0, s48
	ds_read_b128 v[194:197], v152 offset:49152
	ds_read_b128 v[198:201], v152 offset:50176
	ds_read_b128 v[202:205], v152 offset:51200
	ds_read_b128 v[206:209], v152 offset:52224
	ds_read_b128 v[210:213], v152 offset:53248
	ds_read_b128 v[214:217], v152 offset:54272
	ds_read_b128 v[218:221], v152 offset:55296
	ds_read_b128 v[222:225], v152 offset:56320
	global_load_lds_dwordx4 v132, s[98:99]
	s_add_i32 m0, s48, 0x2000
	s_add_u32 s46, s46, 0x40080
	s_addc_u32 s47, s47, 0
	s_add_i32 s48, s69, s6
	global_load_lds_dwordx4 v136, s[98:99]
	s_mov_b32 m0, s48
	s_nop 0
	global_load_lds_dwordx4 v132, s[46:47]
	s_add_i32 m0, s48, 0x2000
	s_nop 0
	global_load_lds_dwordx4 v136, s[46:47]
	s_mov_b32 m0, s53
	s_nop 0
	global_load_lds_dwordx4 v130, s[100:101]
	s_mov_b32 m0, s54
	s_nop 0
	global_load_lds_dwordx4 v134, s[100:101]
	s_waitcnt vmcnt(8)
	s_waitcnt lgkmcnt(0)
	s_setprio 1
	v_mfma_f32_16x16x32_bf16 v[62:65], v[158:161], v[194:197], v[62:65]
	v_mfma_f32_16x16x32_bf16 v[54:57], v[166:169], v[194:197], v[54:57]
	v_mfma_f32_16x16x32_bf16 v[46:49], v[158:161], v[202:205], v[46:49]
	v_mfma_f32_16x16x32_bf16 v[38:41], v[166:169], v[202:205], v[38:41]
	v_mfma_f32_16x16x32_bf16 v[30:33], v[158:161], v[210:213], v[30:33]
	v_mfma_f32_16x16x32_bf16 v[22:25], v[166:169], v[210:213], v[22:25]
	v_mfma_f32_16x16x32_bf16 v[14:17], v[158:161], v[218:221], v[14:17]
	v_mfma_f32_16x16x32_bf16 v[6:9], v[166:169], v[218:221], v[6:9]
	s_barrier
	v_mfma_f32_16x16x32_bf16 v[62:65], v[162:165], v[198:201], v[62:65]
	v_mfma_f32_16x16x32_bf16 v[54:57], v[174:177], v[198:201], v[54:57]
	v_mfma_f32_16x16x32_bf16 v[46:49], v[162:165], v[206:209], v[46:49]
	v_mfma_f32_16x16x32_bf16 v[38:41], v[174:177], v[206:209], v[38:41]
	v_mfma_f32_16x16x32_bf16 v[30:33], v[162:165], v[214:217], v[30:33]
	v_mfma_f32_16x16x32_bf16 v[22:25], v[174:177], v[214:217], v[22:25]
	v_mfma_f32_16x16x32_bf16 v[14:17], v[162:165], v[222:225], v[14:17]
	v_mfma_f32_16x16x32_bf16 v[6:9], v[174:177], v[222:225], v[6:9]
	v_mfma_f32_16x16x32_bf16 v[58:61], v[178:181], v[194:197], v[58:61]
	v_mfma_f32_16x16x32_bf16 v[50:53], v[186:189], v[194:197], v[50:53]
	v_mfma_f32_16x16x32_bf16 v[42:45], v[178:181], v[202:205], v[42:45]
	v_mfma_f32_16x16x32_bf16 v[34:37], v[186:189], v[202:205], v[34:37]
	v_mfma_f32_16x16x32_bf16 v[26:29], v[178:181], v[210:213], v[26:29]
	v_mfma_f32_16x16x32_bf16 v[18:21], v[186:189], v[210:213], v[18:21]
	v_mfma_f32_16x16x32_bf16 v[10:13], v[178:181], v[218:221], v[10:13]
	v_mfma_f32_16x16x32_bf16 v[2:5], v[186:189], v[218:221], v[2:5]
	v_mfma_f32_16x16x32_bf16 v[58:61], v[182:185], v[198:201], v[58:61]
	v_mfma_f32_16x16x32_bf16 v[50:53], v[190:193], v[198:201], v[50:53]
	v_mfma_f32_16x16x32_bf16 v[42:45], v[182:185], v[206:209], v[42:45]
	v_mfma_f32_16x16x32_bf16 v[34:37], v[190:193], v[206:209], v[34:37]
	v_mfma_f32_16x16x32_bf16 v[26:29], v[182:185], v[214:217], v[26:29]
	v_mfma_f32_16x16x32_bf16 v[18:21], v[190:193], v[214:217], v[18:21]
	v_mfma_f32_16x16x32_bf16 v[10:13], v[182:185], v[222:225], v[10:13]
	v_mfma_f32_16x16x32_bf16 v[2:5], v[190:193], v[222:225], v[2:5]
	s_barrier
	s_setprio 0
	s_add_i32 s67, s67, 2
	s_add_u32 s44, s44, 0x100
	s_addc_u32 s45, s45, 0
	s_add_u32 s65, s65, 0x100
	s_addc_u32 s66, s66, 0
	s_cmp_gt_u32 s67, 13
	s_cbranch_scc0 .LBB0_884
	s_and_b64 vcc, exec, s[14:15]
	s_cbranch_vccz .LBB0_887
	s_barrier

; #define PG8_STAGE(bufoff, gbase, voff) do { _Pragma("unroll") for (int _i = 0; _i < 2; ++_i) \
;         __builtin_amdgcn_global_load_lds((const unsigned*)((const char*)(gbase) + (voff)[_i]), (LAS unsigned*)(lds + (bufoff) + ldsw + _i * 8192), 16, 0, 0); } while (0)
; #define PG8_LDA(dst, b, h) do { _Pragma("unroll") for (int m = 0; m < 4; ++m) _Pragma("unroll") for (int k = 0; k < 2; ++k) dst[m][k] = *(const LAS bf16x8*)(lds + PG8_SA(b, h) + aoff + m * 2048 + k * 1024); } while (0)
; #define PG8_LDB(dst, b, h) do { _Pragma("unroll") for (int n = 0; n < 2; ++n) _Pragma("unroll") for (int k = 0; k < 2; ++k) dst[n][k] = *(const LAS bf16x8*)(lds + PG8_SB(b, h) + boff + n * 2048 + k * 1024); } while (0)
; #define PG8_MMA(ai, bj, At, Bt) do { __builtin_amdgcn_s_setprio(1); _Pragma("unroll") for (int m = 0; m < 4; ++m) _Pragma("unroll") for (int n = 0; n < 2; ++n) _Pragma("unroll") for (int k = 0; k < 2; ++k) \
;         acc[ai][bj][m][n] = __builtin_amdgcn_mfma_f32_16x16x32_bf16(Bt[n][k], At[m][k], acc[ai][bj][m][n], 0, 0, 0); __builtin_amdgcn_s_setprio(0); } while (0)
; #define PG8_WAIT_V(n) asm volatile("s_waitcnt vmcnt(" #n ")" ::: "memory")
; #define PG8_WAIT_L(n) asm volatile("s_waitcnt lgkmcnt(" #n ")" ::: "memory")
; #define PG8_BAR __builtin_amdgcn_s_barrier()
; template <class Epi>
; __device__ __forceinline__ void gemm_phase(LAS unsigned char* lds, const Gemm g, const StaticOrder& S, const Epi& E) {
;     ...
;         for (int t = 0; t < nt; t += 2) {
;             const bool last = (t == nt - 2);
;             const char* a1 = cA + (size_t)(t + 1) * kstep;
;             const char* a2 = last ? nA : cA + (size_t)(t + 2) * kstep; const char* b2 = last ? nB : cB + (size_t)(t + 2) * kstep;
;             const char* a3 = a2 + kstep; const char* b3 = b2 + kstep;
;             if constexpr (Epi::MIDK > 0) { if (t == Epi::MIDK) E.mid(acc, cur, wr, wc, fr, fq); }
;             PG8_LDB(B0, 0, 0); PG8_LDB(B1, 0, 1); PG8_SCHED; PG8_LDA(At, 0, 0); PG8_STAGE(PG8_SA(1, 1), a1 + hstep, voffA);
;             PG8_WAIT_V(8); PG8_WAIT_L(0); PG8_BAR; PG8_MMA(0, 0, At, B0); PG8_MMA(0, 1, At, B1); PG8_BAR; PG8_SCHED;
;             PG8_LDA(At, 0, 1); PG8_STAGE(PG8_SB(0, 0), b2, voffB); PG8_STAGE(PG8_SB(0, 1), b2 + hstep, voffB); PG8_STAGE(PG8_SA(0, 0), a2, voffA);
;             PG8_WAIT_V(8); PG8_WAIT_L(0); PG8_BAR; PG8_MMA(1, 0, At, B0); PG8_MMA(1, 1, At, B1); PG8_BAR; PG8_SCHED;
.LBB0_971:
	ds_read_b128 v[130:133], v162
	ds_read_b128 v[134:137], v162 offset:1024
	ds_read_b128 v[154:157], v162 offset:2048
	ds_read_b128 v[166:169], v162 offset:3072
	ds_read_b128 v[174:177], v163
	ds_read_b128 v[178:181], v163 offset:1024
	ds_read_b128 v[182:185], v163 offset:2048
	ds_read_b128 v[186:189], v163 offset:3072
	s_add_u32 s24, s22, 0xfff50080
	s_addc_u32 s25, s23, -1
	s_cmp_eq_u32 s59, 40
	s_cselect_b32 s27, s5, s25
	s_cselect_b32 s26, s4, s24
	s_cselect_b32 s25, s21, s58
	s_cselect_b32 s24, s20, s57
	s_add_i32 m0, s39, 0xc000
	ds_read_b128 v[190:193], v164
	ds_read_b128 v[194:197], v164 offset:1024
	ds_read_b128 v[198:201], v164 offset:2048
	ds_read_b128 v[202:205], v164 offset:3072
	ds_read_b128 v[206:209], v164 offset:4096
	ds_read_b128 v[210:213], v164 offset:5120
	ds_read_b128 v[214:217], v164 offset:6144
	ds_read_b128 v[218:221], v164 offset:7168
	global_load_lds_dwordx4 v146, s[22:23]
	s_add_i32 m0, s39, 0xe000
	s_nop 0
	global_load_lds_dwordx4 v148, s[22:23]
	s_waitcnt vmcnt(8)
	s_waitcnt lgkmcnt(0)
	s_setprio 1
	v_mfma_f32_16x16x32_bf16 v[126:129], v[130:133], v[190:193], v[126:129]
	v_mfma_f32_16x16x32_bf16 v[122:125], v[154:157], v[190:193], v[122:125]
	v_mfma_f32_16x16x32_bf16 v[110:113], v[130:133], v[198:201], v[110:113]
	v_mfma_f32_16x16x32_bf16 v[106:109], v[154:157], v[198:201], v[106:109]
	v_mfma_f32_16x16x32_bf16 v[94:97], v[130:133], v[206:209], v[94:97]
	v_mfma_f32_16x16x32_bf16 v[90:93], v[154:157], v[206:209], v[90:93]
	v_mfma_f32_16x16x32_bf16 v[78:81], v[130:133], v[214:217], v[78:81]
	v_mfma_f32_16x16x32_bf16 v[74:77], v[154:157], v[214:217], v[74:77]
	s_barrier
	v_mfma_f32_16x16x32_bf16 v[126:129], v[134:137], v[194:197], v[126:129]
	v_mfma_f32_16x16x32_bf16 v[122:125], v[166:169], v[194:197], v[122:125]
	v_mfma_f32_16x16x32_bf16 v[110:113], v[134:137], v[202:205], v[110:113]
	v_mfma_f32_16x16x32_bf16 v[106:109], v[166:169], v[202:205], v[106:109]
	v_mfma_f32_16x16x32_bf16 v[94:97], v[134:137], v[210:213], v[94:97]
	v_mfma_f32_16x16x32_bf16 v[90:93], v[166:169], v[210:213], v[90:93]
	v_mfma_f32_16x16x32_bf16 v[78:81], v[134:137], v[218:221], v[78:81]
	v_mfma_f32_16x16x32_bf16 v[74:77], v[166:169], v[218:221], v[74:77]
	v_mfma_f32_16x16x32_bf16 v[118:121], v[174:177], v[190:193], v[118:121]
	v_mfma_f32_16x16x32_bf16 v[114:117], v[182:185], v[190:193], v[114:117]
	v_mfma_f32_16x16x32_bf16 v[102:105], v[174:177], v[198:201], v[102:105]
	v_mfma_f32_16x16x32_bf16 v[98:101], v[182:185], v[198:201], v[98:101]
	v_mfma_f32_16x16x32_bf16 v[86:89], v[174:177], v[206:209], v[86:89]
	v_mfma_f32_16x16x32_bf16 v[82:85], v[182:185], v[206:209], v[82:85]
	v_mfma_f32_16x16x32_bf16 v[70:73], v[174:177], v[214:217], v[70:73]
	v_mfma_f32_16x16x32_bf16 v[66:69], v[182:185], v[214:217], v[66:69]
	v_mfma_f32_16x16x32_bf16 v[118:121], v[178:181], v[194:197], v[118:121]
	v_mfma_f32_16x16x32_bf16 v[114:117], v[186:189], v[194:197], v[114:117]
	v_mfma_f32_16x16x32_bf16 v[102:105], v[178:181], v[202:205], v[102:105]
	v_mfma_f32_16x16x32_bf16 v[98:101], v[186:189], v[202:205], v[98:101]
	v_mfma_f32_16x16x32_bf16 v[86:89], v[178:181], v[210:213], v[86:89]
	v_mfma_f32_16x16x32_bf16 v[82:85], v[186:189], v[210:213], v[82:85]
	v_mfma_f32_16x16x32_bf16 v[70:73], v[178:181], v[218:221], v[70:73]
	v_mfma_f32_16x16x32_bf16 v[66:69], v[186:189], v[218:221], v[66:69]
	s_barrier
	s_setprio 0
	s_add_u32 s98, s24, s14
	s_addc_u32 s99, s25, s15
	s_add_u32 s100, s26, s14
	s_addc_u32 s101, s27, s15
	s_add_i32 s60, s51, s38
	s_mov_b32 m0, s60
	ds_read_b128 v[190:193], v164 offset:16384
	ds_read_b128 v[194:197], v164 offset:17408
	ds_read_b128 v[198:201], v164 offset:18432
	ds_read_b128 v[202:205], v164 offset:19456
	ds_read_b128 v[206:209], v164 offset:20480
	ds_read_b128 v[210:213], v164 offset:21504
	ds_read_b128 v[214:217], v164 offset:22528
	ds_read_b128 v[218:221], v164 offset:23552
	global_load_lds_dwordx4 v140, s[24:25]
	s_add_i32 m0, s60, 0x2000
	s_add_u32 s60, s24, 0xb0000
	s_addc_u32 s61, s25, 0
	s_add_i32 s62, s52, s38
	global_load_lds_dwordx4 v144, s[24:25]
	s_mov_b32 m0, s62
	s_nop 0
	global_load_lds_dwordx4 v140, s[60:61]
	s_add_i32 m0, s62, 0x2000
	s_nop 0
	global_load_lds_dwordx4 v144, s[60:61]
	s_mov_b32 m0, s39
	s_nop 0
	global_load_lds_dwordx4 v138, s[26:27]
	s_mov_b32 m0, s40
	s_nop 0
	global_load_lds_dwordx4 v142, s[26:27]
	s_waitcnt vmcnt(8)
	s_waitcnt lgkmcnt(0)
	s_setprio 1
	v_mfma_f32_16x16x32_bf16 v[62:65], v[130:133], v[190:193], v[62:65]
	v_mfma_f32_16x16x32_bf16 v[58:61], v[154:157], v[190:193], v[58:61]
	v_mfma_f32_16x16x32_bf16 v[46:49], v[130:133], v[198:201], v[46:49]
	v_mfma_f32_16x16x32_bf16 v[42:45], v[154:157], v[198:201], v[42:45]
	v_mfma_f32_16x16x32_bf16 v[30:33], v[130:133], v[206:209], v[30:33]
	v_mfma_f32_16x16x32_bf16 v[26:29], v[154:157], v[206:209], v[26:29]
	v_mfma_f32_16x16x32_bf16 v[14:17], v[130:133], v[214:217], v[14:17]
	v_mfma_f32_16x16x32_bf16 v[10:13], v[154:157], v[214:217], v[10:13]
	s_barrier
; #define PG8_STAGE(bufoff, gbase, voff) do { _Pragma("unroll") for (int _i = 0; _i < 2; ++_i) \
;         __builtin_amdgcn_global_load_lds((const unsigned*)((const char*)(gbase) + (voff)[_i]), (LAS unsigned*)(lds + (bufoff) + ldsw + _i * 8192), 16, 0, 0); } while (0)
; #define PG8_LDA(dst, b, h) do { _Pragma("unroll") for (int m = 0; m < 4; ++m) _Pragma("unroll") for (int k = 0; k < 2; ++k) dst[m][k] = *(const LAS bf16x8*)(lds + PG8_SA(b, h) + aoff + m * 2048 + k * 1024); } while (0)
; #define PG8_LDB(dst, b, h) do { _Pragma("unroll") for (int n = 0; n < 2; ++n) _Pragma("unroll") for (int k = 0; k < 2; ++k) dst[n][k] = *(const LAS bf16x8*)(lds + PG8_SB(b, h) + boff + n * 2048 + k * 1024); } while (0)
; #define PG8_MMA(ai, bj, At, Bt) do { __builtin_amdgcn_s_setprio(1); _Pragma("unroll") for (int m = 0; m < 4; ++m) _Pragma("unroll") for (int n = 0; n < 2; ++n) _Pragma("unroll") for (int k = 0; k < 2; ++k) \
;         acc[ai][bj][m][n] = __builtin_amdgcn_mfma_f32_16x16x32_bf16(Bt[n][k], At[m][k], acc[ai][bj][m][n], 0, 0, 0); __builtin_amdgcn_s_setprio(0); } while (0)
; #define PG8_WAIT_V(n) asm volatile("s_waitcnt vmcnt(" #n ")" ::: "memory")
; #define PG8_WAIT_L(n) asm volatile("s_waitcnt lgkmcnt(" #n ")" ::: "memory")
; #define PG8_BAR __builtin_amdgcn_s_barrier()
; #define PG8_SCHED __builtin_amdgcn_sched_barrier(0)
; template <class Epi>
; __device__ __forceinline__ void gemm_phase(LAS unsigned char* lds, const Gemm g, const StaticOrder& S, const Epi& E) {
;     ...
;             PG8_WAIT_V(8); PG8_WAIT_L(0); PG8_BAR; PG8_MMA(0, 0, At, B0); PG8_MMA(0, 1, At, B1); PG8_BAR; PG8_SCHED;
;             PG8_LDA(At, 0, 1); PG8_STAGE(PG8_SB(0, 0), b2, voffB); PG8_STAGE(PG8_SB(0, 1), b2 + hstep, voffB); PG8_STAGE(PG8_SA(0, 0), a2, voffA);
;             PG8_WAIT_V(8); PG8_WAIT_L(0); PG8_BAR; PG8_MMA(1, 0, At, B0); PG8_MMA(1, 1, At, B1); PG8_BAR; PG8_SCHED;
;             PG8_LDB(B0, 1, 0); PG8_LDB(B1, 1, 1); PG8_SCHED; PG8_LDA(At, 1, 0); PG8_STAGE(PG8_SA(0, 1), a2 + hstep, voffA);
;             PG8_WAIT_V(8); PG8_WAIT_L(0); PG8_BAR; PG8_MMA(0, 0, At, B0); PG8_MMA(0, 1, At, B1); PG8_BAR; PG8_SCHED;
	v_mfma_f32_16x16x32_bf16 v[62:65], v[134:137], v[194:197], v[62:65]
	v_mfma_f32_16x16x32_bf16 v[58:61], v[166:169], v[194:197], v[58:61]
	v_mfma_f32_16x16x32_bf16 v[46:49], v[134:137], v[202:205], v[46:49]
	v_mfma_f32_16x16x32_bf16 v[42:45], v[166:169], v[202:205], v[42:45]
	v_mfma_f32_16x16x32_bf16 v[30:33], v[134:137], v[210:213], v[30:33]
	v_mfma_f32_16x16x32_bf16 v[26:29], v[166:169], v[210:213], v[26:29]
	v_mfma_f32_16x16x32_bf16 v[14:17], v[134:137], v[218:221], v[14:17]
	v_mfma_f32_16x16x32_bf16 v[10:13], v[166:169], v[218:221], v[10:13]
	v_mfma_f32_16x16x32_bf16 v[54:57], v[174:177], v[190:193], v[54:57]
	v_mfma_f32_16x16x32_bf16 v[50:53], v[182:185], v[190:193], v[50:53]
	v_mfma_f32_16x16x32_bf16 v[38:41], v[174:177], v[198:201], v[38:41]
	v_mfma_f32_16x16x32_bf16 v[34:37], v[182:185], v[198:201], v[34:37]
	v_mfma_f32_16x16x32_bf16 v[22:25], v[174:177], v[206:209], v[22:25]
	v_mfma_f32_16x16x32_bf16 v[18:21], v[182:185], v[206:209], v[18:21]
	v_mfma_f32_16x16x32_bf16 v[6:9], v[174:177], v[214:217], v[6:9]
	v_mfma_f32_16x16x32_bf16 v[2:5], v[182:185], v[214:217], v[2:5]
	v_mfma_f32_16x16x32_bf16 v[54:57], v[178:181], v[194:197], v[54:57]
	v_mfma_f32_16x16x32_bf16 v[50:53], v[186:189], v[194:197], v[50:53]
	v_mfma_f32_16x16x32_bf16 v[38:41], v[178:181], v[202:205], v[38:41]
	v_mfma_f32_16x16x32_bf16 v[34:37], v[186:189], v[202:205], v[34:37]
	v_mfma_f32_16x16x32_bf16 v[22:25], v[178:181], v[210:213], v[22:25]
	v_mfma_f32_16x16x32_bf16 v[18:21], v[186:189], v[210:213], v[18:21]
	v_mfma_f32_16x16x32_bf16 v[6:9], v[178:181], v[218:221], v[6:9]
	v_mfma_f32_16x16x32_bf16 v[2:5], v[186:189], v[218:221], v[2:5]
	s_barrier
	s_setprio 0
	s_add_i32 s60, 0, 0x18000
	s_add_i32 s61, 0, 0x1c000
	v_add_u32_e32 v166, s60, v160
	v_add_u32_e32 v186, s61, v160
	ds_read_b128 v[130:133], v166
	ds_read_b128 v[134:137], v166 offset:1024
	ds_read_b128 v[154:157], v166 offset:2048
	ds_read_b128 v[166:169], v166 offset:3072
	ds_read_b128 v[174:177], v186
	ds_read_b128 v[178:181], v186 offset:1024
	ds_read_b128 v[182:185], v186 offset:2048
	ds_read_b128 v[186:189], v186 offset:3072
	s_add_u32 s26, s26, 0xb0000
	s_addc_u32 s27, s27, 0
	s_mov_b32 m0, s41
	ds_read_b128 v[190:193], v164 offset:32768
	ds_read_b128 v[194:197], v164 offset:33792
	ds_read_b128 v[198:201], v164 offset:34816
	ds_read_b128 v[202:205], v164 offset:35840
	ds_read_b128 v[206:209], v164 offset:36864
	ds_read_b128 v[210:213], v164 offset:37888
	ds_read_b128 v[214:217], v164 offset:38912
	ds_read_b128 v[218:221], v164 offset:39936
	global_load_lds_dwordx4 v138, s[26:27]
	s_mov_b32 m0, s42
	s_nop 0
	global_load_lds_dwordx4 v142, s[26:27]
	s_waitcnt vmcnt(8)
	s_waitcnt lgkmcnt(0)
	s_setprio 1
	v_mfma_f32_16x16x32_bf16 v[126:129], v[130:133], v[190:193], v[126:129]
	v_mfma_f32_16x16x32_bf16 v[122:125], v[154:157], v[190:193], v[122:125]
	v_mfma_f32_16x16x32_bf16 v[110:113], v[130:133], v[198:201], v[110:113]
	v_mfma_f32_16x16x32_bf16 v[106:109], v[154:157], v[198:201], v[106:109]
	v_mfma_f32_16x16x32_bf16 v[94:97], v[130:133], v[206:209], v[94:97]
	v_mfma_f32_16x16x32_bf16 v[90:93], v[154:157], v[206:209], v[90:93]
	v_mfma_f32_16x16x32_bf16 v[78:81], v[130:133], v[214:217], v[78:81]
	v_mfma_f32_16x16x32_bf16 v[74:77], v[154:157], v[214:217], v[74:77]
	s_barrier
	v_mfma_f32_16x16x32_bf16 v[126:129], v[134:137], v[194:197], v[126:129]
	v_mfma_f32_16x16x32_bf16 v[122:125], v[166:169], v[194:197], v[122:125]
	v_mfma_f32_16x16x32_bf16 v[110:113], v[134:137], v[202:205], v[110:113]
	v_mfma_f32_16x16x32_bf16 v[106:109], v[166:169], v[202:205], v[106:109]
	v_mfma_f32_16x16x32_bf16 v[94:97], v[134:137], v[210:213], v[94:97]
	v_mfma_f32_16x16x32_bf16 v[90:93], v[166:169], v[210:213], v[90:93]
	v_mfma_f32_16x16x32_bf16 v[78:81], v[134:137], v[218:221], v[78:81]
	v_mfma_f32_16x16x32_bf16 v[74:77], v[166:169], v[218:221], v[74:77]
	v_mfma_f32_16x16x32_bf16 v[118:121], v[174:177], v[190:193], v[118:121]
	v_mfma_f32_16x16x32_bf16 v[114:117], v[182:185], v[190:193], v[114:117]
	v_mfma_f32_16x16x32_bf16 v[102:105], v[174:177], v[198:201], v[102:105]
	v_mfma_f32_16x16x32_bf16 v[98:101], v[182:185], v[198:201], v[98:101]
	v_mfma_f32_16x16x32_bf16 v[86:89], v[174:177], v[206:209], v[86:89]
	v_mfma_f32_16x16x32_bf16 v[82:85], v[182:185], v[206:209], v[82:85]
	v_mfma_f32_16x16x32_bf16 v[70:73], v[174:177], v[214:217], v[70:73]
	v_mfma_f32_16x16x32_bf16 v[66:69], v[182:185], v[214:217], v[66:69]
	v_mfma_f32_16x16x32_bf16 v[118:121], v[178:181], v[194:197], v[118:121]
	v_mfma_f32_16x16x32_bf16 v[114:117], v[186:189], v[194:197], v[114:117]
	v_mfma_f32_16x16x32_bf16 v[102:105], v[178:181], v[202:205], v[102:105]
	v_mfma_f32_16x16x32_bf16 v[98:101], v[186:189], v[202:205], v[98:101]
	v_mfma_f32_16x16x32_bf16 v[86:89], v[178:181], v[210:213], v[86:89]
	v_mfma_f32_16x16x32_bf16 v[82:85], v[186:189], v[210:213], v[82:85]
	v_mfma_f32_16x16x32_bf16 v[70:73], v[178:181], v[218:221], v[70:73]
	v_mfma_f32_16x16x32_bf16 v[66:69], v[186:189], v[218:221], v[66:69]
	s_barrier
; #define PG8_STAGE(bufoff, gbase, voff) do { _Pragma("unroll") for (int _i = 0; _i < 2; ++_i) \
;         __builtin_amdgcn_global_load_lds((const unsigned*)((const char*)(gbase) + (voff)[_i]), (LAS unsigned*)(lds + (bufoff) + ldsw + _i * 8192), 16, 0, 0); } while (0)
; #define PG8_LDA(dst, b, h) do { _Pragma("unroll") for (int m = 0; m < 4; ++m) _Pragma("unroll") for (int k = 0; k < 2; ++k) dst[m][k] = *(const LAS bf16x8*)(lds + PG8_SA(b, h) + aoff + m * 2048 + k * 1024); } while (0)
; #define PG8_MMA(ai, bj, At, Bt) do { __builtin_amdgcn_s_setprio(1); _Pragma("unroll") for (int m = 0; m < 4; ++m) _Pragma("unroll") for (int n = 0; n < 2; ++n) _Pragma("unroll") for (int k = 0; k < 2; ++k) \
;         acc[ai][bj][m][n] = __builtin_amdgcn_mfma_f32_16x16x32_bf16(Bt[n][k], At[m][k], acc[ai][bj][m][n], 0, 0, 0); __builtin_amdgcn_s_setprio(0); } while (0)
; #define PG8_WAIT_V(n) asm volatile("s_waitcnt vmcnt(" #n ")" ::: "memory")
; #define PG8_WAIT_L(n) asm volatile("s_waitcnt lgkmcnt(" #n ")" ::: "memory")
; #define PG8_BAR __builtin_amdgcn_s_barrier()
; #define PG8_SCHED __builtin_amdgcn_sched_barrier(0)
; template <class Epi>
; __device__ __forceinline__ void gemm_phase(LAS unsigned char* lds, const Gemm g, const StaticOrder& S, const Epi& E) {
;     ...
;             PG8_WAIT_V(8); PG8_WAIT_L(0); PG8_BAR; PG8_MMA(0, 0, At, B0); PG8_MMA(0, 1, At, B1); PG8_BAR; PG8_SCHED;
;             PG8_LDA(At, 1, 1); PG8_STAGE(PG8_SB(1, 0), b3, voffB); PG8_STAGE(PG8_SB(1, 1), b3 + hstep, voffB); PG8_STAGE(PG8_SA(1, 0), a3, voffA);
;             PG8_WAIT_V(8); PG8_WAIT_L(0); PG8_BAR; PG8_MMA(1, 0, At, B0); PG8_MMA(1, 1, At, B1); PG8_BAR; PG8_SCHED;
;         }
;         if (wr == 0) PG8_BAR;
	s_setprio 0
	s_add_i32 s26, s60, s38
	s_mov_b32 m0, s26
	ds_read_b128 v[190:193], v164 offset:49152
	ds_read_b128 v[194:197], v164 offset:50176
	ds_read_b128 v[198:201], v164 offset:51200
	ds_read_b128 v[202:205], v164 offset:52224
	ds_read_b128 v[206:209], v164 offset:53248
	ds_read_b128 v[210:213], v164 offset:54272
	ds_read_b128 v[214:217], v164 offset:55296
	ds_read_b128 v[218:221], v164 offset:56320
	global_load_lds_dwordx4 v140, s[98:99]
	s_add_i32 m0, s26, 0x2000
	s_add_u32 s24, s24, 0xb0080
	s_addc_u32 s25, s25, 0
	s_add_i32 s26, s61, s38
	global_load_lds_dwordx4 v144, s[98:99]
	s_mov_b32 m0, s26
	s_nop 0
	global_load_lds_dwordx4 v140, s[24:25]
	s_add_i32 m0, s26, 0x2000
	s_nop 0
	global_load_lds_dwordx4 v144, s[24:25]
	s_mov_b32 m0, s44
	s_nop 0
	global_load_lds_dwordx4 v138, s[100:101]
	s_mov_b32 m0, s45
	s_nop 0
	global_load_lds_dwordx4 v142, s[100:101]
	s_waitcnt vmcnt(8)
	s_waitcnt lgkmcnt(0)
	s_setprio 1
	v_mfma_f32_16x16x32_bf16 v[62:65], v[130:133], v[190:193], v[62:65]
	v_mfma_f32_16x16x32_bf16 v[58:61], v[154:157], v[190:193], v[58:61]
	v_mfma_f32_16x16x32_bf16 v[46:49], v[130:133], v[198:201], v[46:49]
	v_mfma_f32_16x16x32_bf16 v[42:45], v[154:157], v[198:201], v[42:45]
	v_mfma_f32_16x16x32_bf16 v[30:33], v[130:133], v[206:209], v[30:33]
	v_mfma_f32_16x16x32_bf16 v[26:29], v[154:157], v[206:209], v[26:29]
	v_mfma_f32_16x16x32_bf16 v[14:17], v[130:133], v[214:217], v[14:17]
	v_mfma_f32_16x16x32_bf16 v[10:13], v[154:157], v[214:217], v[10:13]
	s_barrier
	v_mfma_f32_16x16x32_bf16 v[62:65], v[134:137], v[194:197], v[62:65]
	v_mfma_f32_16x16x32_bf16 v[58:61], v[166:169], v[194:197], v[58:61]
	v_mfma_f32_16x16x32_bf16 v[46:49], v[134:137], v[202:205], v[46:49]
	v_mfma_f32_16x16x32_bf16 v[42:45], v[166:169], v[202:205], v[42:45]
	v_mfma_f32_16x16x32_bf16 v[30:33], v[134:137], v[210:213], v[30:33]
	v_mfma_f32_16x16x32_bf16 v[26:29], v[166:169], v[210:213], v[26:29]
	v_mfma_f32_16x16x32_bf16 v[14:17], v[134:137], v[218:221], v[14:17]
	v_mfma_f32_16x16x32_bf16 v[10:13], v[166:169], v[218:221], v[10:13]
	v_mfma_f32_16x16x32_bf16 v[54:57], v[174:177], v[190:193], v[54:57]
	v_mfma_f32_16x16x32_bf16 v[50:53], v[182:185], v[190:193], v[50:53]
	v_mfma_f32_16x16x32_bf16 v[38:41], v[174:177], v[198:201], v[38:41]
	v_mfma_f32_16x16x32_bf16 v[34:37], v[182:185], v[198:201], v[34:37]
	v_mfma_f32_16x16x32_bf16 v[22:25], v[174:177], v[206:209], v[22:25]
	v_mfma_f32_16x16x32_bf16 v[18:21], v[182:185], v[206:209], v[18:21]
	v_mfma_f32_16x16x32_bf16 v[6:9], v[174:177], v[214:217], v[6:9]
	v_mfma_f32_16x16x32_bf16 v[2:5], v[182:185], v[214:217], v[2:5]
	v_mfma_f32_16x16x32_bf16 v[54:57], v[178:181], v[194:197], v[54:57]
	v_mfma_f32_16x16x32_bf16 v[50:53], v[186:189], v[194:197], v[50:53]
	v_mfma_f32_16x16x32_bf16 v[38:41], v[178:181], v[202:205], v[38:41]
	v_mfma_f32_16x16x32_bf16 v[34:37], v[186:189], v[202:205], v[34:37]
	v_mfma_f32_16x16x32_bf16 v[22:25], v[178:181], v[210:213], v[22:25]
	v_mfma_f32_16x16x32_bf16 v[18:21], v[186:189], v[210:213], v[18:21]
	v_mfma_f32_16x16x32_bf16 v[6:9], v[178:181], v[218:221], v[6:9]
	v_mfma_f32_16x16x32_bf16 v[2:5], v[186:189], v[218:221], v[2:5]
	s_barrier
	s_setprio 0
	s_add_i32 s59, s59, 2
	s_add_u32 s22, s22, 0x100
	s_addc_u32 s23, s23, 0
	s_add_u32 s57, s57, 0x100
	s_addc_u32 s58, s58, 0
	s_cmp_gt_u32 s59, 41
	s_cbranch_scc0 .LBB0_971
	s_and_b64 vcc, exec, s[18:19]
	s_cbranch_vccz .LBB0_974
	s_barrier
